# deferred generation check: generation word read early (at each unit's first K iteration), polling loop only as fallback
# baseline (speedup 1.0000x reference)
; #define PG8_STAGE(bufoff, gbase, voff) do { _Pragma("unroll") for (int _i = 0; _i < 2; ++_i) \
;         __builtin_amdgcn_global_load_lds((const unsigned*)((const char*)(gbase) + (voff)[_i]), (PG8_LAS unsigned*)(lds + (bufoff) + ldsw + _i * 8192), 16, 0, 0); } while (0)
; #define PG8_LDA(dst, b, h) do { _Pragma("unroll") for (int m = 0; m < 4; ++m) _Pragma("unroll") for (int k = 0; k < 2; ++k) dst[m][k] = *(const PG8_LAS bf16x8*)(lds + PG8_SA(b, h) + aoff + m * 2048 + k * 1024); } while (0)
; #define PG8_LDB(dst, b, h) do { _Pragma("unroll") for (int n = 0; n < 2; ++n) _Pragma("unroll") for (int k = 0; k < 2; ++k) dst[n][k] = *(const PG8_LAS bf16x8*)(lds + PG8_SB(b, h) + boff + n * 2048 + k * 1024); } while (0)
; #define PG8_WAIT_V(n) asm volatile("s_waitcnt vmcnt(" #n ")" ::: "memory")
; #define PG8_WAIT_L(n) asm volatile("s_waitcnt lgkmcnt(" #n ")" ::: "memory")
; #define PG8_BAR __builtin_amdgcn_s_barrier()
; #define PG8_SCHED __builtin_amdgcn_sched_barrier(0)
; template <class Epi, class Sched, bool ALIGN_EPI = false, bool SP2 = false>
; __device__ __forceinline__ void gemm_phase(PG8_LAS unsigned char* lds, const Gemm g, const Sched& S, const Epi& E) {
;     ...
;         const bool has_next = S.next(ui + 1, nxt);
;         const char* nA = has_next ? (const char*)g.A + (size_t)nxt.pm * tstep : cA; const char* nB = has_next ? (const char*)g.Bt + (size_t)nxt.pn * tstep : cB;
;         for (int t = 0; t < nt; t += 2) {
;             const bool last = (t == nt - 2);
;             const char* a1 = cA + (size_t)(t + 1) * kstep;
;             const char* a2 = last ? nA : cA + (size_t)(t + 2) * kstep; const char* b2 = last ? nB : cB + (size_t)(t + 2) * kstep;
;             const char* a3 = a2 + kstep; const char* b3 = b2 + kstep;
;             if (last && has_next) S.a_ready(nxt);
;             if constexpr (SP2) {
;             PG8_LDB(B0, 0, 0); PG8_LDB(B1, 0, 1); PG8_SCHED; PG8_LDA(At, 0, 0); PG8_STAGE(PG8_SA(1, 1), a1 + hstep, voffA);
;             PG8_WAIT_V(8); PG8_WAIT_L(0); PG8_BAR; PG8_MMA(0, 0, At, B0); PG8_MMA(0, 1, At, B1); PG8_BAR; PG8_SCHED;
;             PG8_LDA(At, 0, 1); PG8_STAGE(PG8_SB(0, 0), b2, voffB); PG8_STAGE(PG8_SB(0, 1), b2 + hstep, voffB); PG8_STAGE(PG8_SA(0, 0), a2, voffA);
;             PG8_WAIT_V(8); PG8_WAIT_L(0); PG8_BAR; PG8_MMA(1, 0, At, B0); PG8_MMA(1, 1, At, B1); PG8_BAR; PG8_SCHED;
.LBB0_413:
	s_ashr_i32 s43, s42, 31
	s_lshl_b64 s[48:49], s[42:43], 19
	s_add_u32 s48, s36, s48
	s_addc_u32 s49, s37, s49
	s_and_b64 s[50:51], s[4:5], exec
	s_cselect_b32 s43, s49, s21
	s_cselect_b32 s78, s48, s20
	s_ashr_i32 s19, s18, 31
	s_lshl_b64 s[50:51], s[18:19], 19
	s_add_u32 s50, s61, s50
	s_addc_u32 s51, s62, s51
	s_and_b64 s[54:55], s[4:5], exec
	s_cselect_b32 s19, s51, s53
	s_cselect_b32 s79, s50, s52
	s_add_u32 s20, s20, 0x40080
	s_addc_u32 s21, s21, 0
	s_add_u32 s80, s52, 0x100
	s_addc_u32 s81, s53, 0
	s_mov_b32 s84, -2
	s_add_u32 s98, s28, 0x183500
	s_addc_u32 s99, s29, 0
	v_mov_b32_e32 v251, 0
	global_load_dword v250, v251, s[98:99] sc1
	ds_read_b128 v[146:149], v165
	ds_read_b128 v[150:153], v165 offset:1024
	ds_read_b128 v[154:157], v165 offset:2048
	ds_read_b128 v[168:171], v165 offset:3072
	ds_read_b128 v[172:175], v166
	ds_read_b128 v[176:179], v166 offset:1024
	ds_read_b128 v[180:183], v166 offset:2048
	ds_read_b128 v[184:187], v166 offset:3072
	s_add_u32 s52, s20, 0xfffc0080
	s_addc_u32 s53, s21, -1
	s_cmp_eq_u32 s84, 12
	s_cselect_b32 s55, s43, s53
	s_cselect_b32 s54, s78, s52
	s_cselect_b32 s53, s19, s81
	s_cselect_b32 s52, s79, s80
	s_add_i32 m0, s35, 0xc000
	ds_read_b128 v[188:191], v167
	ds_read_b128 v[192:195], v167 offset:1024
	ds_read_b128 v[198:201], v167 offset:2048
	ds_read_b128 v[202:205], v167 offset:3072
	ds_read_b128 v[206:209], v167 offset:4096
	ds_read_b128 v[210:213], v167 offset:5120
	ds_read_b128 v[214:217], v167 offset:6144
	ds_read_b128 v[218:221], v167 offset:7168
	global_load_lds_dwordx4 v138, s[20:21]
	s_add_i32 m0, s35, 0xe000
	s_nop 0
	global_load_lds_dwordx4 v140, s[20:21]
	s_waitcnt vmcnt(8)
	s_waitcnt lgkmcnt(0)
	s_barrier
	v_mfma_f32_16x16x32_bf16 v[124:127], v[146:149], v[188:191], 0
	v_mfma_f32_16x16x32_bf16 v[120:123], v[154:157], v[188:191], 0
	v_mfma_f32_16x16x32_bf16 v[108:111], v[146:149], v[198:201], 0
	v_mfma_f32_16x16x32_bf16 v[104:107], v[154:157], v[198:201], 0
	v_mfma_f32_16x16x32_bf16 v[92:95], v[146:149], v[206:209], 0
	v_mfma_f32_16x16x32_bf16 v[88:91], v[154:157], v[206:209], 0
	v_mfma_f32_16x16x32_bf16 v[76:79], v[146:149], v[214:217], 0
	v_mfma_f32_16x16x32_bf16 v[72:75], v[154:157], v[214:217], 0
	v_mfma_f32_16x16x32_bf16 v[124:127], v[150:153], v[192:195], v[124:127]
	v_mfma_f32_16x16x32_bf16 v[120:123], v[168:171], v[192:195], v[120:123]
	v_mfma_f32_16x16x32_bf16 v[108:111], v[150:153], v[202:205], v[108:111]
	v_mfma_f32_16x16x32_bf16 v[104:107], v[168:171], v[202:205], v[104:107]
	v_mfma_f32_16x16x32_bf16 v[92:95], v[150:153], v[210:213], v[92:95]
	v_mfma_f32_16x16x32_bf16 v[88:91], v[168:171], v[210:213], v[88:91]
	v_mfma_f32_16x16x32_bf16 v[76:79], v[150:153], v[218:221], v[76:79]
	v_mfma_f32_16x16x32_bf16 v[72:75], v[168:171], v[218:221], v[72:75]
	v_mfma_f32_16x16x32_bf16 v[116:119], v[172:175], v[188:191], 0
	v_mfma_f32_16x16x32_bf16 v[112:115], v[180:183], v[188:191], 0
	v_mfma_f32_16x16x32_bf16 v[100:103], v[172:175], v[198:201], 0
	v_mfma_f32_16x16x32_bf16 v[96:99], v[180:183], v[198:201], 0
	v_mfma_f32_16x16x32_bf16 v[84:87], v[172:175], v[206:209], 0
	v_mfma_f32_16x16x32_bf16 v[80:83], v[180:183], v[206:209], 0
	v_mfma_f32_16x16x32_bf16 v[68:71], v[172:175], v[214:217], 0
	v_mfma_f32_16x16x32_bf16 v[64:67], v[180:183], v[214:217], 0
	v_mfma_f32_16x16x32_bf16 v[116:119], v[176:179], v[192:195], v[116:119]
	v_mfma_f32_16x16x32_bf16 v[112:115], v[184:187], v[192:195], v[112:115]
	v_mfma_f32_16x16x32_bf16 v[100:103], v[176:179], v[202:205], v[100:103]
	v_mfma_f32_16x16x32_bf16 v[96:99], v[184:187], v[202:205], v[96:99]
	v_mfma_f32_16x16x32_bf16 v[84:87], v[176:179], v[210:213], v[84:87]
	v_mfma_f32_16x16x32_bf16 v[80:83], v[184:187], v[210:213], v[80:83]
	v_mfma_f32_16x16x32_bf16 v[68:71], v[176:179], v[218:221], v[68:71]
	v_mfma_f32_16x16x32_bf16 v[64:67], v[184:187], v[218:221], v[64:67]
	s_barrier
	s_add_i32 s85, s72, s63
	s_add_u32 s98, s52, s8
	s_addc_u32 s99, s53, s9
	s_add_u32 s100, s54, s8
	s_addc_u32 s101, s55, s9
	s_mov_b32 m0, s85
	ds_read_b128 v[188:191], v167 offset:16384
	ds_read_b128 v[192:195], v167 offset:17408
	ds_read_b128 v[198:201], v167 offset:18432
	ds_read_b128 v[202:205], v167 offset:19456
	ds_read_b128 v[206:209], v167 offset:20480
	ds_read_b128 v[210:213], v167 offset:21504
	ds_read_b128 v[214:217], v167 offset:22528
	ds_read_b128 v[218:221], v167 offset:23552
	global_load_lds_dwordx4 v132, s[52:53]
	s_add_i32 m0, s85, 0x2000
	s_add_u32 s86, s52, 0x40000
	s_addc_u32 s87, s53, 0
	s_add_i32 s85, s73, s63
	global_load_lds_dwordx4 v128, s[52:53]
	s_mov_b32 m0, s85
	s_nop 0
	global_load_lds_dwordx4 v132, s[86:87]
	s_add_i32 m0, s85, 0x2000
	s_nop 0
	global_load_lds_dwordx4 v128, s[86:87]
	s_mov_b32 m0, s35
	s_nop 0
	global_load_lds_dwordx4 v134, s[54:55]
	s_mov_b32 m0, s65
	s_nop 0
	global_load_lds_dwordx4 v130, s[54:55]
	s_waitcnt vmcnt(8)
	s_waitcnt lgkmcnt(0)
	s_barrier
; #define PG8_STAGE(bufoff, gbase, voff) do { _Pragma("unroll") for (int _i = 0; _i < 2; ++_i) \
;         __builtin_amdgcn_global_load_lds((const unsigned*)((const char*)(gbase) + (voff)[_i]), (PG8_LAS unsigned*)(lds + (bufoff) + ldsw + _i * 8192), 16, 0, 0); } while (0)
; #define PG8_LDA(dst, b, h) do { _Pragma("unroll") for (int m = 0; m < 4; ++m) _Pragma("unroll") for (int k = 0; k < 2; ++k) dst[m][k] = *(const PG8_LAS bf16x8*)(lds + PG8_SA(b, h) + aoff + m * 2048 + k * 1024); } while (0)
; #define PG8_LDB(dst, b, h) do { _Pragma("unroll") for (int n = 0; n < 2; ++n) _Pragma("unroll") for (int k = 0; k < 2; ++k) dst[n][k] = *(const PG8_LAS bf16x8*)(lds + PG8_SB(b, h) + boff + n * 2048 + k * 1024); } while (0)
; #define PG8_MMA(ai, bj, At, Bt) do { __builtin_amdgcn_s_setprio(1); _Pragma("unroll") for (int m = 0; m < 4; ++m) _Pragma("unroll") for (int n = 0; n < 2; ++n) _Pragma("unroll") for (int k = 0; k < 2; ++k) \
;         acc[ai][bj][m][n] = __builtin_amdgcn_mfma_f32_16x16x32_bf16(Bt[n][k], At[m][k], acc[ai][bj][m][n], 0, 0, 0); __builtin_amdgcn_s_setprio(0); } while (0)
; #define PG8_WAIT_V(n) asm volatile("s_waitcnt vmcnt(" #n ")" ::: "memory")
; #define PG8_WAIT_L(n) asm volatile("s_waitcnt lgkmcnt(" #n ")" ::: "memory")
; #define PG8_BAR __builtin_amdgcn_s_barrier()
; #define PG8_SCHED __builtin_amdgcn_sched_barrier(0)
; template <class Epi, class Sched, bool ALIGN_EPI = false, bool SP2 = false>
; __device__ __forceinline__ void gemm_phase(PG8_LAS unsigned char* lds, const Gemm g, const Sched& S, const Epi& E) {
;     ...
;             PG8_WAIT_V(8); PG8_WAIT_L(0); PG8_BAR; PG8_MMA(1, 0, At, B0); PG8_MMA(1, 1, At, B1); PG8_BAR; PG8_SCHED;
;             PG8_LDB(B0, 1, 0); PG8_LDB(B1, 1, 1); PG8_SCHED; PG8_LDA(At, 1, 0); PG8_STAGE(PG8_SA(0, 1), a2 + hstep, voffA);
;             PG8_WAIT_V(8); PG8_WAIT_L(0); PG8_BAR; PG8_MMA(0, 0, At, B0); PG8_MMA(0, 1, At, B1); PG8_BAR; PG8_SCHED;
	v_mfma_f32_16x16x32_bf16 v[60:63], v[146:149], v[188:191], 0
	v_mfma_f32_16x16x32_bf16 v[56:59], v[154:157], v[188:191], 0
	v_mfma_f32_16x16x32_bf16 v[44:47], v[146:149], v[198:201], 0
	v_mfma_f32_16x16x32_bf16 v[40:43], v[154:157], v[198:201], 0
	v_mfma_f32_16x16x32_bf16 v[28:31], v[146:149], v[206:209], 0
	v_mfma_f32_16x16x32_bf16 v[24:27], v[154:157], v[206:209], 0
	v_mfma_f32_16x16x32_bf16 v[12:15], v[146:149], v[214:217], 0
	v_mfma_f32_16x16x32_bf16 v[8:11], v[154:157], v[214:217], 0
	v_mfma_f32_16x16x32_bf16 v[60:63], v[150:153], v[192:195], v[60:63]
	v_mfma_f32_16x16x32_bf16 v[56:59], v[168:171], v[192:195], v[56:59]
	v_mfma_f32_16x16x32_bf16 v[44:47], v[150:153], v[202:205], v[44:47]
	v_mfma_f32_16x16x32_bf16 v[40:43], v[168:171], v[202:205], v[40:43]
	v_mfma_f32_16x16x32_bf16 v[28:31], v[150:153], v[210:213], v[28:31]
	v_mfma_f32_16x16x32_bf16 v[24:27], v[168:171], v[210:213], v[24:27]
	v_mfma_f32_16x16x32_bf16 v[12:15], v[150:153], v[218:221], v[12:15]
	v_mfma_f32_16x16x32_bf16 v[8:11], v[168:171], v[218:221], v[8:11]
	v_mfma_f32_16x16x32_bf16 v[52:55], v[172:175], v[188:191], 0
	v_mfma_f32_16x16x32_bf16 v[48:51], v[180:183], v[188:191], 0
	v_mfma_f32_16x16x32_bf16 v[36:39], v[172:175], v[198:201], 0
	v_mfma_f32_16x16x32_bf16 v[32:35], v[180:183], v[198:201], 0
	v_mfma_f32_16x16x32_bf16 v[20:23], v[172:175], v[206:209], 0
	v_mfma_f32_16x16x32_bf16 v[16:19], v[180:183], v[206:209], 0
	v_mfma_f32_16x16x32_bf16 v[4:7], v[172:175], v[214:217], 0
	v_mfma_f32_16x16x32_bf16 v[0:3], v[180:183], v[214:217], 0
	v_mfma_f32_16x16x32_bf16 v[52:55], v[176:179], v[192:195], v[52:55]
	v_mfma_f32_16x16x32_bf16 v[48:51], v[184:187], v[192:195], v[48:51]
	v_mfma_f32_16x16x32_bf16 v[36:39], v[176:179], v[202:205], v[36:39]
	v_mfma_f32_16x16x32_bf16 v[32:35], v[184:187], v[202:205], v[32:35]
	v_mfma_f32_16x16x32_bf16 v[20:23], v[176:179], v[210:213], v[20:23]
	v_mfma_f32_16x16x32_bf16 v[16:19], v[184:187], v[210:213], v[16:19]
	v_mfma_f32_16x16x32_bf16 v[4:7], v[176:179], v[218:221], v[4:7]
	v_mfma_f32_16x16x32_bf16 v[0:3], v[184:187], v[218:221], v[0:3]
	s_barrier
	s_add_i32 s85, 0, 0x18000
	v_add_u32_e32 v136, s85, v161
	s_add_i32 s86, 0, 0x1c000
	ds_read_b128 v[146:149], v136
	ds_read_b128 v[150:153], v136 offset:1024
	ds_read_b128 v[154:157], v136 offset:2048
	ds_read_b128 v[168:171], v136 offset:3072
	v_add_u32_e32 v136, s86, v161
	ds_read_b128 v[172:175], v136
	ds_read_b128 v[176:179], v136 offset:1024
	ds_read_b128 v[180:183], v136 offset:2048
	ds_read_b128 v[184:187], v136 offset:3072
	s_add_u32 s54, s54, 0x40000
	s_addc_u32 s55, s55, 0
	s_mov_b32 m0, s66
	ds_read_b128 v[188:191], v167 offset:32768
	ds_read_b128 v[192:195], v167 offset:33792
	ds_read_b128 v[198:201], v167 offset:34816
	ds_read_b128 v[202:205], v167 offset:35840
	ds_read_b128 v[206:209], v167 offset:36864
	ds_read_b128 v[210:213], v167 offset:37888
	ds_read_b128 v[214:217], v167 offset:38912
	ds_read_b128 v[218:221], v167 offset:39936
	global_load_lds_dwordx4 v134, s[54:55]
	s_mov_b32 m0, s67
	s_nop 0
	global_load_lds_dwordx4 v130, s[54:55]
	s_waitcnt vmcnt(8)
	s_waitcnt lgkmcnt(0)
	s_barrier
	v_mfma_f32_16x16x32_bf16 v[124:127], v[146:149], v[188:191], v[124:127]
	v_mfma_f32_16x16x32_bf16 v[120:123], v[154:157], v[188:191], v[120:123]
	v_mfma_f32_16x16x32_bf16 v[108:111], v[146:149], v[198:201], v[108:111]
	v_mfma_f32_16x16x32_bf16 v[104:107], v[154:157], v[198:201], v[104:107]
	v_mfma_f32_16x16x32_bf16 v[92:95], v[146:149], v[206:209], v[92:95]
	v_mfma_f32_16x16x32_bf16 v[88:91], v[154:157], v[206:209], v[88:91]
	v_mfma_f32_16x16x32_bf16 v[76:79], v[146:149], v[214:217], v[76:79]
	v_mfma_f32_16x16x32_bf16 v[72:75], v[154:157], v[214:217], v[72:75]
	v_mfma_f32_16x16x32_bf16 v[124:127], v[150:153], v[192:195], v[124:127]
	v_mfma_f32_16x16x32_bf16 v[120:123], v[168:171], v[192:195], v[120:123]
	v_mfma_f32_16x16x32_bf16 v[108:111], v[150:153], v[202:205], v[108:111]
	v_mfma_f32_16x16x32_bf16 v[104:107], v[168:171], v[202:205], v[104:107]
	v_mfma_f32_16x16x32_bf16 v[92:95], v[150:153], v[210:213], v[92:95]
	v_mfma_f32_16x16x32_bf16 v[88:91], v[168:171], v[210:213], v[88:91]
	v_mfma_f32_16x16x32_bf16 v[76:79], v[150:153], v[218:221], v[76:79]
	v_mfma_f32_16x16x32_bf16 v[72:75], v[168:171], v[218:221], v[72:75]
	v_mfma_f32_16x16x32_bf16 v[116:119], v[172:175], v[188:191], v[116:119]
	v_mfma_f32_16x16x32_bf16 v[112:115], v[180:183], v[188:191], v[112:115]
	v_mfma_f32_16x16x32_bf16 v[100:103], v[172:175], v[198:201], v[100:103]
	v_mfma_f32_16x16x32_bf16 v[96:99], v[180:183], v[198:201], v[96:99]
	v_mfma_f32_16x16x32_bf16 v[84:87], v[172:175], v[206:209], v[84:87]
	v_mfma_f32_16x16x32_bf16 v[80:83], v[180:183], v[206:209], v[80:83]
	v_mfma_f32_16x16x32_bf16 v[68:71], v[172:175], v[214:217], v[68:71]
	v_mfma_f32_16x16x32_bf16 v[64:67], v[180:183], v[214:217], v[64:67]
	v_mfma_f32_16x16x32_bf16 v[116:119], v[176:179], v[192:195], v[116:119]
	v_mfma_f32_16x16x32_bf16 v[112:115], v[184:187], v[192:195], v[112:115]
	v_mfma_f32_16x16x32_bf16 v[100:103], v[176:179], v[202:205], v[100:103]
	v_mfma_f32_16x16x32_bf16 v[96:99], v[184:187], v[202:205], v[96:99]
	v_mfma_f32_16x16x32_bf16 v[84:87], v[176:179], v[210:213], v[84:87]
	v_mfma_f32_16x16x32_bf16 v[80:83], v[184:187], v[210:213], v[80:83]
	v_mfma_f32_16x16x32_bf16 v[68:71], v[176:179], v[218:221], v[68:71]
	v_mfma_f32_16x16x32_bf16 v[64:67], v[184:187], v[218:221], v[64:67]
	s_barrier
; #define PG8_STAGE(bufoff, gbase, voff) do { _Pragma("unroll") for (int _i = 0; _i < 2; ++_i) \
;         __builtin_amdgcn_global_load_lds((const unsigned*)((const char*)(gbase) + (voff)[_i]), (PG8_LAS unsigned*)(lds + (bufoff) + ldsw + _i * 8192), 16, 0, 0); } while (0)
; #define PG8_LDA(dst, b, h) do { _Pragma("unroll") for (int m = 0; m < 4; ++m) _Pragma("unroll") for (int k = 0; k < 2; ++k) dst[m][k] = *(const PG8_LAS bf16x8*)(lds + PG8_SA(b, h) + aoff + m * 2048 + k * 1024); } while (0)
; #define PG8_LDB(dst, b, h) do { _Pragma("unroll") for (int n = 0; n < 2; ++n) _Pragma("unroll") for (int k = 0; k < 2; ++k) dst[n][k] = *(const PG8_LAS bf16x8*)(lds + PG8_SB(b, h) + boff + n * 2048 + k * 1024); } while (0)
; #define PG8_MMA(ai, bj, At, Bt) do { __builtin_amdgcn_s_setprio(1); _Pragma("unroll") for (int m = 0; m < 4; ++m) _Pragma("unroll") for (int n = 0; n < 2; ++n) _Pragma("unroll") for (int k = 0; k < 2; ++k) \
;         acc[ai][bj][m][n] = __builtin_amdgcn_mfma_f32_16x16x32_bf16(Bt[n][k], At[m][k], acc[ai][bj][m][n], 0, 0, 0); __builtin_amdgcn_s_setprio(0); } while (0)
; #define PG8_WAIT_V(n) asm volatile("s_waitcnt vmcnt(" #n ")" ::: "memory")
; #define PG8_WAIT_L(n) asm volatile("s_waitcnt lgkmcnt(" #n ")" ::: "memory")
; #define PG8_BAR __builtin_amdgcn_s_barrier()
; #define PG8_SCHED __builtin_amdgcn_sched_barrier(0)
; template <class Epi, class Sched, bool ALIGN_EPI = false, bool SP2 = false>
; __device__ __forceinline__ void gemm_phase(PG8_LAS unsigned char* lds, const Gemm g, const Sched& S, const Epi& E) {
;     ...
;             PG8_LDB(B0, 0, 0); PG8_LDB(B1, 0, 1); PG8_SCHED; PG8_LDA(At, 0, 0); PG8_STAGE(PG8_SA(1, 1), a1 + hstep, voffA);
;             PG8_WAIT_V(8); PG8_WAIT_L(0); PG8_BAR; PG8_MMA(0, 0, At, B0); PG8_MMA(0, 1, At, B1); PG8_BAR; PG8_SCHED;
;     ...
;             PG8_LDA(At, 1, 1); PG8_STAGE(PG8_SB(1, 0), b3, voffB); PG8_STAGE(PG8_SB(1, 1), b3 + hstep, voffB); PG8_STAGE(PG8_SA(1, 0), a3, voffA);
;             PG8_WAIT_V(8); PG8_WAIT_L(0); PG8_BAR; PG8_MMA(1, 0, At, B0); PG8_MMA(1, 1, At, B1); PG8_BAR; PG8_SCHED;
	s_add_i32 s54, s85, s63
	s_mov_b32 m0, s54
	ds_read_b128 v[188:191], v167 offset:49152
	ds_read_b128 v[192:195], v167 offset:50176
	ds_read_b128 v[198:201], v167 offset:51200
	ds_read_b128 v[202:205], v167 offset:52224
	ds_read_b128 v[206:209], v167 offset:53248
	ds_read_b128 v[210:213], v167 offset:54272
	ds_read_b128 v[214:217], v167 offset:55296
	ds_read_b128 v[218:221], v167 offset:56320
	global_load_lds_dwordx4 v132, s[98:99]
	s_add_i32 m0, s54, 0x2000
	s_add_u32 s52, s52, 0x40080
	s_addc_u32 s53, s53, 0
	s_add_i32 s54, s86, s63
	global_load_lds_dwordx4 v128, s[98:99]
	s_mov_b32 m0, s54
	s_nop 0
	global_load_lds_dwordx4 v132, s[52:53]
	s_add_i32 m0, s54, 0x2000
	s_nop 0
	global_load_lds_dwordx4 v128, s[52:53]
	s_mov_b32 m0, s69
	s_nop 0
	global_load_lds_dwordx4 v134, s[100:101]
	s_mov_b32 m0, s70
	s_nop 0
	global_load_lds_dwordx4 v130, s[100:101]
	s_waitcnt vmcnt(8)
	s_waitcnt lgkmcnt(0)
	s_barrier
	v_mfma_f32_16x16x32_bf16 v[60:63], v[146:149], v[188:191], v[60:63]
	v_mfma_f32_16x16x32_bf16 v[56:59], v[154:157], v[188:191], v[56:59]
	v_mfma_f32_16x16x32_bf16 v[44:47], v[146:149], v[198:201], v[44:47]
	v_mfma_f32_16x16x32_bf16 v[40:43], v[154:157], v[198:201], v[40:43]
	v_mfma_f32_16x16x32_bf16 v[28:31], v[146:149], v[206:209], v[28:31]
	v_mfma_f32_16x16x32_bf16 v[24:27], v[154:157], v[206:209], v[24:27]
	v_mfma_f32_16x16x32_bf16 v[12:15], v[146:149], v[214:217], v[12:15]
	v_mfma_f32_16x16x32_bf16 v[8:11], v[154:157], v[214:217], v[8:11]
	v_mfma_f32_16x16x32_bf16 v[60:63], v[150:153], v[192:195], v[60:63]
	v_mfma_f32_16x16x32_bf16 v[56:59], v[168:171], v[192:195], v[56:59]
	v_mfma_f32_16x16x32_bf16 v[44:47], v[150:153], v[202:205], v[44:47]
	v_mfma_f32_16x16x32_bf16 v[40:43], v[168:171], v[202:205], v[40:43]
	v_mfma_f32_16x16x32_bf16 v[28:31], v[150:153], v[210:213], v[28:31]
	v_mfma_f32_16x16x32_bf16 v[24:27], v[168:171], v[210:213], v[24:27]
	v_mfma_f32_16x16x32_bf16 v[12:15], v[150:153], v[218:221], v[12:15]
	v_mfma_f32_16x16x32_bf16 v[8:11], v[168:171], v[218:221], v[8:11]
	v_mfma_f32_16x16x32_bf16 v[52:55], v[172:175], v[188:191], v[52:55]
	v_mfma_f32_16x16x32_bf16 v[48:51], v[180:183], v[188:191], v[48:51]
	v_mfma_f32_16x16x32_bf16 v[36:39], v[172:175], v[198:201], v[36:39]
	v_mfma_f32_16x16x32_bf16 v[32:35], v[180:183], v[198:201], v[32:35]
	v_mfma_f32_16x16x32_bf16 v[20:23], v[172:175], v[206:209], v[20:23]
	v_mfma_f32_16x16x32_bf16 v[16:19], v[180:183], v[206:209], v[16:19]
	v_mfma_f32_16x16x32_bf16 v[4:7], v[172:175], v[214:217], v[4:7]
	v_mfma_f32_16x16x32_bf16 v[0:3], v[180:183], v[214:217], v[0:3]
	v_mfma_f32_16x16x32_bf16 v[52:55], v[176:179], v[192:195], v[52:55]
	v_mfma_f32_16x16x32_bf16 v[48:51], v[184:187], v[192:195], v[48:51]
	v_mfma_f32_16x16x32_bf16 v[36:39], v[176:179], v[202:205], v[36:39]
	v_mfma_f32_16x16x32_bf16 v[32:35], v[184:187], v[202:205], v[32:35]
	v_mfma_f32_16x16x32_bf16 v[20:23], v[176:179], v[210:213], v[20:23]
	v_mfma_f32_16x16x32_bf16 v[16:19], v[184:187], v[210:213], v[16:19]
	v_mfma_f32_16x16x32_bf16 v[4:7], v[176:179], v[218:221], v[4:7]
	v_mfma_f32_16x16x32_bf16 v[0:3], v[184:187], v[218:221], v[0:3]
	s_barrier
	s_add_i32 s84, s84, 2
	s_add_u32 s20, s20, 0x100
	s_addc_u32 s21, s21, 0
	s_add_u32 s80, s80, 0x100
	s_addc_u32 s81, s81, 0
	s_cmp_gt_u32 s84, 13
.LBB0_414:
	ds_read_b128 v[146:149], v165
	ds_read_b128 v[150:153], v165 offset:1024
	ds_read_b128 v[154:157], v165 offset:2048
	ds_read_b128 v[168:171], v165 offset:3072
	ds_read_b128 v[172:175], v166
	ds_read_b128 v[176:179], v166 offset:1024
	ds_read_b128 v[180:183], v166 offset:2048
	ds_read_b128 v[184:187], v166 offset:3072
	s_add_u32 s52, s20, 0xfffc0080
	s_addc_u32 s53, s21, -1
	s_cmp_eq_u32 s84, 12
	s_cselect_b32 s55, s43, s53
	s_cselect_b32 s54, s78, s52
	s_cselect_b32 s53, s19, s81
	s_cselect_b32 s52, s79, s80
	s_add_i32 m0, s35, 0xc000
	ds_read_b128 v[188:191], v167
	ds_read_b128 v[192:195], v167 offset:1024
	ds_read_b128 v[198:201], v167 offset:2048
	ds_read_b128 v[202:205], v167 offset:3072
	ds_read_b128 v[206:209], v167 offset:4096
	ds_read_b128 v[210:213], v167 offset:5120
	ds_read_b128 v[214:217], v167 offset:6144
	ds_read_b128 v[218:221], v167 offset:7168
	global_load_lds_dwordx4 v138, s[20:21]
	s_add_i32 m0, s35, 0xe000
	s_nop 0
	global_load_lds_dwordx4 v140, s[20:21]
	s_waitcnt vmcnt(8)
	s_waitcnt lgkmcnt(0)
	s_barrier
	v_mfma_f32_16x16x32_bf16 v[124:127], v[146:149], v[188:191], v[124:127]
	v_mfma_f32_16x16x32_bf16 v[120:123], v[154:157], v[188:191], v[120:123]
	v_mfma_f32_16x16x32_bf16 v[108:111], v[146:149], v[198:201], v[108:111]
	v_mfma_f32_16x16x32_bf16 v[104:107], v[154:157], v[198:201], v[104:107]
	v_mfma_f32_16x16x32_bf16 v[92:95], v[146:149], v[206:209], v[92:95]
	v_mfma_f32_16x16x32_bf16 v[88:91], v[154:157], v[206:209], v[88:91]
	v_mfma_f32_16x16x32_bf16 v[76:79], v[146:149], v[214:217], v[76:79]
	v_mfma_f32_16x16x32_bf16 v[72:75], v[154:157], v[214:217], v[72:75]
	v_mfma_f32_16x16x32_bf16 v[124:127], v[150:153], v[192:195], v[124:127]
	v_mfma_f32_16x16x32_bf16 v[120:123], v[168:171], v[192:195], v[120:123]
	v_mfma_f32_16x16x32_bf16 v[108:111], v[150:153], v[202:205], v[108:111]
	v_mfma_f32_16x16x32_bf16 v[104:107], v[168:171], v[202:205], v[104:107]
	v_mfma_f32_16x16x32_bf16 v[92:95], v[150:153], v[210:213], v[92:95]
	v_mfma_f32_16x16x32_bf16 v[88:91], v[168:171], v[210:213], v[88:91]
	v_mfma_f32_16x16x32_bf16 v[76:79], v[150:153], v[218:221], v[76:79]
	v_mfma_f32_16x16x32_bf16 v[72:75], v[168:171], v[218:221], v[72:75]
	v_mfma_f32_16x16x32_bf16 v[116:119], v[172:175], v[188:191], v[116:119]
	v_mfma_f32_16x16x32_bf16 v[112:115], v[180:183], v[188:191], v[112:115]
	v_mfma_f32_16x16x32_bf16 v[100:103], v[172:175], v[198:201], v[100:103]
	v_mfma_f32_16x16x32_bf16 v[96:99], v[180:183], v[198:201], v[96:99]
	v_mfma_f32_16x16x32_bf16 v[84:87], v[172:175], v[206:209], v[84:87]
	v_mfma_f32_16x16x32_bf16 v[80:83], v[180:183], v[206:209], v[80:83]
	v_mfma_f32_16x16x32_bf16 v[68:71], v[172:175], v[214:217], v[68:71]
	v_mfma_f32_16x16x32_bf16 v[64:67], v[180:183], v[214:217], v[64:67]
	v_mfma_f32_16x16x32_bf16 v[116:119], v[176:179], v[192:195], v[116:119]
	v_mfma_f32_16x16x32_bf16 v[112:115], v[184:187], v[192:195], v[112:115]
	v_mfma_f32_16x16x32_bf16 v[100:103], v[176:179], v[202:205], v[100:103]
	v_mfma_f32_16x16x32_bf16 v[96:99], v[184:187], v[202:205], v[96:99]
	v_mfma_f32_16x16x32_bf16 v[84:87], v[176:179], v[210:213], v[84:87]
	v_mfma_f32_16x16x32_bf16 v[80:83], v[184:187], v[210:213], v[80:83]
	v_mfma_f32_16x16x32_bf16 v[68:71], v[176:179], v[218:221], v[68:71]
	v_mfma_f32_16x16x32_bf16 v[64:67], v[184:187], v[218:221], v[64:67]
	s_barrier
; #define PG8_STAGE(bufoff, gbase, voff) do { _Pragma("unroll") for (int _i = 0; _i < 2; ++_i) \
;         __builtin_amdgcn_global_load_lds((const unsigned*)((const char*)(gbase) + (voff)[_i]), (PG8_LAS unsigned*)(lds + (bufoff) + ldsw + _i * 8192), 16, 0, 0); } while (0)
; #define PG8_LDA(dst, b, h) do { _Pragma("unroll") for (int m = 0; m < 4; ++m) _Pragma("unroll") for (int k = 0; k < 2; ++k) dst[m][k] = *(const PG8_LAS bf16x8*)(lds + PG8_SA(b, h) + aoff + m * 2048 + k * 1024); } while (0)
; #define PG8_LDB(dst, b, h) do { _Pragma("unroll") for (int n = 0; n < 2; ++n) _Pragma("unroll") for (int k = 0; k < 2; ++k) dst[n][k] = *(const PG8_LAS bf16x8*)(lds + PG8_SB(b, h) + boff + n * 2048 + k * 1024); } while (0)
; #define PG8_MMA(ai, bj, At, Bt) do { __builtin_amdgcn_s_setprio(1); _Pragma("unroll") for (int m = 0; m < 4; ++m) _Pragma("unroll") for (int n = 0; n < 2; ++n) _Pragma("unroll") for (int k = 0; k < 2; ++k) \
;         acc[ai][bj][m][n] = __builtin_amdgcn_mfma_f32_16x16x32_bf16(Bt[n][k], At[m][k], acc[ai][bj][m][n], 0, 0, 0); __builtin_amdgcn_s_setprio(0); } while (0)
; #define PG8_WAIT_V(n) asm volatile("s_waitcnt vmcnt(" #n ")" ::: "memory")
; #define PG8_WAIT_L(n) asm volatile("s_waitcnt lgkmcnt(" #n ")" ::: "memory")
; #define PG8_BAR __builtin_amdgcn_s_barrier()
; #define PG8_SCHED __builtin_amdgcn_sched_barrier(0)
; template <class Epi, class Sched, bool ALIGN_EPI = false, bool SP2 = false>
; __device__ __forceinline__ void gemm_phase(PG8_LAS unsigned char* lds, const Gemm g, const Sched& S, const Epi& E) {
;     ...
;             PG8_LDA(At, 0, 1); PG8_STAGE(PG8_SB(0, 0), b2, voffB); PG8_STAGE(PG8_SB(0, 1), b2 + hstep, voffB); PG8_STAGE(PG8_SA(0, 0), a2, voffA);
;             PG8_WAIT_V(8); PG8_WAIT_L(0); PG8_BAR; PG8_MMA(1, 0, At, B0); PG8_MMA(1, 1, At, B1); PG8_BAR; PG8_SCHED;
;             PG8_LDB(B0, 1, 0); PG8_LDB(B1, 1, 1); PG8_SCHED; PG8_LDA(At, 1, 0); PG8_STAGE(PG8_SA(0, 1), a2 + hstep, voffA);
;             PG8_WAIT_V(8); PG8_WAIT_L(0); PG8_BAR; PG8_MMA(0, 0, At, B0); PG8_MMA(0, 1, At, B1); PG8_BAR; PG8_SCHED;
	s_add_i32 s85, s72, s63
	s_add_u32 s98, s52, s8
	s_addc_u32 s99, s53, s9
	s_add_u32 s100, s54, s8
	s_addc_u32 s101, s55, s9
	s_mov_b32 m0, s85
	ds_read_b128 v[188:191], v167 offset:16384
	ds_read_b128 v[192:195], v167 offset:17408
	ds_read_b128 v[198:201], v167 offset:18432
	ds_read_b128 v[202:205], v167 offset:19456
	ds_read_b128 v[206:209], v167 offset:20480
	ds_read_b128 v[210:213], v167 offset:21504
	ds_read_b128 v[214:217], v167 offset:22528
	ds_read_b128 v[218:221], v167 offset:23552
	global_load_lds_dwordx4 v132, s[52:53]
	s_add_i32 m0, s85, 0x2000
	s_add_u32 s86, s52, 0x40000
	s_addc_u32 s87, s53, 0
	s_add_i32 s85, s73, s63
	global_load_lds_dwordx4 v128, s[52:53]
	s_mov_b32 m0, s85
	s_nop 0
	global_load_lds_dwordx4 v132, s[86:87]
	s_add_i32 m0, s85, 0x2000
	s_nop 0
	global_load_lds_dwordx4 v128, s[86:87]
	s_mov_b32 m0, s35
	s_nop 0
	global_load_lds_dwordx4 v134, s[54:55]
	s_mov_b32 m0, s65
	s_nop 0
	global_load_lds_dwordx4 v130, s[54:55]
	s_waitcnt vmcnt(8)
	s_waitcnt lgkmcnt(0)
	s_barrier
	v_mfma_f32_16x16x32_bf16 v[60:63], v[146:149], v[188:191], v[60:63]
	v_mfma_f32_16x16x32_bf16 v[56:59], v[154:157], v[188:191], v[56:59]
	v_mfma_f32_16x16x32_bf16 v[44:47], v[146:149], v[198:201], v[44:47]
	v_mfma_f32_16x16x32_bf16 v[40:43], v[154:157], v[198:201], v[40:43]
	v_mfma_f32_16x16x32_bf16 v[28:31], v[146:149], v[206:209], v[28:31]
	v_mfma_f32_16x16x32_bf16 v[24:27], v[154:157], v[206:209], v[24:27]
	v_mfma_f32_16x16x32_bf16 v[12:15], v[146:149], v[214:217], v[12:15]
	v_mfma_f32_16x16x32_bf16 v[8:11], v[154:157], v[214:217], v[8:11]
	v_mfma_f32_16x16x32_bf16 v[60:63], v[150:153], v[192:195], v[60:63]
	v_mfma_f32_16x16x32_bf16 v[56:59], v[168:171], v[192:195], v[56:59]
	v_mfma_f32_16x16x32_bf16 v[44:47], v[150:153], v[202:205], v[44:47]
	v_mfma_f32_16x16x32_bf16 v[40:43], v[168:171], v[202:205], v[40:43]
	v_mfma_f32_16x16x32_bf16 v[28:31], v[150:153], v[210:213], v[28:31]
	v_mfma_f32_16x16x32_bf16 v[24:27], v[168:171], v[210:213], v[24:27]
	v_mfma_f32_16x16x32_bf16 v[12:15], v[150:153], v[218:221], v[12:15]
	v_mfma_f32_16x16x32_bf16 v[8:11], v[168:171], v[218:221], v[8:11]
	v_mfma_f32_16x16x32_bf16 v[52:55], v[172:175], v[188:191], v[52:55]
	v_mfma_f32_16x16x32_bf16 v[48:51], v[180:183], v[188:191], v[48:51]
	v_mfma_f32_16x16x32_bf16 v[36:39], v[172:175], v[198:201], v[36:39]
	v_mfma_f32_16x16x32_bf16 v[32:35], v[180:183], v[198:201], v[32:35]
	v_mfma_f32_16x16x32_bf16 v[20:23], v[172:175], v[206:209], v[20:23]
	v_mfma_f32_16x16x32_bf16 v[16:19], v[180:183], v[206:209], v[16:19]
	v_mfma_f32_16x16x32_bf16 v[4:7], v[172:175], v[214:217], v[4:7]
	v_mfma_f32_16x16x32_bf16 v[0:3], v[180:183], v[214:217], v[0:3]
	v_mfma_f32_16x16x32_bf16 v[52:55], v[176:179], v[192:195], v[52:55]
	v_mfma_f32_16x16x32_bf16 v[48:51], v[184:187], v[192:195], v[48:51]
	v_mfma_f32_16x16x32_bf16 v[36:39], v[176:179], v[202:205], v[36:39]
	v_mfma_f32_16x16x32_bf16 v[32:35], v[184:187], v[202:205], v[32:35]
	v_mfma_f32_16x16x32_bf16 v[20:23], v[176:179], v[210:213], v[20:23]
	v_mfma_f32_16x16x32_bf16 v[16:19], v[184:187], v[210:213], v[16:19]
	v_mfma_f32_16x16x32_bf16 v[4:7], v[176:179], v[218:221], v[4:7]
	v_mfma_f32_16x16x32_bf16 v[0:3], v[184:187], v[218:221], v[0:3]
	s_barrier
	s_add_i32 s85, 0, 0x18000
	v_add_u32_e32 v136, s85, v161
	s_add_i32 s86, 0, 0x1c000
	ds_read_b128 v[146:149], v136
	ds_read_b128 v[150:153], v136 offset:1024
	ds_read_b128 v[154:157], v136 offset:2048
	ds_read_b128 v[168:171], v136 offset:3072
	v_add_u32_e32 v136, s86, v161
	ds_read_b128 v[172:175], v136
	ds_read_b128 v[176:179], v136 offset:1024
	ds_read_b128 v[180:183], v136 offset:2048
	ds_read_b128 v[184:187], v136 offset:3072
	s_add_u32 s54, s54, 0x40000
	s_addc_u32 s55, s55, 0
	s_mov_b32 m0, s66
	ds_read_b128 v[188:191], v167 offset:32768
	ds_read_b128 v[192:195], v167 offset:33792
	ds_read_b128 v[198:201], v167 offset:34816
	ds_read_b128 v[202:205], v167 offset:35840
	ds_read_b128 v[206:209], v167 offset:36864
	ds_read_b128 v[210:213], v167 offset:37888
	ds_read_b128 v[214:217], v167 offset:38912
	ds_read_b128 v[218:221], v167 offset:39936
	global_load_lds_dwordx4 v134, s[54:55]
	s_mov_b32 m0, s67
	s_nop 0
	global_load_lds_dwordx4 v130, s[54:55]
	s_waitcnt vmcnt(8)
	s_waitcnt lgkmcnt(0)
	s_barrier
; #define PG8_STAGE(bufoff, gbase, voff) do { _Pragma("unroll") for (int _i = 0; _i < 2; ++_i) \
;         __builtin_amdgcn_global_load_lds((const unsigned*)((const char*)(gbase) + (voff)[_i]), (PG8_LAS unsigned*)(lds + (bufoff) + ldsw + _i * 8192), 16, 0, 0); } while (0)
; #define PG8_LDA(dst, b, h) do { _Pragma("unroll") for (int m = 0; m < 4; ++m) _Pragma("unroll") for (int k = 0; k < 2; ++k) dst[m][k] = *(const PG8_LAS bf16x8*)(lds + PG8_SA(b, h) + aoff + m * 2048 + k * 1024); } while (0)
; #define PG8_MMA(ai, bj, At, Bt) do { __builtin_amdgcn_s_setprio(1); _Pragma("unroll") for (int m = 0; m < 4; ++m) _Pragma("unroll") for (int n = 0; n < 2; ++n) _Pragma("unroll") for (int k = 0; k < 2; ++k) \
;         acc[ai][bj][m][n] = __builtin_amdgcn_mfma_f32_16x16x32_bf16(Bt[n][k], At[m][k], acc[ai][bj][m][n], 0, 0, 0); __builtin_amdgcn_s_setprio(0); } while (0)
; #define PG8_WAIT_V(n) asm volatile("s_waitcnt vmcnt(" #n ")" ::: "memory")
; #define PG8_WAIT_L(n) asm volatile("s_waitcnt lgkmcnt(" #n ")" ::: "memory")
; #define PG8_BAR __builtin_amdgcn_s_barrier()
; #define PG8_SCHED __builtin_amdgcn_sched_barrier(0)
; template <class Epi, class Sched, bool ALIGN_EPI = false, bool SP2 = false>
; __device__ __forceinline__ void gemm_phase(PG8_LAS unsigned char* lds, const Gemm g, const Sched& S, const Epi& E) {
;     ...
;             PG8_WAIT_V(8); PG8_WAIT_L(0); PG8_BAR; PG8_MMA(0, 0, At, B0); PG8_MMA(0, 1, At, B1); PG8_BAR; PG8_SCHED;
;             PG8_LDA(At, 1, 1); PG8_STAGE(PG8_SB(1, 0), b3, voffB); PG8_STAGE(PG8_SB(1, 1), b3 + hstep, voffB); PG8_STAGE(PG8_SA(1, 0), a3, voffA);
;             PG8_WAIT_V(8); PG8_WAIT_L(0); PG8_BAR; PG8_MMA(1, 0, At, B0); PG8_MMA(1, 1, At, B1); PG8_BAR; PG8_SCHED;
;     ...
;         if constexpr (ALIGN_EPI) { if (wr == 0) PG8_BAR; }
;         if constexpr (!Epi::AFTER_DRAIN) { E(acc, cur, wr, wc, fr, fq); S.done(cur); }
	v_mfma_f32_16x16x32_bf16 v[124:127], v[146:149], v[188:191], v[124:127]
	v_mfma_f32_16x16x32_bf16 v[120:123], v[154:157], v[188:191], v[120:123]
	v_mfma_f32_16x16x32_bf16 v[108:111], v[146:149], v[198:201], v[108:111]
	v_mfma_f32_16x16x32_bf16 v[104:107], v[154:157], v[198:201], v[104:107]
	v_mfma_f32_16x16x32_bf16 v[92:95], v[146:149], v[206:209], v[92:95]
	v_mfma_f32_16x16x32_bf16 v[88:91], v[154:157], v[206:209], v[88:91]
	v_mfma_f32_16x16x32_bf16 v[76:79], v[146:149], v[214:217], v[76:79]
	v_mfma_f32_16x16x32_bf16 v[72:75], v[154:157], v[214:217], v[72:75]
	v_mfma_f32_16x16x32_bf16 v[124:127], v[150:153], v[192:195], v[124:127]
	v_mfma_f32_16x16x32_bf16 v[120:123], v[168:171], v[192:195], v[120:123]
	v_mfma_f32_16x16x32_bf16 v[108:111], v[150:153], v[202:205], v[108:111]
	v_mfma_f32_16x16x32_bf16 v[104:107], v[168:171], v[202:205], v[104:107]
	v_mfma_f32_16x16x32_bf16 v[92:95], v[150:153], v[210:213], v[92:95]
	v_mfma_f32_16x16x32_bf16 v[88:91], v[168:171], v[210:213], v[88:91]
	v_mfma_f32_16x16x32_bf16 v[76:79], v[150:153], v[218:221], v[76:79]
	v_mfma_f32_16x16x32_bf16 v[72:75], v[168:171], v[218:221], v[72:75]
	v_mfma_f32_16x16x32_bf16 v[116:119], v[172:175], v[188:191], v[116:119]
	v_mfma_f32_16x16x32_bf16 v[112:115], v[180:183], v[188:191], v[112:115]
	v_mfma_f32_16x16x32_bf16 v[100:103], v[172:175], v[198:201], v[100:103]
	v_mfma_f32_16x16x32_bf16 v[96:99], v[180:183], v[198:201], v[96:99]
	v_mfma_f32_16x16x32_bf16 v[84:87], v[172:175], v[206:209], v[84:87]
	v_mfma_f32_16x16x32_bf16 v[80:83], v[180:183], v[206:209], v[80:83]
	v_mfma_f32_16x16x32_bf16 v[68:71], v[172:175], v[214:217], v[68:71]
	v_mfma_f32_16x16x32_bf16 v[64:67], v[180:183], v[214:217], v[64:67]
	v_mfma_f32_16x16x32_bf16 v[116:119], v[176:179], v[192:195], v[116:119]
	v_mfma_f32_16x16x32_bf16 v[112:115], v[184:187], v[192:195], v[112:115]
	v_mfma_f32_16x16x32_bf16 v[100:103], v[176:179], v[202:205], v[100:103]
	v_mfma_f32_16x16x32_bf16 v[96:99], v[184:187], v[202:205], v[96:99]
	v_mfma_f32_16x16x32_bf16 v[84:87], v[176:179], v[210:213], v[84:87]
	v_mfma_f32_16x16x32_bf16 v[80:83], v[184:187], v[210:213], v[80:83]
	v_mfma_f32_16x16x32_bf16 v[68:71], v[176:179], v[218:221], v[68:71]
	v_mfma_f32_16x16x32_bf16 v[64:67], v[184:187], v[218:221], v[64:67]
	s_barrier
	s_add_i32 s54, s85, s63
	s_mov_b32 m0, s54
	ds_read_b128 v[188:191], v167 offset:49152
	ds_read_b128 v[192:195], v167 offset:50176
	ds_read_b128 v[198:201], v167 offset:51200
	ds_read_b128 v[202:205], v167 offset:52224
	ds_read_b128 v[206:209], v167 offset:53248
	ds_read_b128 v[210:213], v167 offset:54272
	ds_read_b128 v[214:217], v167 offset:55296
	ds_read_b128 v[218:221], v167 offset:56320
	global_load_lds_dwordx4 v132, s[98:99]
	s_add_i32 m0, s54, 0x2000
	s_add_u32 s52, s52, 0x40080
	s_addc_u32 s53, s53, 0
	s_add_i32 s54, s86, s63
	global_load_lds_dwordx4 v128, s[98:99]
	s_mov_b32 m0, s54
	s_nop 0
	global_load_lds_dwordx4 v132, s[52:53]
	s_add_i32 m0, s54, 0x2000
	s_nop 0
	global_load_lds_dwordx4 v128, s[52:53]
	s_mov_b32 m0, s69
	s_nop 0
	global_load_lds_dwordx4 v134, s[100:101]
	s_mov_b32 m0, s70
	s_nop 0
	global_load_lds_dwordx4 v130, s[100:101]
	s_waitcnt vmcnt(8)
	s_waitcnt lgkmcnt(0)
	s_barrier
	v_mfma_f32_16x16x32_bf16 v[60:63], v[146:149], v[188:191], v[60:63]
	v_mfma_f32_16x16x32_bf16 v[56:59], v[154:157], v[188:191], v[56:59]
	v_mfma_f32_16x16x32_bf16 v[44:47], v[146:149], v[198:201], v[44:47]
	v_mfma_f32_16x16x32_bf16 v[40:43], v[154:157], v[198:201], v[40:43]
	v_mfma_f32_16x16x32_bf16 v[28:31], v[146:149], v[206:209], v[28:31]
	v_mfma_f32_16x16x32_bf16 v[24:27], v[154:157], v[206:209], v[24:27]
	v_mfma_f32_16x16x32_bf16 v[12:15], v[146:149], v[214:217], v[12:15]
	v_mfma_f32_16x16x32_bf16 v[8:11], v[154:157], v[214:217], v[8:11]
	v_mfma_f32_16x16x32_bf16 v[60:63], v[150:153], v[192:195], v[60:63]
	v_mfma_f32_16x16x32_bf16 v[56:59], v[168:171], v[192:195], v[56:59]
	v_mfma_f32_16x16x32_bf16 v[44:47], v[150:153], v[202:205], v[44:47]
	v_mfma_f32_16x16x32_bf16 v[40:43], v[168:171], v[202:205], v[40:43]
	v_mfma_f32_16x16x32_bf16 v[28:31], v[150:153], v[210:213], v[28:31]
	v_mfma_f32_16x16x32_bf16 v[24:27], v[168:171], v[210:213], v[24:27]
	v_mfma_f32_16x16x32_bf16 v[12:15], v[150:153], v[218:221], v[12:15]
	v_mfma_f32_16x16x32_bf16 v[8:11], v[168:171], v[218:221], v[8:11]
	v_mfma_f32_16x16x32_bf16 v[52:55], v[172:175], v[188:191], v[52:55]
	v_mfma_f32_16x16x32_bf16 v[48:51], v[180:183], v[188:191], v[48:51]
	v_mfma_f32_16x16x32_bf16 v[36:39], v[172:175], v[198:201], v[36:39]
	v_mfma_f32_16x16x32_bf16 v[32:35], v[180:183], v[198:201], v[32:35]
	v_mfma_f32_16x16x32_bf16 v[20:23], v[172:175], v[206:209], v[20:23]
	v_mfma_f32_16x16x32_bf16 v[16:19], v[180:183], v[206:209], v[16:19]
	v_mfma_f32_16x16x32_bf16 v[4:7], v[172:175], v[214:217], v[4:7]
	v_mfma_f32_16x16x32_bf16 v[0:3], v[180:183], v[214:217], v[0:3]
	v_mfma_f32_16x16x32_bf16 v[52:55], v[176:179], v[192:195], v[52:55]
	v_mfma_f32_16x16x32_bf16 v[48:51], v[184:187], v[192:195], v[48:51]
	v_mfma_f32_16x16x32_bf16 v[36:39], v[176:179], v[202:205], v[36:39]
	v_mfma_f32_16x16x32_bf16 v[32:35], v[184:187], v[202:205], v[32:35]
	v_mfma_f32_16x16x32_bf16 v[20:23], v[176:179], v[210:213], v[20:23]
	v_mfma_f32_16x16x32_bf16 v[16:19], v[184:187], v[210:213], v[16:19]
	v_mfma_f32_16x16x32_bf16 v[4:7], v[176:179], v[218:221], v[4:7]
	v_mfma_f32_16x16x32_bf16 v[0:3], v[184:187], v[218:221], v[0:3]
	s_barrier
	s_add_i32 s84, s84, 2
	s_add_u32 s20, s20, 0x100
	s_addc_u32 s21, s21, 0
	s_add_u32 s80, s80, 0x100
	s_addc_u32 s81, s81, 0
	s_cmp_gt_u32 s84, 13
	s_cbranch_scc0 .LBB0_414
	v_readlane_b32 s101, v249, 49
	s_nop 3
	s_cmp_eq_u32 s101, 0
	s_cbranch_scc1 .Ldw_done_0
	v_cmp_le_u32_e32 vcc, s101, v250
	s_cbranch_vccnz .Ldw_ok_0
	s_add_u32 s98, s28, 0x183500
	s_addc_u32 s99, s29, 0
	v_mov_b32_e32 v251, 0
	s_mov_b32 s100, 0

; #define PG8_STAGE(bufoff, gbase, voff) do { _Pragma("unroll") for (int _i = 0; _i < 2; ++_i) \
;         __builtin_amdgcn_global_load_lds((const unsigned*)((const char*)(gbase) + (voff)[_i]), (PG8_LAS unsigned*)(lds + (bufoff) + ldsw + _i * 8192), 16, 0, 0); } while (0)
; #define PG8_LDA(dst, b, h) do { _Pragma("unroll") for (int m = 0; m < 4; ++m) _Pragma("unroll") for (int k = 0; k < 2; ++k) dst[m][k] = *(const PG8_LAS bf16x8*)(lds + PG8_SA(b, h) + aoff + m * 2048 + k * 1024); } while (0)
; #define PG8_LDB(dst, b, h) do { _Pragma("unroll") for (int n = 0; n < 2; ++n) _Pragma("unroll") for (int k = 0; k < 2; ++k) dst[n][k] = *(const PG8_LAS bf16x8*)(lds + PG8_SB(b, h) + boff + n * 2048 + k * 1024); } while (0)
; #define PG8_WAIT_V(n) asm volatile("s_waitcnt vmcnt(" #n ")" ::: "memory")
; #define PG8_WAIT_L(n) asm volatile("s_waitcnt lgkmcnt(" #n ")" ::: "memory")
; #define PG8_BAR __builtin_amdgcn_s_barrier()
; #define PG8_SCHED __builtin_amdgcn_sched_barrier(0)
; template <class Epi, class Sched, bool ALIGN_EPI = false, bool SP2 = false>
; __device__ __forceinline__ void gemm_phase(PG8_LAS unsigned char* lds, const Gemm g, const Sched& S, const Epi& E) {
;     ...
;         const bool has_next = S.next(ui + 1, nxt);
;         const char* nA = has_next ? (const char*)g.A + (size_t)nxt.pm * tstep : cA; const char* nB = has_next ? (const char*)g.Bt + (size_t)nxt.pn * tstep : cB;
;         for (int t = 0; t < nt; t += 2) {
;             const bool last = (t == nt - 2);
;             const char* a1 = cA + (size_t)(t + 1) * kstep;
;             const char* a2 = last ? nA : cA + (size_t)(t + 2) * kstep; const char* b2 = last ? nB : cB + (size_t)(t + 2) * kstep;
;             const char* a3 = a2 + kstep; const char* b3 = b2 + kstep;
;             if (last && has_next) S.a_ready(nxt);
;             if constexpr (SP2) {
;             PG8_LDB(B0, 0, 0); PG8_LDB(B1, 0, 1); PG8_SCHED; PG8_LDA(At, 0, 0); PG8_STAGE(PG8_SA(1, 1), a1 + hstep, voffA);
;             PG8_WAIT_V(8); PG8_WAIT_L(0); PG8_BAR; PG8_MMA(0, 0, At, B0); PG8_MMA(0, 1, At, B1); PG8_BAR; PG8_SCHED;
;             PG8_LDA(At, 0, 1); PG8_STAGE(PG8_SB(0, 0), b2, voffB); PG8_STAGE(PG8_SB(0, 1), b2 + hstep, voffB); PG8_STAGE(PG8_SA(0, 0), a2, voffA);
;             PG8_WAIT_V(8); PG8_WAIT_L(0); PG8_BAR; PG8_MMA(1, 0, At, B0); PG8_MMA(1, 1, At, B1); PG8_BAR; PG8_SCHED;
.LBB0_809:
	s_ashr_i32 s15, s14, 31
	s_lshl_b64 s[16:17], s[14:15], 19
	s_add_u32 s16, s36, s16
	s_addc_u32 s17, s37, s17
	s_and_b64 s[18:19], s[4:5], exec
	s_cselect_b32 s15, s17, s21
	s_cselect_b32 s65, s16, s20
	s_ashr_i32 s13, s12, 31
	s_lshl_b64 s[18:19], s[12:13], 19
	s_add_u32 s18, s50, s18
	s_addc_u32 s19, s51, s19
	s_and_b64 s[44:45], s[4:5], exec
	s_cselect_b32 s13, s19, s39
	s_cselect_b32 s66, s18, s38
	s_add_u32 s20, s20, 0x40080
	s_addc_u32 s21, s21, 0
	s_add_u32 s67, s38, 0x100
	s_addc_u32 s68, s39, 0
	s_mov_b32 s69, -2
	s_add_u32 s98, s28, 0x183500
	s_addc_u32 s99, s29, 0
	v_mov_b32_e32 v251, 0
	global_load_dword v250, v251, s[98:99] sc1
	ds_read_b128 v[154:157], v150
	ds_read_b128 v[158:161], v150 offset:1024
	ds_read_b128 v[162:165], v150 offset:2048
	ds_read_b128 v[166:169], v150 offset:3072
	ds_read_b128 v[170:173], v151
	ds_read_b128 v[174:177], v151 offset:1024
	ds_read_b128 v[178:181], v151 offset:2048
	ds_read_b128 v[182:185], v151 offset:3072
	s_add_u32 s38, s20, 0xfffc0080
	s_addc_u32 s39, s21, -1
	s_cmp_eq_u32 s69, 12
	s_cselect_b32 s45, s15, s39
	s_cselect_b32 s44, s65, s38
	s_cselect_b32 s39, s13, s68
	s_cselect_b32 s38, s66, s67
	s_add_i32 m0, s35, 0xc000
	ds_read_b128 v[186:189], v152
	ds_read_b128 v[190:193], v152 offset:1024
	ds_read_b128 v[198:201], v152 offset:2048
	ds_read_b128 v[202:205], v152 offset:3072
	ds_read_b128 v[206:209], v152 offset:4096
	ds_read_b128 v[210:213], v152 offset:5120
	ds_read_b128 v[214:217], v152 offset:6144
	ds_read_b128 v[218:221], v152 offset:7168
	global_load_lds_dwordx4 v136, s[20:21]
	s_add_i32 m0, s35, 0xe000
	s_nop 0
	global_load_lds_dwordx4 v138, s[20:21]
	s_waitcnt vmcnt(8)
	s_waitcnt lgkmcnt(0)
	s_barrier
	v_mfma_f32_16x16x32_bf16 v[124:127], v[154:157], v[186:189], 0
	v_mfma_f32_16x16x32_bf16 v[116:119], v[162:165], v[186:189], 0
	v_mfma_f32_16x16x32_bf16 v[108:111], v[154:157], v[198:201], 0
	v_mfma_f32_16x16x32_bf16 v[100:103], v[162:165], v[198:201], 0
	v_mfma_f32_16x16x32_bf16 v[92:95], v[154:157], v[206:209], 0
	v_mfma_f32_16x16x32_bf16 v[84:87], v[162:165], v[206:209], 0
	v_mfma_f32_16x16x32_bf16 v[76:79], v[154:157], v[214:217], 0
	v_mfma_f32_16x16x32_bf16 v[68:71], v[162:165], v[214:217], 0
	v_mfma_f32_16x16x32_bf16 v[124:127], v[158:161], v[190:193], v[124:127]
	v_mfma_f32_16x16x32_bf16 v[116:119], v[166:169], v[190:193], v[116:119]
	v_mfma_f32_16x16x32_bf16 v[108:111], v[158:161], v[202:205], v[108:111]
	v_mfma_f32_16x16x32_bf16 v[100:103], v[166:169], v[202:205], v[100:103]
	v_mfma_f32_16x16x32_bf16 v[92:95], v[158:161], v[210:213], v[92:95]
	v_mfma_f32_16x16x32_bf16 v[84:87], v[166:169], v[210:213], v[84:87]
	v_mfma_f32_16x16x32_bf16 v[76:79], v[158:161], v[218:221], v[76:79]
	v_mfma_f32_16x16x32_bf16 v[68:71], v[166:169], v[218:221], v[68:71]
	v_mfma_f32_16x16x32_bf16 v[120:123], v[170:173], v[186:189], 0
	v_mfma_f32_16x16x32_bf16 v[112:115], v[178:181], v[186:189], 0
	v_mfma_f32_16x16x32_bf16 v[104:107], v[170:173], v[198:201], 0
	v_mfma_f32_16x16x32_bf16 v[96:99], v[178:181], v[198:201], 0
	v_mfma_f32_16x16x32_bf16 v[88:91], v[170:173], v[206:209], 0
	v_mfma_f32_16x16x32_bf16 v[80:83], v[178:181], v[206:209], 0
	v_mfma_f32_16x16x32_bf16 v[72:75], v[170:173], v[214:217], 0
	v_mfma_f32_16x16x32_bf16 v[64:67], v[178:181], v[214:217], 0
	v_mfma_f32_16x16x32_bf16 v[120:123], v[174:177], v[190:193], v[120:123]
	v_mfma_f32_16x16x32_bf16 v[112:115], v[182:185], v[190:193], v[112:115]
	v_mfma_f32_16x16x32_bf16 v[104:107], v[174:177], v[202:205], v[104:107]
	v_mfma_f32_16x16x32_bf16 v[96:99], v[182:185], v[202:205], v[96:99]
	v_mfma_f32_16x16x32_bf16 v[88:91], v[174:177], v[210:213], v[88:91]
	v_mfma_f32_16x16x32_bf16 v[80:83], v[182:185], v[210:213], v[80:83]
	v_mfma_f32_16x16x32_bf16 v[72:75], v[174:177], v[218:221], v[72:75]
	v_mfma_f32_16x16x32_bf16 v[64:67], v[182:185], v[218:221], v[64:67]
	s_barrier
	s_add_i32 s70, s60, s52
	s_add_u32 s98, s38, s8
	s_addc_u32 s99, s39, s9
	s_add_u32 s100, s44, s8
	s_addc_u32 s101, s45, s9
	s_mov_b32 m0, s70
	ds_read_b128 v[186:189], v152 offset:16384
	ds_read_b128 v[190:193], v152 offset:17408
	ds_read_b128 v[198:201], v152 offset:18432
	ds_read_b128 v[202:205], v152 offset:19456
	ds_read_b128 v[206:209], v152 offset:20480
	ds_read_b128 v[210:213], v152 offset:21504
	ds_read_b128 v[214:217], v152 offset:22528
	ds_read_b128 v[218:221], v152 offset:23552
	global_load_lds_dwordx4 v132, s[38:39]
	s_add_i32 m0, s70, 0x2000
	s_add_u32 s70, s38, 0x40000
	s_addc_u32 s71, s39, 0
	s_add_i32 s72, s61, s52
	global_load_lds_dwordx4 v128, s[38:39]
	s_mov_b32 m0, s72
	s_nop 0
	global_load_lds_dwordx4 v132, s[70:71]
	s_add_i32 m0, s72, 0x2000
	s_nop 0
	global_load_lds_dwordx4 v128, s[70:71]
	s_mov_b32 m0, s35
	s_nop 0
	global_load_lds_dwordx4 v134, s[44:45]
	s_mov_b32 m0, s54
	s_nop 0
	global_load_lds_dwordx4 v130, s[44:45]
	s_waitcnt vmcnt(8)
	s_waitcnt lgkmcnt(0)
	s_barrier
; #define PG8_STAGE(bufoff, gbase, voff) do { _Pragma("unroll") for (int _i = 0; _i < 2; ++_i) \
;         __builtin_amdgcn_global_load_lds((const unsigned*)((const char*)(gbase) + (voff)[_i]), (PG8_LAS unsigned*)(lds + (bufoff) + ldsw + _i * 8192), 16, 0, 0); } while (0)
; #define PG8_LDA(dst, b, h) do { _Pragma("unroll") for (int m = 0; m < 4; ++m) _Pragma("unroll") for (int k = 0; k < 2; ++k) dst[m][k] = *(const PG8_LAS bf16x8*)(lds + PG8_SA(b, h) + aoff + m * 2048 + k * 1024); } while (0)
; #define PG8_LDB(dst, b, h) do { _Pragma("unroll") for (int n = 0; n < 2; ++n) _Pragma("unroll") for (int k = 0; k < 2; ++k) dst[n][k] = *(const PG8_LAS bf16x8*)(lds + PG8_SB(b, h) + boff + n * 2048 + k * 1024); } while (0)
; #define PG8_MMA(ai, bj, At, Bt) do { __builtin_amdgcn_s_setprio(1); _Pragma("unroll") for (int m = 0; m < 4; ++m) _Pragma("unroll") for (int n = 0; n < 2; ++n) _Pragma("unroll") for (int k = 0; k < 2; ++k) \
;         acc[ai][bj][m][n] = __builtin_amdgcn_mfma_f32_16x16x32_bf16(Bt[n][k], At[m][k], acc[ai][bj][m][n], 0, 0, 0); __builtin_amdgcn_s_setprio(0); } while (0)
; #define PG8_WAIT_V(n) asm volatile("s_waitcnt vmcnt(" #n ")" ::: "memory")
; #define PG8_WAIT_L(n) asm volatile("s_waitcnt lgkmcnt(" #n ")" ::: "memory")
; #define PG8_BAR __builtin_amdgcn_s_barrier()
; #define PG8_SCHED __builtin_amdgcn_sched_barrier(0)
; template <class Epi, class Sched, bool ALIGN_EPI = false, bool SP2 = false>
; __device__ __forceinline__ void gemm_phase(PG8_LAS unsigned char* lds, const Gemm g, const Sched& S, const Epi& E) {
;     ...
;             PG8_WAIT_V(8); PG8_WAIT_L(0); PG8_BAR; PG8_MMA(1, 0, At, B0); PG8_MMA(1, 1, At, B1); PG8_BAR; PG8_SCHED;
;             PG8_LDB(B0, 1, 0); PG8_LDB(B1, 1, 1); PG8_SCHED; PG8_LDA(At, 1, 0); PG8_STAGE(PG8_SA(0, 1), a2 + hstep, voffA);
;             PG8_WAIT_V(8); PG8_WAIT_L(0); PG8_BAR; PG8_MMA(0, 0, At, B0); PG8_MMA(0, 1, At, B1); PG8_BAR; PG8_SCHED;
	v_mfma_f32_16x16x32_bf16 v[60:63], v[154:157], v[186:189], 0
	v_mfma_f32_16x16x32_bf16 v[52:55], v[162:165], v[186:189], 0
	v_mfma_f32_16x16x32_bf16 v[44:47], v[154:157], v[198:201], 0
	v_mfma_f32_16x16x32_bf16 v[36:39], v[162:165], v[198:201], 0
	v_mfma_f32_16x16x32_bf16 v[28:31], v[154:157], v[206:209], 0
	v_mfma_f32_16x16x32_bf16 v[20:23], v[162:165], v[206:209], 0
	v_mfma_f32_16x16x32_bf16 v[12:15], v[154:157], v[214:217], 0
	v_mfma_f32_16x16x32_bf16 v[4:7], v[162:165], v[214:217], 0
	v_mfma_f32_16x16x32_bf16 v[60:63], v[158:161], v[190:193], v[60:63]
	v_mfma_f32_16x16x32_bf16 v[52:55], v[166:169], v[190:193], v[52:55]
	v_mfma_f32_16x16x32_bf16 v[44:47], v[158:161], v[202:205], v[44:47]
	v_mfma_f32_16x16x32_bf16 v[36:39], v[166:169], v[202:205], v[36:39]
	v_mfma_f32_16x16x32_bf16 v[28:31], v[158:161], v[210:213], v[28:31]
	v_mfma_f32_16x16x32_bf16 v[20:23], v[166:169], v[210:213], v[20:23]
	v_mfma_f32_16x16x32_bf16 v[12:15], v[158:161], v[218:221], v[12:15]
	v_mfma_f32_16x16x32_bf16 v[4:7], v[166:169], v[218:221], v[4:7]
	v_mfma_f32_16x16x32_bf16 v[56:59], v[170:173], v[186:189], 0
	v_mfma_f32_16x16x32_bf16 v[48:51], v[178:181], v[186:189], 0
	v_mfma_f32_16x16x32_bf16 v[40:43], v[170:173], v[198:201], 0
	v_mfma_f32_16x16x32_bf16 v[32:35], v[178:181], v[198:201], 0
	v_mfma_f32_16x16x32_bf16 v[24:27], v[170:173], v[206:209], 0
	v_mfma_f32_16x16x32_bf16 v[16:19], v[178:181], v[206:209], 0
	v_mfma_f32_16x16x32_bf16 v[8:11], v[170:173], v[214:217], 0
	v_mfma_f32_16x16x32_bf16 v[0:3], v[178:181], v[214:217], 0
	v_mfma_f32_16x16x32_bf16 v[56:59], v[174:177], v[190:193], v[56:59]
	v_mfma_f32_16x16x32_bf16 v[48:51], v[182:185], v[190:193], v[48:51]
	v_mfma_f32_16x16x32_bf16 v[40:43], v[174:177], v[202:205], v[40:43]
	v_mfma_f32_16x16x32_bf16 v[32:35], v[182:185], v[202:205], v[32:35]
	v_mfma_f32_16x16x32_bf16 v[24:27], v[174:177], v[210:213], v[24:27]
	v_mfma_f32_16x16x32_bf16 v[16:19], v[182:185], v[210:213], v[16:19]
	v_mfma_f32_16x16x32_bf16 v[8:11], v[174:177], v[218:221], v[8:11]
	v_mfma_f32_16x16x32_bf16 v[0:3], v[182:185], v[218:221], v[0:3]
	s_barrier
	s_add_i32 s70, 0, 0x18000
	v_add_u32_e32 v153, s70, v147
	s_add_i32 s71, 0, 0x1c000
	ds_read_b128 v[154:157], v153
	ds_read_b128 v[158:161], v153 offset:1024
	ds_read_b128 v[162:165], v153 offset:2048
	ds_read_b128 v[166:169], v153 offset:3072
	v_add_u32_e32 v153, s71, v147
	ds_read_b128 v[170:173], v153
	ds_read_b128 v[174:177], v153 offset:1024
	ds_read_b128 v[178:181], v153 offset:2048
	ds_read_b128 v[182:185], v153 offset:3072
	s_add_u32 s44, s44, 0x40000
	s_addc_u32 s45, s45, 0
	s_mov_b32 m0, s55
	ds_read_b128 v[186:189], v152 offset:32768
	ds_read_b128 v[190:193], v152 offset:33792
	ds_read_b128 v[198:201], v152 offset:34816
	ds_read_b128 v[202:205], v152 offset:35840
	ds_read_b128 v[206:209], v152 offset:36864
	ds_read_b128 v[210:213], v152 offset:37888
	ds_read_b128 v[214:217], v152 offset:38912
	ds_read_b128 v[218:221], v152 offset:39936
	global_load_lds_dwordx4 v134, s[44:45]
	s_mov_b32 m0, s56
	s_nop 0
	global_load_lds_dwordx4 v130, s[44:45]
	s_waitcnt vmcnt(8)
	s_waitcnt lgkmcnt(0)
	s_barrier
	v_mfma_f32_16x16x32_bf16 v[124:127], v[154:157], v[186:189], v[124:127]
	v_mfma_f32_16x16x32_bf16 v[116:119], v[162:165], v[186:189], v[116:119]
	v_mfma_f32_16x16x32_bf16 v[108:111], v[154:157], v[198:201], v[108:111]
	v_mfma_f32_16x16x32_bf16 v[100:103], v[162:165], v[198:201], v[100:103]
	v_mfma_f32_16x16x32_bf16 v[92:95], v[154:157], v[206:209], v[92:95]
	v_mfma_f32_16x16x32_bf16 v[84:87], v[162:165], v[206:209], v[84:87]
	v_mfma_f32_16x16x32_bf16 v[76:79], v[154:157], v[214:217], v[76:79]
	v_mfma_f32_16x16x32_bf16 v[68:71], v[162:165], v[214:217], v[68:71]
	v_mfma_f32_16x16x32_bf16 v[124:127], v[158:161], v[190:193], v[124:127]
	v_mfma_f32_16x16x32_bf16 v[116:119], v[166:169], v[190:193], v[116:119]
	v_mfma_f32_16x16x32_bf16 v[108:111], v[158:161], v[202:205], v[108:111]
	v_mfma_f32_16x16x32_bf16 v[100:103], v[166:169], v[202:205], v[100:103]
	v_mfma_f32_16x16x32_bf16 v[92:95], v[158:161], v[210:213], v[92:95]
	v_mfma_f32_16x16x32_bf16 v[84:87], v[166:169], v[210:213], v[84:87]
	v_mfma_f32_16x16x32_bf16 v[76:79], v[158:161], v[218:221], v[76:79]
	v_mfma_f32_16x16x32_bf16 v[68:71], v[166:169], v[218:221], v[68:71]
	v_mfma_f32_16x16x32_bf16 v[120:123], v[170:173], v[186:189], v[120:123]
	v_mfma_f32_16x16x32_bf16 v[112:115], v[178:181], v[186:189], v[112:115]
	v_mfma_f32_16x16x32_bf16 v[104:107], v[170:173], v[198:201], v[104:107]
	v_mfma_f32_16x16x32_bf16 v[96:99], v[178:181], v[198:201], v[96:99]
	v_mfma_f32_16x16x32_bf16 v[88:91], v[170:173], v[206:209], v[88:91]
	v_mfma_f32_16x16x32_bf16 v[80:83], v[178:181], v[206:209], v[80:83]
	v_mfma_f32_16x16x32_bf16 v[72:75], v[170:173], v[214:217], v[72:75]
	v_mfma_f32_16x16x32_bf16 v[64:67], v[178:181], v[214:217], v[64:67]
	v_mfma_f32_16x16x32_bf16 v[120:123], v[174:177], v[190:193], v[120:123]
	v_mfma_f32_16x16x32_bf16 v[112:115], v[182:185], v[190:193], v[112:115]
	v_mfma_f32_16x16x32_bf16 v[104:107], v[174:177], v[202:205], v[104:107]
	v_mfma_f32_16x16x32_bf16 v[96:99], v[182:185], v[202:205], v[96:99]
	v_mfma_f32_16x16x32_bf16 v[88:91], v[174:177], v[210:213], v[88:91]
	v_mfma_f32_16x16x32_bf16 v[80:83], v[182:185], v[210:213], v[80:83]
	v_mfma_f32_16x16x32_bf16 v[72:75], v[174:177], v[218:221], v[72:75]
	v_mfma_f32_16x16x32_bf16 v[64:67], v[182:185], v[218:221], v[64:67]
	s_barrier
; #define PG8_STAGE(bufoff, gbase, voff) do { _Pragma("unroll") for (int _i = 0; _i < 2; ++_i) \
;         __builtin_amdgcn_global_load_lds((const unsigned*)((const char*)(gbase) + (voff)[_i]), (PG8_LAS unsigned*)(lds + (bufoff) + ldsw + _i * 8192), 16, 0, 0); } while (0)
; #define PG8_LDA(dst, b, h) do { _Pragma("unroll") for (int m = 0; m < 4; ++m) _Pragma("unroll") for (int k = 0; k < 2; ++k) dst[m][k] = *(const PG8_LAS bf16x8*)(lds + PG8_SA(b, h) + aoff + m * 2048 + k * 1024); } while (0)
; #define PG8_LDB(dst, b, h) do { _Pragma("unroll") for (int n = 0; n < 2; ++n) _Pragma("unroll") for (int k = 0; k < 2; ++k) dst[n][k] = *(const PG8_LAS bf16x8*)(lds + PG8_SB(b, h) + boff + n * 2048 + k * 1024); } while (0)
; #define PG8_MMA(ai, bj, At, Bt) do { __builtin_amdgcn_s_setprio(1); _Pragma("unroll") for (int m = 0; m < 4; ++m) _Pragma("unroll") for (int n = 0; n < 2; ++n) _Pragma("unroll") for (int k = 0; k < 2; ++k) \
;         acc[ai][bj][m][n] = __builtin_amdgcn_mfma_f32_16x16x32_bf16(Bt[n][k], At[m][k], acc[ai][bj][m][n], 0, 0, 0); __builtin_amdgcn_s_setprio(0); } while (0)
; #define PG8_WAIT_V(n) asm volatile("s_waitcnt vmcnt(" #n ")" ::: "memory")
; #define PG8_WAIT_L(n) asm volatile("s_waitcnt lgkmcnt(" #n ")" ::: "memory")
; #define PG8_BAR __builtin_amdgcn_s_barrier()
; #define PG8_SCHED __builtin_amdgcn_sched_barrier(0)
; template <class Epi, class Sched, bool ALIGN_EPI = false, bool SP2 = false>
; __device__ __forceinline__ void gemm_phase(PG8_LAS unsigned char* lds, const Gemm g, const Sched& S, const Epi& E) {
;     ...
;             PG8_LDB(B0, 0, 0); PG8_LDB(B1, 0, 1); PG8_SCHED; PG8_LDA(At, 0, 0); PG8_STAGE(PG8_SA(1, 1), a1 + hstep, voffA);
;             PG8_WAIT_V(8); PG8_WAIT_L(0); PG8_BAR; PG8_MMA(0, 0, At, B0); PG8_MMA(0, 1, At, B1); PG8_BAR; PG8_SCHED;
;     ...
;             PG8_LDA(At, 1, 1); PG8_STAGE(PG8_SB(1, 0), b3, voffB); PG8_STAGE(PG8_SB(1, 1), b3 + hstep, voffB); PG8_STAGE(PG8_SA(1, 0), a3, voffA);
;             PG8_WAIT_V(8); PG8_WAIT_L(0); PG8_BAR; PG8_MMA(1, 0, At, B0); PG8_MMA(1, 1, At, B1); PG8_BAR; PG8_SCHED;
	s_add_i32 s44, s70, s52
	s_mov_b32 m0, s44
	ds_read_b128 v[186:189], v152 offset:49152
	ds_read_b128 v[190:193], v152 offset:50176
	ds_read_b128 v[198:201], v152 offset:51200
	ds_read_b128 v[202:205], v152 offset:52224
	ds_read_b128 v[206:209], v152 offset:53248
	ds_read_b128 v[210:213], v152 offset:54272
	ds_read_b128 v[214:217], v152 offset:55296
	ds_read_b128 v[218:221], v152 offset:56320
	global_load_lds_dwordx4 v132, s[98:99]
	s_add_i32 m0, s44, 0x2000
	s_add_u32 s38, s38, 0x40080
	s_addc_u32 s39, s39, 0
	s_add_i32 s44, s71, s52
	global_load_lds_dwordx4 v128, s[98:99]
	s_mov_b32 m0, s44
	s_nop 0
	global_load_lds_dwordx4 v132, s[38:39]
	s_add_i32 m0, s44, 0x2000
	s_nop 0
	global_load_lds_dwordx4 v128, s[38:39]
	s_mov_b32 m0, s58
	s_nop 0
	global_load_lds_dwordx4 v134, s[100:101]
	s_mov_b32 m0, s59
	s_nop 0
	global_load_lds_dwordx4 v130, s[100:101]
	s_waitcnt vmcnt(8)
	s_waitcnt lgkmcnt(0)
	s_barrier
	v_mfma_f32_16x16x32_bf16 v[60:63], v[154:157], v[186:189], v[60:63]
	v_mfma_f32_16x16x32_bf16 v[52:55], v[162:165], v[186:189], v[52:55]
	v_mfma_f32_16x16x32_bf16 v[44:47], v[154:157], v[198:201], v[44:47]
	v_mfma_f32_16x16x32_bf16 v[36:39], v[162:165], v[198:201], v[36:39]
	v_mfma_f32_16x16x32_bf16 v[28:31], v[154:157], v[206:209], v[28:31]
	v_mfma_f32_16x16x32_bf16 v[20:23], v[162:165], v[206:209], v[20:23]
	v_mfma_f32_16x16x32_bf16 v[12:15], v[154:157], v[214:217], v[12:15]
	v_mfma_f32_16x16x32_bf16 v[4:7], v[162:165], v[214:217], v[4:7]
	v_mfma_f32_16x16x32_bf16 v[60:63], v[158:161], v[190:193], v[60:63]
	v_mfma_f32_16x16x32_bf16 v[52:55], v[166:169], v[190:193], v[52:55]
	v_mfma_f32_16x16x32_bf16 v[44:47], v[158:161], v[202:205], v[44:47]
	v_mfma_f32_16x16x32_bf16 v[36:39], v[166:169], v[202:205], v[36:39]
	v_mfma_f32_16x16x32_bf16 v[28:31], v[158:161], v[210:213], v[28:31]
	v_mfma_f32_16x16x32_bf16 v[20:23], v[166:169], v[210:213], v[20:23]
	v_mfma_f32_16x16x32_bf16 v[12:15], v[158:161], v[218:221], v[12:15]
	v_mfma_f32_16x16x32_bf16 v[4:7], v[166:169], v[218:221], v[4:7]
	v_mfma_f32_16x16x32_bf16 v[56:59], v[170:173], v[186:189], v[56:59]
	v_mfma_f32_16x16x32_bf16 v[48:51], v[178:181], v[186:189], v[48:51]
	v_mfma_f32_16x16x32_bf16 v[40:43], v[170:173], v[198:201], v[40:43]
	v_mfma_f32_16x16x32_bf16 v[32:35], v[178:181], v[198:201], v[32:35]
	v_mfma_f32_16x16x32_bf16 v[24:27], v[170:173], v[206:209], v[24:27]
	v_mfma_f32_16x16x32_bf16 v[16:19], v[178:181], v[206:209], v[16:19]
	v_mfma_f32_16x16x32_bf16 v[8:11], v[170:173], v[214:217], v[8:11]
	v_mfma_f32_16x16x32_bf16 v[0:3], v[178:181], v[214:217], v[0:3]
	v_mfma_f32_16x16x32_bf16 v[56:59], v[174:177], v[190:193], v[56:59]
	v_mfma_f32_16x16x32_bf16 v[48:51], v[182:185], v[190:193], v[48:51]
	v_mfma_f32_16x16x32_bf16 v[40:43], v[174:177], v[202:205], v[40:43]
	v_mfma_f32_16x16x32_bf16 v[32:35], v[182:185], v[202:205], v[32:35]
	v_mfma_f32_16x16x32_bf16 v[24:27], v[174:177], v[210:213], v[24:27]
	v_mfma_f32_16x16x32_bf16 v[16:19], v[182:185], v[210:213], v[16:19]
	v_mfma_f32_16x16x32_bf16 v[8:11], v[174:177], v[218:221], v[8:11]
	v_mfma_f32_16x16x32_bf16 v[0:3], v[182:185], v[218:221], v[0:3]
	s_barrier
	s_add_i32 s69, s69, 2
	s_add_u32 s20, s20, 0x100
	s_addc_u32 s21, s21, 0
	s_add_u32 s67, s67, 0x100
	s_addc_u32 s68, s68, 0
	s_cmp_gt_u32 s69, 13
.LBB0_810:
	ds_read_b128 v[154:157], v150
	ds_read_b128 v[158:161], v150 offset:1024
	ds_read_b128 v[162:165], v150 offset:2048
	ds_read_b128 v[166:169], v150 offset:3072
	ds_read_b128 v[170:173], v151
	ds_read_b128 v[174:177], v151 offset:1024
	ds_read_b128 v[178:181], v151 offset:2048
	ds_read_b128 v[182:185], v151 offset:3072
	s_add_u32 s38, s20, 0xfffc0080
	s_addc_u32 s39, s21, -1
	s_cmp_eq_u32 s69, 12
	s_cselect_b32 s45, s15, s39
	s_cselect_b32 s44, s65, s38
	s_cselect_b32 s39, s13, s68
	s_cselect_b32 s38, s66, s67
	s_add_i32 m0, s35, 0xc000
	ds_read_b128 v[186:189], v152
	ds_read_b128 v[190:193], v152 offset:1024
	ds_read_b128 v[198:201], v152 offset:2048
	ds_read_b128 v[202:205], v152 offset:3072
	ds_read_b128 v[206:209], v152 offset:4096
	ds_read_b128 v[210:213], v152 offset:5120
	ds_read_b128 v[214:217], v152 offset:6144
	ds_read_b128 v[218:221], v152 offset:7168
	global_load_lds_dwordx4 v136, s[20:21]
	s_add_i32 m0, s35, 0xe000
	s_nop 0
	global_load_lds_dwordx4 v138, s[20:21]
	s_waitcnt vmcnt(8)
	s_waitcnt lgkmcnt(0)
	s_barrier
	v_mfma_f32_16x16x32_bf16 v[124:127], v[154:157], v[186:189], v[124:127]
	v_mfma_f32_16x16x32_bf16 v[116:119], v[162:165], v[186:189], v[116:119]
	v_mfma_f32_16x16x32_bf16 v[108:111], v[154:157], v[198:201], v[108:111]
	v_mfma_f32_16x16x32_bf16 v[100:103], v[162:165], v[198:201], v[100:103]
	v_mfma_f32_16x16x32_bf16 v[92:95], v[154:157], v[206:209], v[92:95]
	v_mfma_f32_16x16x32_bf16 v[84:87], v[162:165], v[206:209], v[84:87]
	v_mfma_f32_16x16x32_bf16 v[76:79], v[154:157], v[214:217], v[76:79]
	v_mfma_f32_16x16x32_bf16 v[68:71], v[162:165], v[214:217], v[68:71]
	v_mfma_f32_16x16x32_bf16 v[124:127], v[158:161], v[190:193], v[124:127]
	v_mfma_f32_16x16x32_bf16 v[116:119], v[166:169], v[190:193], v[116:119]
	v_mfma_f32_16x16x32_bf16 v[108:111], v[158:161], v[202:205], v[108:111]
	v_mfma_f32_16x16x32_bf16 v[100:103], v[166:169], v[202:205], v[100:103]
	v_mfma_f32_16x16x32_bf16 v[92:95], v[158:161], v[210:213], v[92:95]
	v_mfma_f32_16x16x32_bf16 v[84:87], v[166:169], v[210:213], v[84:87]
	v_mfma_f32_16x16x32_bf16 v[76:79], v[158:161], v[218:221], v[76:79]
	v_mfma_f32_16x16x32_bf16 v[68:71], v[166:169], v[218:221], v[68:71]
	v_mfma_f32_16x16x32_bf16 v[120:123], v[170:173], v[186:189], v[120:123]
	v_mfma_f32_16x16x32_bf16 v[112:115], v[178:181], v[186:189], v[112:115]
	v_mfma_f32_16x16x32_bf16 v[104:107], v[170:173], v[198:201], v[104:107]
	v_mfma_f32_16x16x32_bf16 v[96:99], v[178:181], v[198:201], v[96:99]
	v_mfma_f32_16x16x32_bf16 v[88:91], v[170:173], v[206:209], v[88:91]
	v_mfma_f32_16x16x32_bf16 v[80:83], v[178:181], v[206:209], v[80:83]
	v_mfma_f32_16x16x32_bf16 v[72:75], v[170:173], v[214:217], v[72:75]
	v_mfma_f32_16x16x32_bf16 v[64:67], v[178:181], v[214:217], v[64:67]
	v_mfma_f32_16x16x32_bf16 v[120:123], v[174:177], v[190:193], v[120:123]
	v_mfma_f32_16x16x32_bf16 v[112:115], v[182:185], v[190:193], v[112:115]
	v_mfma_f32_16x16x32_bf16 v[104:107], v[174:177], v[202:205], v[104:107]
	v_mfma_f32_16x16x32_bf16 v[96:99], v[182:185], v[202:205], v[96:99]
	v_mfma_f32_16x16x32_bf16 v[88:91], v[174:177], v[210:213], v[88:91]
	v_mfma_f32_16x16x32_bf16 v[80:83], v[182:185], v[210:213], v[80:83]
	v_mfma_f32_16x16x32_bf16 v[72:75], v[174:177], v[218:221], v[72:75]
	v_mfma_f32_16x16x32_bf16 v[64:67], v[182:185], v[218:221], v[64:67]
	s_barrier
; #define PG8_STAGE(bufoff, gbase, voff) do { _Pragma("unroll") for (int _i = 0; _i < 2; ++_i) \
;         __builtin_amdgcn_global_load_lds((const unsigned*)((const char*)(gbase) + (voff)[_i]), (PG8_LAS unsigned*)(lds + (bufoff) + ldsw + _i * 8192), 16, 0, 0); } while (0)
; #define PG8_LDA(dst, b, h) do { _Pragma("unroll") for (int m = 0; m < 4; ++m) _Pragma("unroll") for (int k = 0; k < 2; ++k) dst[m][k] = *(const PG8_LAS bf16x8*)(lds + PG8_SA(b, h) + aoff + m * 2048 + k * 1024); } while (0)
; #define PG8_LDB(dst, b, h) do { _Pragma("unroll") for (int n = 0; n < 2; ++n) _Pragma("unroll") for (int k = 0; k < 2; ++k) dst[n][k] = *(const PG8_LAS bf16x8*)(lds + PG8_SB(b, h) + boff + n * 2048 + k * 1024); } while (0)
; #define PG8_MMA(ai, bj, At, Bt) do { __builtin_amdgcn_s_setprio(1); _Pragma("unroll") for (int m = 0; m < 4; ++m) _Pragma("unroll") for (int n = 0; n < 2; ++n) _Pragma("unroll") for (int k = 0; k < 2; ++k) \
;         acc[ai][bj][m][n] = __builtin_amdgcn_mfma_f32_16x16x32_bf16(Bt[n][k], At[m][k], acc[ai][bj][m][n], 0, 0, 0); __builtin_amdgcn_s_setprio(0); } while (0)
; #define PG8_WAIT_V(n) asm volatile("s_waitcnt vmcnt(" #n ")" ::: "memory")
; #define PG8_WAIT_L(n) asm volatile("s_waitcnt lgkmcnt(" #n ")" ::: "memory")
; #define PG8_BAR __builtin_amdgcn_s_barrier()
; #define PG8_SCHED __builtin_amdgcn_sched_barrier(0)
; template <class Epi, class Sched, bool ALIGN_EPI = false, bool SP2 = false>
; __device__ __forceinline__ void gemm_phase(PG8_LAS unsigned char* lds, const Gemm g, const Sched& S, const Epi& E) {
;     ...
;             PG8_LDA(At, 0, 1); PG8_STAGE(PG8_SB(0, 0), b2, voffB); PG8_STAGE(PG8_SB(0, 1), b2 + hstep, voffB); PG8_STAGE(PG8_SA(0, 0), a2, voffA);
;             PG8_WAIT_V(8); PG8_WAIT_L(0); PG8_BAR; PG8_MMA(1, 0, At, B0); PG8_MMA(1, 1, At, B1); PG8_BAR; PG8_SCHED;
;             PG8_LDB(B0, 1, 0); PG8_LDB(B1, 1, 1); PG8_SCHED; PG8_LDA(At, 1, 0); PG8_STAGE(PG8_SA(0, 1), a2 + hstep, voffA);
;             PG8_WAIT_V(8); PG8_WAIT_L(0); PG8_BAR; PG8_MMA(0, 0, At, B0); PG8_MMA(0, 1, At, B1); PG8_BAR; PG8_SCHED;
	s_add_i32 s70, s60, s52
	s_add_u32 s98, s38, s8
	s_addc_u32 s99, s39, s9
	s_add_u32 s100, s44, s8
	s_addc_u32 s101, s45, s9
	s_mov_b32 m0, s70
	ds_read_b128 v[186:189], v152 offset:16384
	ds_read_b128 v[190:193], v152 offset:17408
	ds_read_b128 v[198:201], v152 offset:18432
	ds_read_b128 v[202:205], v152 offset:19456
	ds_read_b128 v[206:209], v152 offset:20480
	ds_read_b128 v[210:213], v152 offset:21504
	ds_read_b128 v[214:217], v152 offset:22528
	ds_read_b128 v[218:221], v152 offset:23552
	global_load_lds_dwordx4 v132, s[38:39]
	s_add_i32 m0, s70, 0x2000
	s_add_u32 s70, s38, 0x40000
	s_addc_u32 s71, s39, 0
	s_add_i32 s72, s61, s52
	global_load_lds_dwordx4 v128, s[38:39]
	s_mov_b32 m0, s72
	s_nop 0
	global_load_lds_dwordx4 v132, s[70:71]
	s_add_i32 m0, s72, 0x2000
	s_nop 0
	global_load_lds_dwordx4 v128, s[70:71]
	s_mov_b32 m0, s35
	s_nop 0
	global_load_lds_dwordx4 v134, s[44:45]
	s_mov_b32 m0, s54
	s_nop 0
	global_load_lds_dwordx4 v130, s[44:45]
	s_waitcnt vmcnt(8)
	s_waitcnt lgkmcnt(0)
	s_barrier
	v_mfma_f32_16x16x32_bf16 v[60:63], v[154:157], v[186:189], v[60:63]
	v_mfma_f32_16x16x32_bf16 v[52:55], v[162:165], v[186:189], v[52:55]
	v_mfma_f32_16x16x32_bf16 v[44:47], v[154:157], v[198:201], v[44:47]
	v_mfma_f32_16x16x32_bf16 v[36:39], v[162:165], v[198:201], v[36:39]
	v_mfma_f32_16x16x32_bf16 v[28:31], v[154:157], v[206:209], v[28:31]
	v_mfma_f32_16x16x32_bf16 v[20:23], v[162:165], v[206:209], v[20:23]
	v_mfma_f32_16x16x32_bf16 v[12:15], v[154:157], v[214:217], v[12:15]
	v_mfma_f32_16x16x32_bf16 v[4:7], v[162:165], v[214:217], v[4:7]
	v_mfma_f32_16x16x32_bf16 v[60:63], v[158:161], v[190:193], v[60:63]
	v_mfma_f32_16x16x32_bf16 v[52:55], v[166:169], v[190:193], v[52:55]
	v_mfma_f32_16x16x32_bf16 v[44:47], v[158:161], v[202:205], v[44:47]
	v_mfma_f32_16x16x32_bf16 v[36:39], v[166:169], v[202:205], v[36:39]
	v_mfma_f32_16x16x32_bf16 v[28:31], v[158:161], v[210:213], v[28:31]
	v_mfma_f32_16x16x32_bf16 v[20:23], v[166:169], v[210:213], v[20:23]
	v_mfma_f32_16x16x32_bf16 v[12:15], v[158:161], v[218:221], v[12:15]
	v_mfma_f32_16x16x32_bf16 v[4:7], v[166:169], v[218:221], v[4:7]
	v_mfma_f32_16x16x32_bf16 v[56:59], v[170:173], v[186:189], v[56:59]
	v_mfma_f32_16x16x32_bf16 v[48:51], v[178:181], v[186:189], v[48:51]
	v_mfma_f32_16x16x32_bf16 v[40:43], v[170:173], v[198:201], v[40:43]
	v_mfma_f32_16x16x32_bf16 v[32:35], v[178:181], v[198:201], v[32:35]
	v_mfma_f32_16x16x32_bf16 v[24:27], v[170:173], v[206:209], v[24:27]
	v_mfma_f32_16x16x32_bf16 v[16:19], v[178:181], v[206:209], v[16:19]
	v_mfma_f32_16x16x32_bf16 v[8:11], v[170:173], v[214:217], v[8:11]
	v_mfma_f32_16x16x32_bf16 v[0:3], v[178:181], v[214:217], v[0:3]
	v_mfma_f32_16x16x32_bf16 v[56:59], v[174:177], v[190:193], v[56:59]
	v_mfma_f32_16x16x32_bf16 v[48:51], v[182:185], v[190:193], v[48:51]
	v_mfma_f32_16x16x32_bf16 v[40:43], v[174:177], v[202:205], v[40:43]
	v_mfma_f32_16x16x32_bf16 v[32:35], v[182:185], v[202:205], v[32:35]
	v_mfma_f32_16x16x32_bf16 v[24:27], v[174:177], v[210:213], v[24:27]
	v_mfma_f32_16x16x32_bf16 v[16:19], v[182:185], v[210:213], v[16:19]
	v_mfma_f32_16x16x32_bf16 v[8:11], v[174:177], v[218:221], v[8:11]
	v_mfma_f32_16x16x32_bf16 v[0:3], v[182:185], v[218:221], v[0:3]
	s_barrier
	s_add_i32 s70, 0, 0x18000
	v_add_u32_e32 v153, s70, v147
	s_add_i32 s71, 0, 0x1c000
	ds_read_b128 v[154:157], v153
	ds_read_b128 v[158:161], v153 offset:1024
	ds_read_b128 v[162:165], v153 offset:2048
	ds_read_b128 v[166:169], v153 offset:3072
	v_add_u32_e32 v153, s71, v147
	ds_read_b128 v[170:173], v153
	ds_read_b128 v[174:177], v153 offset:1024
	ds_read_b128 v[178:181], v153 offset:2048
	ds_read_b128 v[182:185], v153 offset:3072
	s_add_u32 s44, s44, 0x40000
	s_addc_u32 s45, s45, 0
	s_mov_b32 m0, s55
	ds_read_b128 v[186:189], v152 offset:32768
	ds_read_b128 v[190:193], v152 offset:33792
	ds_read_b128 v[198:201], v152 offset:34816
	ds_read_b128 v[202:205], v152 offset:35840
	ds_read_b128 v[206:209], v152 offset:36864
	ds_read_b128 v[210:213], v152 offset:37888
	ds_read_b128 v[214:217], v152 offset:38912
	ds_read_b128 v[218:221], v152 offset:39936
	global_load_lds_dwordx4 v134, s[44:45]
	s_mov_b32 m0, s56
	s_nop 0
	global_load_lds_dwordx4 v130, s[44:45]
	s_waitcnt vmcnt(8)
	s_waitcnt lgkmcnt(0)
	s_barrier
; #define PG8_STAGE(bufoff, gbase, voff) do { _Pragma("unroll") for (int _i = 0; _i < 2; ++_i) \
;         __builtin_amdgcn_global_load_lds((const unsigned*)((const char*)(gbase) + (voff)[_i]), (PG8_LAS unsigned*)(lds + (bufoff) + ldsw + _i * 8192), 16, 0, 0); } while (0)
; #define PG8_LDA(dst, b, h) do { _Pragma("unroll") for (int m = 0; m < 4; ++m) _Pragma("unroll") for (int k = 0; k < 2; ++k) dst[m][k] = *(const PG8_LAS bf16x8*)(lds + PG8_SA(b, h) + aoff + m * 2048 + k * 1024); } while (0)
; #define PG8_MMA(ai, bj, At, Bt) do { __builtin_amdgcn_s_setprio(1); _Pragma("unroll") for (int m = 0; m < 4; ++m) _Pragma("unroll") for (int n = 0; n < 2; ++n) _Pragma("unroll") for (int k = 0; k < 2; ++k) \
;         acc[ai][bj][m][n] = __builtin_amdgcn_mfma_f32_16x16x32_bf16(Bt[n][k], At[m][k], acc[ai][bj][m][n], 0, 0, 0); __builtin_amdgcn_s_setprio(0); } while (0)
; #define PG8_WAIT_V(n) asm volatile("s_waitcnt vmcnt(" #n ")" ::: "memory")
; #define PG8_WAIT_L(n) asm volatile("s_waitcnt lgkmcnt(" #n ")" ::: "memory")
; #define PG8_BAR __builtin_amdgcn_s_barrier()
; #define PG8_SCHED __builtin_amdgcn_sched_barrier(0)
; template <class Epi, class Sched, bool ALIGN_EPI = false, bool SP2 = false>
; __device__ __forceinline__ void gemm_phase(PG8_LAS unsigned char* lds, const Gemm g, const Sched& S, const Epi& E) {
;     ...
;             PG8_WAIT_V(8); PG8_WAIT_L(0); PG8_BAR; PG8_MMA(0, 0, At, B0); PG8_MMA(0, 1, At, B1); PG8_BAR; PG8_SCHED;
;             PG8_LDA(At, 1, 1); PG8_STAGE(PG8_SB(1, 0), b3, voffB); PG8_STAGE(PG8_SB(1, 1), b3 + hstep, voffB); PG8_STAGE(PG8_SA(1, 0), a3, voffA);
;             PG8_WAIT_V(8); PG8_WAIT_L(0); PG8_BAR; PG8_MMA(1, 0, At, B0); PG8_MMA(1, 1, At, B1); PG8_BAR; PG8_SCHED;
;     ...
;         if constexpr (ALIGN_EPI) { if (wr == 0) PG8_BAR; }
;         if constexpr (!Epi::AFTER_DRAIN) { E(acc, cur, wr, wc, fr, fq); S.done(cur); }
	v_mfma_f32_16x16x32_bf16 v[124:127], v[154:157], v[186:189], v[124:127]
	v_mfma_f32_16x16x32_bf16 v[116:119], v[162:165], v[186:189], v[116:119]
	v_mfma_f32_16x16x32_bf16 v[108:111], v[154:157], v[198:201], v[108:111]
	v_mfma_f32_16x16x32_bf16 v[100:103], v[162:165], v[198:201], v[100:103]
	v_mfma_f32_16x16x32_bf16 v[92:95], v[154:157], v[206:209], v[92:95]
	v_mfma_f32_16x16x32_bf16 v[84:87], v[162:165], v[206:209], v[84:87]
	v_mfma_f32_16x16x32_bf16 v[76:79], v[154:157], v[214:217], v[76:79]
	v_mfma_f32_16x16x32_bf16 v[68:71], v[162:165], v[214:217], v[68:71]
	v_mfma_f32_16x16x32_bf16 v[124:127], v[158:161], v[190:193], v[124:127]
	v_mfma_f32_16x16x32_bf16 v[116:119], v[166:169], v[190:193], v[116:119]
	v_mfma_f32_16x16x32_bf16 v[108:111], v[158:161], v[202:205], v[108:111]
	v_mfma_f32_16x16x32_bf16 v[100:103], v[166:169], v[202:205], v[100:103]
	v_mfma_f32_16x16x32_bf16 v[92:95], v[158:161], v[210:213], v[92:95]
	v_mfma_f32_16x16x32_bf16 v[84:87], v[166:169], v[210:213], v[84:87]
	v_mfma_f32_16x16x32_bf16 v[76:79], v[158:161], v[218:221], v[76:79]
	v_mfma_f32_16x16x32_bf16 v[68:71], v[166:169], v[218:221], v[68:71]
	v_mfma_f32_16x16x32_bf16 v[120:123], v[170:173], v[186:189], v[120:123]
	v_mfma_f32_16x16x32_bf16 v[112:115], v[178:181], v[186:189], v[112:115]
	v_mfma_f32_16x16x32_bf16 v[104:107], v[170:173], v[198:201], v[104:107]
	v_mfma_f32_16x16x32_bf16 v[96:99], v[178:181], v[198:201], v[96:99]
	v_mfma_f32_16x16x32_bf16 v[88:91], v[170:173], v[206:209], v[88:91]
	v_mfma_f32_16x16x32_bf16 v[80:83], v[178:181], v[206:209], v[80:83]
	v_mfma_f32_16x16x32_bf16 v[72:75], v[170:173], v[214:217], v[72:75]
	v_mfma_f32_16x16x32_bf16 v[64:67], v[178:181], v[214:217], v[64:67]
	v_mfma_f32_16x16x32_bf16 v[120:123], v[174:177], v[190:193], v[120:123]
	v_mfma_f32_16x16x32_bf16 v[112:115], v[182:185], v[190:193], v[112:115]
	v_mfma_f32_16x16x32_bf16 v[104:107], v[174:177], v[202:205], v[104:107]
	v_mfma_f32_16x16x32_bf16 v[96:99], v[182:185], v[202:205], v[96:99]
	v_mfma_f32_16x16x32_bf16 v[88:91], v[174:177], v[210:213], v[88:91]
	v_mfma_f32_16x16x32_bf16 v[80:83], v[182:185], v[210:213], v[80:83]
	v_mfma_f32_16x16x32_bf16 v[72:75], v[174:177], v[218:221], v[72:75]
	v_mfma_f32_16x16x32_bf16 v[64:67], v[182:185], v[218:221], v[64:67]
	s_barrier
	s_add_i32 s44, s70, s52
	s_mov_b32 m0, s44
	ds_read_b128 v[186:189], v152 offset:49152
	ds_read_b128 v[190:193], v152 offset:50176
	ds_read_b128 v[198:201], v152 offset:51200
	ds_read_b128 v[202:205], v152 offset:52224
	ds_read_b128 v[206:209], v152 offset:53248
	ds_read_b128 v[210:213], v152 offset:54272
	ds_read_b128 v[214:217], v152 offset:55296
	ds_read_b128 v[218:221], v152 offset:56320
	global_load_lds_dwordx4 v132, s[98:99]
	s_add_i32 m0, s44, 0x2000
	s_add_u32 s38, s38, 0x40080
	s_addc_u32 s39, s39, 0
	s_add_i32 s44, s71, s52
	global_load_lds_dwordx4 v128, s[98:99]
	s_mov_b32 m0, s44
	s_nop 0
	global_load_lds_dwordx4 v132, s[38:39]
	s_add_i32 m0, s44, 0x2000
	s_nop 0
	global_load_lds_dwordx4 v128, s[38:39]
	s_mov_b32 m0, s58
	s_nop 0
	global_load_lds_dwordx4 v134, s[100:101]
	s_mov_b32 m0, s59
	s_nop 0
	global_load_lds_dwordx4 v130, s[100:101]
	s_waitcnt vmcnt(8)
	s_waitcnt lgkmcnt(0)
	s_barrier
	v_mfma_f32_16x16x32_bf16 v[60:63], v[154:157], v[186:189], v[60:63]
	v_mfma_f32_16x16x32_bf16 v[52:55], v[162:165], v[186:189], v[52:55]
	v_mfma_f32_16x16x32_bf16 v[44:47], v[154:157], v[198:201], v[44:47]
	v_mfma_f32_16x16x32_bf16 v[36:39], v[162:165], v[198:201], v[36:39]
	v_mfma_f32_16x16x32_bf16 v[28:31], v[154:157], v[206:209], v[28:31]
	v_mfma_f32_16x16x32_bf16 v[20:23], v[162:165], v[206:209], v[20:23]
	v_mfma_f32_16x16x32_bf16 v[12:15], v[154:157], v[214:217], v[12:15]
	v_mfma_f32_16x16x32_bf16 v[4:7], v[162:165], v[214:217], v[4:7]
	v_mfma_f32_16x16x32_bf16 v[60:63], v[158:161], v[190:193], v[60:63]
	v_mfma_f32_16x16x32_bf16 v[52:55], v[166:169], v[190:193], v[52:55]
	v_mfma_f32_16x16x32_bf16 v[44:47], v[158:161], v[202:205], v[44:47]
	v_mfma_f32_16x16x32_bf16 v[36:39], v[166:169], v[202:205], v[36:39]
	v_mfma_f32_16x16x32_bf16 v[28:31], v[158:161], v[210:213], v[28:31]
	v_mfma_f32_16x16x32_bf16 v[20:23], v[166:169], v[210:213], v[20:23]
	v_mfma_f32_16x16x32_bf16 v[12:15], v[158:161], v[218:221], v[12:15]
	v_mfma_f32_16x16x32_bf16 v[4:7], v[166:169], v[218:221], v[4:7]
	v_mfma_f32_16x16x32_bf16 v[56:59], v[170:173], v[186:189], v[56:59]
	v_mfma_f32_16x16x32_bf16 v[48:51], v[178:181], v[186:189], v[48:51]
	v_mfma_f32_16x16x32_bf16 v[40:43], v[170:173], v[198:201], v[40:43]
	v_mfma_f32_16x16x32_bf16 v[32:35], v[178:181], v[198:201], v[32:35]
	v_mfma_f32_16x16x32_bf16 v[24:27], v[170:173], v[206:209], v[24:27]
	v_mfma_f32_16x16x32_bf16 v[16:19], v[178:181], v[206:209], v[16:19]
	v_mfma_f32_16x16x32_bf16 v[8:11], v[170:173], v[214:217], v[8:11]
	v_mfma_f32_16x16x32_bf16 v[0:3], v[178:181], v[214:217], v[0:3]
	v_mfma_f32_16x16x32_bf16 v[56:59], v[174:177], v[190:193], v[56:59]
	v_mfma_f32_16x16x32_bf16 v[48:51], v[182:185], v[190:193], v[48:51]
	v_mfma_f32_16x16x32_bf16 v[40:43], v[174:177], v[202:205], v[40:43]
	v_mfma_f32_16x16x32_bf16 v[32:35], v[182:185], v[202:205], v[32:35]
	v_mfma_f32_16x16x32_bf16 v[24:27], v[174:177], v[210:213], v[24:27]
	v_mfma_f32_16x16x32_bf16 v[16:19], v[182:185], v[210:213], v[16:19]
	v_mfma_f32_16x16x32_bf16 v[8:11], v[174:177], v[218:221], v[8:11]
	v_mfma_f32_16x16x32_bf16 v[0:3], v[182:185], v[218:221], v[0:3]
	s_barrier
	s_add_i32 s69, s69, 2
	s_add_u32 s20, s20, 0x100
	s_addc_u32 s21, s21, 0
	s_add_u32 s67, s67, 0x100
	s_addc_u32 s68, s68, 0
	s_cmp_gt_u32 s69, 13
	s_cbranch_scc0 .LBB0_810
	v_readlane_b32 s101, v249, 49
	s_nop 3
	s_cmp_eq_u32 s101, 0
	s_cbranch_scc1 .Ldw_done_1
	v_cmp_le_u32_e32 vcc, s101, v250
	s_cbranch_vccnz .Ldw_ok_1
	s_add_u32 s98, s28, 0x183500
	s_addc_u32 s99, s29, 0
	v_mov_b32_e32 v251, 0
	s_mov_b32 s100, 0

; #define PG8_STAGE(bufoff, gbase, voff) do { _Pragma("unroll") for (int _i = 0; _i < 2; ++_i) \
;         __builtin_amdgcn_global_load_lds((const unsigned*)((const char*)(gbase) + (voff)[_i]), (PG8_LAS unsigned*)(lds + (bufoff) + ldsw + _i * 8192), 16, 0, 0); } while (0)
; #define PG8_LDA(dst, b, h) do { _Pragma("unroll") for (int m = 0; m < 4; ++m) _Pragma("unroll") for (int k = 0; k < 2; ++k) dst[m][k] = *(const PG8_LAS bf16x8*)(lds + PG8_SA(b, h) + aoff + m * 2048 + k * 1024); } while (0)
; #define PG8_LDB(dst, b, h) do { _Pragma("unroll") for (int n = 0; n < 2; ++n) _Pragma("unroll") for (int k = 0; k < 2; ++k) dst[n][k] = *(const PG8_LAS bf16x8*)(lds + PG8_SB(b, h) + boff + n * 2048 + k * 1024); } while (0)
; #define PG8_WAIT_V(n) asm volatile("s_waitcnt vmcnt(" #n ")" ::: "memory")
; #define PG8_WAIT_L(n) asm volatile("s_waitcnt lgkmcnt(" #n ")" ::: "memory")
; #define PG8_BAR __builtin_amdgcn_s_barrier()
; #define PG8_SCHED __builtin_amdgcn_sched_barrier(0)
; template <class Epi, class Sched, bool ALIGN_EPI = false, bool SP2 = false>
; __device__ __forceinline__ void gemm_phase(PG8_LAS unsigned char* lds, const Gemm g, const Sched& S, const Epi& E) {
;     ...
;         const bool has_next = S.next(ui + 1, nxt);
;         const char* nA = has_next ? (const char*)g.A + (size_t)nxt.pm * tstep : cA; const char* nB = has_next ? (const char*)g.Bt + (size_t)nxt.pn * tstep : cB;
;         for (int t = 0; t < nt; t += 2) {
;             const bool last = (t == nt - 2);
;             const char* a1 = cA + (size_t)(t + 1) * kstep;
;             const char* a2 = last ? nA : cA + (size_t)(t + 2) * kstep; const char* b2 = last ? nB : cB + (size_t)(t + 2) * kstep;
;             const char* a3 = a2 + kstep; const char* b3 = b2 + kstep;
;             if (last && has_next) S.a_ready(nxt);
;             if constexpr (SP2) {
;             PG8_LDB(B0, 0, 0); PG8_LDB(B1, 0, 1); PG8_SCHED; PG8_LDA(At, 0, 0); PG8_STAGE(PG8_SA(1, 1), a1 + hstep, voffA);
;             PG8_WAIT_V(8); PG8_WAIT_L(0); PG8_BAR; PG8_MMA(0, 0, At, B0); PG8_MMA(0, 1, At, B1); PG8_BAR; PG8_SCHED;
;             PG8_LDA(At, 0, 1); PG8_STAGE(PG8_SB(0, 0), b2, voffB); PG8_STAGE(PG8_SB(0, 1), b2 + hstep, voffB); PG8_STAGE(PG8_SA(0, 0), a2, voffA);
;             PG8_WAIT_V(8); PG8_WAIT_L(0); PG8_BAR; PG8_MMA(1, 0, At, B0); PG8_MMA(1, 1, At, B1); PG8_BAR; PG8_SCHED;
.LBB0_1199:
	s_ashr_i32 s57, s56, 31
	s_lshl_b64 s[58:59], s[56:57], 19
	s_add_u32 s58, s36, s58
	s_addc_u32 s59, s37, s59
	s_and_b64 s[60:61], s[8:9], exec
	s_cselect_b32 s1, s59, s21
	s_cselect_b32 s57, s58, s20
	s_ashr_i32 s55, s54, 31
	s_lshl_b64 s[60:61], s[54:55], 19
	s_add_u32 s60, s68, s60
	s_addc_u32 s61, s69, s61
	s_and_b64 s[62:63], s[8:9], exec
	s_cselect_b32 s55, s61, s35
	s_cselect_b32 s85, s60, s34
	s_add_u32 s20, s20, 0x40080
	s_addc_u32 s21, s21, 0
	s_add_u32 s86, s34, 0x100
	s_addc_u32 s87, s35, 0
	s_mov_b32 s88, -2
	s_waitcnt lgkmcnt(0)
	s_add_u32 s98, s28, 0x183500
	s_addc_u32 s99, s29, 0
	v_mov_b32_e32 v251, 0
	global_load_dword v250, v251, s[98:99] sc1
	ds_read_b128 v[140:143], v163
	ds_read_b128 v[168:171], v163 offset:1024
	ds_read_b128 v[172:175], v163 offset:2048
	ds_read_b128 v[176:179], v163 offset:3072
	ds_read_b128 v[180:183], v164
	ds_read_b128 v[184:187], v164 offset:1024
	ds_read_b128 v[188:191], v164 offset:2048
	ds_read_b128 v[192:195], v164 offset:3072
	s_add_u32 s34, s20, 0xfffc0080
	s_addc_u32 s35, s21, -1
	s_cmp_eq_u32 s88, 12
	s_cselect_b32 s63, s1, s35
	s_cselect_b32 s62, s57, s34
	s_cselect_b32 s35, s55, s87
	s_cselect_b32 s34, s85, s86
	s_add_i32 m0, s71, 0xc000
	ds_read_b128 v[198:201], v165
	ds_read_b128 v[202:205], v165 offset:1024
	ds_read_b128 v[206:209], v165 offset:2048
	ds_read_b128 v[210:213], v165 offset:3072
	ds_read_b128 v[214:217], v165 offset:4096
	ds_read_b128 v[218:221], v165 offset:5120
	ds_read_b128 v[222:225], v165 offset:6144
	ds_read_b128 v[226:229], v165 offset:7168
	global_load_lds_dwordx4 v132, s[20:21]
	s_add_i32 m0, s71, 0xe000
	s_nop 0
	global_load_lds_dwordx4 v134, s[20:21]
	s_waitcnt vmcnt(8)
	s_waitcnt lgkmcnt(0)
	s_barrier
	v_mfma_f32_16x16x32_bf16 v[124:127], v[140:143], v[198:201], 0
	v_mfma_f32_16x16x32_bf16 v[120:123], v[172:175], v[198:201], 0
	v_mfma_f32_16x16x32_bf16 v[108:111], v[140:143], v[206:209], 0
	v_mfma_f32_16x16x32_bf16 v[104:107], v[172:175], v[206:209], 0
	v_mfma_f32_16x16x32_bf16 v[92:95], v[140:143], v[214:217], 0
	v_mfma_f32_16x16x32_bf16 v[88:91], v[172:175], v[214:217], 0
	v_mfma_f32_16x16x32_bf16 v[76:79], v[140:143], v[222:225], 0
	v_mfma_f32_16x16x32_bf16 v[72:75], v[172:175], v[222:225], 0
	v_mfma_f32_16x16x32_bf16 v[124:127], v[168:171], v[202:205], v[124:127]
	v_mfma_f32_16x16x32_bf16 v[120:123], v[176:179], v[202:205], v[120:123]
	v_mfma_f32_16x16x32_bf16 v[108:111], v[168:171], v[210:213], v[108:111]
	v_mfma_f32_16x16x32_bf16 v[104:107], v[176:179], v[210:213], v[104:107]
	v_mfma_f32_16x16x32_bf16 v[92:95], v[168:171], v[218:221], v[92:95]
	v_mfma_f32_16x16x32_bf16 v[88:91], v[176:179], v[218:221], v[88:91]
	v_mfma_f32_16x16x32_bf16 v[76:79], v[168:171], v[226:229], v[76:79]
	v_mfma_f32_16x16x32_bf16 v[72:75], v[176:179], v[226:229], v[72:75]
	v_mfma_f32_16x16x32_bf16 v[116:119], v[180:183], v[198:201], 0
	v_mfma_f32_16x16x32_bf16 v[112:115], v[188:191], v[198:201], 0
	v_mfma_f32_16x16x32_bf16 v[100:103], v[180:183], v[206:209], 0
	v_mfma_f32_16x16x32_bf16 v[96:99], v[188:191], v[206:209], 0
	v_mfma_f32_16x16x32_bf16 v[84:87], v[180:183], v[214:217], 0
	v_mfma_f32_16x16x32_bf16 v[80:83], v[188:191], v[214:217], 0
	v_mfma_f32_16x16x32_bf16 v[68:71], v[180:183], v[222:225], 0
	v_mfma_f32_16x16x32_bf16 v[64:67], v[188:191], v[222:225], 0
	v_mfma_f32_16x16x32_bf16 v[116:119], v[184:187], v[202:205], v[116:119]
	v_mfma_f32_16x16x32_bf16 v[112:115], v[192:195], v[202:205], v[112:115]
	v_mfma_f32_16x16x32_bf16 v[100:103], v[184:187], v[210:213], v[100:103]
	v_mfma_f32_16x16x32_bf16 v[96:99], v[192:195], v[210:213], v[96:99]
	v_mfma_f32_16x16x32_bf16 v[84:87], v[184:187], v[218:221], v[84:87]
	v_mfma_f32_16x16x32_bf16 v[80:83], v[192:195], v[218:221], v[80:83]
	v_mfma_f32_16x16x32_bf16 v[68:71], v[184:187], v[226:229], v[68:71]
	v_mfma_f32_16x16x32_bf16 v[64:67], v[192:195], v[226:229], v[64:67]
	s_barrier
	s_add_i32 s89, s77, s70
	s_add_u32 s98, s34, s18
	s_addc_u32 s99, s35, s19
	s_add_u32 s100, s62, s18
	s_addc_u32 s101, s63, s19
	s_mov_b32 m0, s89
	ds_read_b128 v[198:201], v165 offset:16384
	ds_read_b128 v[202:205], v165 offset:17408
	ds_read_b128 v[206:209], v165 offset:18432
	ds_read_b128 v[210:213], v165 offset:19456
	ds_read_b128 v[214:217], v165 offset:20480
	ds_read_b128 v[218:221], v165 offset:21504
	ds_read_b128 v[222:225], v165 offset:22528
	ds_read_b128 v[226:229], v165 offset:23552
	global_load_lds_dwordx4 v146, s[34:35]
	s_add_i32 m0, s89, 0x2000
	s_add_u32 s90, s34, 0x40000
	s_addc_u32 s91, s35, 0
	s_add_i32 s89, s78, s70
	global_load_lds_dwordx4 v150, s[34:35]
	s_mov_b32 m0, s89
	s_nop 0
	global_load_lds_dwordx4 v146, s[90:91]
	s_add_i32 m0, s89, 0x2000
	s_nop 0
	global_load_lds_dwordx4 v150, s[90:91]
	s_mov_b32 m0, s71
	s_nop 0
	global_load_lds_dwordx4 v144, s[62:63]
	s_mov_b32 m0, s72
	s_nop 0
	global_load_lds_dwordx4 v148, s[62:63]
	s_waitcnt vmcnt(8)
	s_waitcnt lgkmcnt(0)
	s_barrier
; #define PG8_STAGE(bufoff, gbase, voff) do { _Pragma("unroll") for (int _i = 0; _i < 2; ++_i) \
;         __builtin_amdgcn_global_load_lds((const unsigned*)((const char*)(gbase) + (voff)[_i]), (PG8_LAS unsigned*)(lds + (bufoff) + ldsw + _i * 8192), 16, 0, 0); } while (0)
; #define PG8_LDA(dst, b, h) do { _Pragma("unroll") for (int m = 0; m < 4; ++m) _Pragma("unroll") for (int k = 0; k < 2; ++k) dst[m][k] = *(const PG8_LAS bf16x8*)(lds + PG8_SA(b, h) + aoff + m * 2048 + k * 1024); } while (0)
; #define PG8_LDB(dst, b, h) do { _Pragma("unroll") for (int n = 0; n < 2; ++n) _Pragma("unroll") for (int k = 0; k < 2; ++k) dst[n][k] = *(const PG8_LAS bf16x8*)(lds + PG8_SB(b, h) + boff + n * 2048 + k * 1024); } while (0)
; #define PG8_MMA(ai, bj, At, Bt) do { __builtin_amdgcn_s_setprio(1); _Pragma("unroll") for (int m = 0; m < 4; ++m) _Pragma("unroll") for (int n = 0; n < 2; ++n) _Pragma("unroll") for (int k = 0; k < 2; ++k) \
;         acc[ai][bj][m][n] = __builtin_amdgcn_mfma_f32_16x16x32_bf16(Bt[n][k], At[m][k], acc[ai][bj][m][n], 0, 0, 0); __builtin_amdgcn_s_setprio(0); } while (0)
; #define PG8_WAIT_V(n) asm volatile("s_waitcnt vmcnt(" #n ")" ::: "memory")
; #define PG8_WAIT_L(n) asm volatile("s_waitcnt lgkmcnt(" #n ")" ::: "memory")
; #define PG8_BAR __builtin_amdgcn_s_barrier()
; #define PG8_SCHED __builtin_amdgcn_sched_barrier(0)
; template <class Epi, class Sched, bool ALIGN_EPI = false, bool SP2 = false>
; __device__ __forceinline__ void gemm_phase(PG8_LAS unsigned char* lds, const Gemm g, const Sched& S, const Epi& E) {
;     ...
;             PG8_WAIT_V(8); PG8_WAIT_L(0); PG8_BAR; PG8_MMA(1, 0, At, B0); PG8_MMA(1, 1, At, B1); PG8_BAR; PG8_SCHED;
;             PG8_LDB(B0, 1, 0); PG8_LDB(B1, 1, 1); PG8_SCHED; PG8_LDA(At, 1, 0); PG8_STAGE(PG8_SA(0, 1), a2 + hstep, voffA);
;             PG8_WAIT_V(8); PG8_WAIT_L(0); PG8_BAR; PG8_MMA(0, 0, At, B0); PG8_MMA(0, 1, At, B1); PG8_BAR; PG8_SCHED;
	v_mfma_f32_16x16x32_bf16 v[60:63], v[140:143], v[198:201], 0
	v_mfma_f32_16x16x32_bf16 v[56:59], v[172:175], v[198:201], 0
	v_mfma_f32_16x16x32_bf16 v[48:51], v[140:143], v[206:209], 0
	v_mfma_f32_16x16x32_bf16 v[40:43], v[172:175], v[206:209], 0
	v_mfma_f32_16x16x32_bf16 v[32:35], v[140:143], v[214:217], 0
	v_mfma_f32_16x16x32_bf16 v[24:27], v[172:175], v[214:217], 0
	v_mfma_f32_16x16x32_bf16 v[16:19], v[140:143], v[222:225], 0
	v_mfma_f32_16x16x32_bf16 v[8:11], v[172:175], v[222:225], 0
	v_mfma_f32_16x16x32_bf16 v[60:63], v[168:171], v[202:205], v[60:63]
	v_mfma_f32_16x16x32_bf16 v[56:59], v[176:179], v[202:205], v[56:59]
	v_mfma_f32_16x16x32_bf16 v[48:51], v[168:171], v[210:213], v[48:51]
	v_mfma_f32_16x16x32_bf16 v[40:43], v[176:179], v[210:213], v[40:43]
	v_mfma_f32_16x16x32_bf16 v[32:35], v[168:171], v[218:221], v[32:35]
	v_mfma_f32_16x16x32_bf16 v[24:27], v[176:179], v[218:221], v[24:27]
	v_mfma_f32_16x16x32_bf16 v[16:19], v[168:171], v[226:229], v[16:19]
	v_mfma_f32_16x16x32_bf16 v[8:11], v[176:179], v[226:229], v[8:11]
	v_mfma_f32_16x16x32_bf16 v[52:55], v[180:183], v[198:201], 0
	v_mfma_f32_16x16x32_bf16 v[44:47], v[188:191], v[198:201], 0
	v_mfma_f32_16x16x32_bf16 v[36:39], v[180:183], v[206:209], 0
	v_mfma_f32_16x16x32_bf16 v[28:31], v[188:191], v[206:209], 0
	v_mfma_f32_16x16x32_bf16 v[20:23], v[180:183], v[214:217], 0
	v_mfma_f32_16x16x32_bf16 v[12:15], v[188:191], v[214:217], 0
	v_mfma_f32_16x16x32_bf16 v[4:7], v[180:183], v[222:225], 0
	v_mfma_f32_16x16x32_bf16 v[0:3], v[188:191], v[222:225], 0
	v_mfma_f32_16x16x32_bf16 v[52:55], v[184:187], v[202:205], v[52:55]
	v_mfma_f32_16x16x32_bf16 v[44:47], v[192:195], v[202:205], v[44:47]
	v_mfma_f32_16x16x32_bf16 v[36:39], v[184:187], v[210:213], v[36:39]
	v_mfma_f32_16x16x32_bf16 v[28:31], v[192:195], v[210:213], v[28:31]
	v_mfma_f32_16x16x32_bf16 v[20:23], v[184:187], v[218:221], v[20:23]
	v_mfma_f32_16x16x32_bf16 v[12:15], v[192:195], v[218:221], v[12:15]
	v_mfma_f32_16x16x32_bf16 v[4:7], v[184:187], v[226:229], v[4:7]
	v_mfma_f32_16x16x32_bf16 v[0:3], v[192:195], v[226:229], v[0:3]
	s_barrier
	s_add_i32 s89, 0, 0x18000
	v_add_u32_e32 v128, s89, v161
	s_add_i32 s90, 0, 0x1c000
	ds_read_b128 v[140:143], v128
	ds_read_b128 v[168:171], v128 offset:1024
	ds_read_b128 v[172:175], v128 offset:2048
	ds_read_b128 v[176:179], v128 offset:3072
	v_add_u32_e32 v128, s90, v161
	ds_read_b128 v[180:183], v128
	ds_read_b128 v[184:187], v128 offset:1024
	ds_read_b128 v[188:191], v128 offset:2048
	ds_read_b128 v[192:195], v128 offset:3072
	s_add_u32 s62, s62, 0x40000
	s_addc_u32 s63, s63, 0
	s_mov_b32 m0, s73
	ds_read_b128 v[198:201], v165 offset:32768
	ds_read_b128 v[202:205], v165 offset:33792
	ds_read_b128 v[206:209], v165 offset:34816
	ds_read_b128 v[210:213], v165 offset:35840
	ds_read_b128 v[214:217], v165 offset:36864
	ds_read_b128 v[218:221], v165 offset:37888
	ds_read_b128 v[222:225], v165 offset:38912
	ds_read_b128 v[226:229], v165 offset:39936
	global_load_lds_dwordx4 v144, s[62:63]
	s_mov_b32 m0, s74
	s_nop 0
	global_load_lds_dwordx4 v148, s[62:63]
	s_waitcnt vmcnt(8)
	s_waitcnt lgkmcnt(0)
	s_barrier
	v_mfma_f32_16x16x32_bf16 v[124:127], v[140:143], v[198:201], v[124:127]
	v_mfma_f32_16x16x32_bf16 v[120:123], v[172:175], v[198:201], v[120:123]
	v_mfma_f32_16x16x32_bf16 v[108:111], v[140:143], v[206:209], v[108:111]
	v_mfma_f32_16x16x32_bf16 v[104:107], v[172:175], v[206:209], v[104:107]
	v_mfma_f32_16x16x32_bf16 v[92:95], v[140:143], v[214:217], v[92:95]
	v_mfma_f32_16x16x32_bf16 v[88:91], v[172:175], v[214:217], v[88:91]
	v_mfma_f32_16x16x32_bf16 v[76:79], v[140:143], v[222:225], v[76:79]
	v_mfma_f32_16x16x32_bf16 v[72:75], v[172:175], v[222:225], v[72:75]
	v_mfma_f32_16x16x32_bf16 v[124:127], v[168:171], v[202:205], v[124:127]
	v_mfma_f32_16x16x32_bf16 v[120:123], v[176:179], v[202:205], v[120:123]
	v_mfma_f32_16x16x32_bf16 v[108:111], v[168:171], v[210:213], v[108:111]
	v_mfma_f32_16x16x32_bf16 v[104:107], v[176:179], v[210:213], v[104:107]
	v_mfma_f32_16x16x32_bf16 v[92:95], v[168:171], v[218:221], v[92:95]
	v_mfma_f32_16x16x32_bf16 v[88:91], v[176:179], v[218:221], v[88:91]
	v_mfma_f32_16x16x32_bf16 v[76:79], v[168:171], v[226:229], v[76:79]
	v_mfma_f32_16x16x32_bf16 v[72:75], v[176:179], v[226:229], v[72:75]
	v_mfma_f32_16x16x32_bf16 v[116:119], v[180:183], v[198:201], v[116:119]
	v_mfma_f32_16x16x32_bf16 v[112:115], v[188:191], v[198:201], v[112:115]
	v_mfma_f32_16x16x32_bf16 v[100:103], v[180:183], v[206:209], v[100:103]
	v_mfma_f32_16x16x32_bf16 v[96:99], v[188:191], v[206:209], v[96:99]
	v_mfma_f32_16x16x32_bf16 v[84:87], v[180:183], v[214:217], v[84:87]
	v_mfma_f32_16x16x32_bf16 v[80:83], v[188:191], v[214:217], v[80:83]
	v_mfma_f32_16x16x32_bf16 v[68:71], v[180:183], v[222:225], v[68:71]
	v_mfma_f32_16x16x32_bf16 v[64:67], v[188:191], v[222:225], v[64:67]
	v_mfma_f32_16x16x32_bf16 v[116:119], v[184:187], v[202:205], v[116:119]
	v_mfma_f32_16x16x32_bf16 v[112:115], v[192:195], v[202:205], v[112:115]
	v_mfma_f32_16x16x32_bf16 v[100:103], v[184:187], v[210:213], v[100:103]
	v_mfma_f32_16x16x32_bf16 v[96:99], v[192:195], v[210:213], v[96:99]
	v_mfma_f32_16x16x32_bf16 v[84:87], v[184:187], v[218:221], v[84:87]
	v_mfma_f32_16x16x32_bf16 v[80:83], v[192:195], v[218:221], v[80:83]
	v_mfma_f32_16x16x32_bf16 v[68:71], v[184:187], v[226:229], v[68:71]
	v_mfma_f32_16x16x32_bf16 v[64:67], v[192:195], v[226:229], v[64:67]
	s_barrier
; #define PG8_STAGE(bufoff, gbase, voff) do { _Pragma("unroll") for (int _i = 0; _i < 2; ++_i) \
;         __builtin_amdgcn_global_load_lds((const unsigned*)((const char*)(gbase) + (voff)[_i]), (PG8_LAS unsigned*)(lds + (bufoff) + ldsw + _i * 8192), 16, 0, 0); } while (0)
; #define PG8_LDA(dst, b, h) do { _Pragma("unroll") for (int m = 0; m < 4; ++m) _Pragma("unroll") for (int k = 0; k < 2; ++k) dst[m][k] = *(const PG8_LAS bf16x8*)(lds + PG8_SA(b, h) + aoff + m * 2048 + k * 1024); } while (0)
; #define PG8_LDB(dst, b, h) do { _Pragma("unroll") for (int n = 0; n < 2; ++n) _Pragma("unroll") for (int k = 0; k < 2; ++k) dst[n][k] = *(const PG8_LAS bf16x8*)(lds + PG8_SB(b, h) + boff + n * 2048 + k * 1024); } while (0)
; #define PG8_MMA(ai, bj, At, Bt) do { __builtin_amdgcn_s_setprio(1); _Pragma("unroll") for (int m = 0; m < 4; ++m) _Pragma("unroll") for (int n = 0; n < 2; ++n) _Pragma("unroll") for (int k = 0; k < 2; ++k) \
;         acc[ai][bj][m][n] = __builtin_amdgcn_mfma_f32_16x16x32_bf16(Bt[n][k], At[m][k], acc[ai][bj][m][n], 0, 0, 0); __builtin_amdgcn_s_setprio(0); } while (0)
; #define PG8_WAIT_V(n) asm volatile("s_waitcnt vmcnt(" #n ")" ::: "memory")
; #define PG8_WAIT_L(n) asm volatile("s_waitcnt lgkmcnt(" #n ")" ::: "memory")
; #define PG8_BAR __builtin_amdgcn_s_barrier()
; #define PG8_SCHED __builtin_amdgcn_sched_barrier(0)
; template <class Epi, class Sched, bool ALIGN_EPI = false, bool SP2 = false>
; __device__ __forceinline__ void gemm_phase(PG8_LAS unsigned char* lds, const Gemm g, const Sched& S, const Epi& E) {
;     ...
;             PG8_LDB(B0, 0, 0); PG8_LDB(B1, 0, 1); PG8_SCHED; PG8_LDA(At, 0, 0); PG8_STAGE(PG8_SA(1, 1), a1 + hstep, voffA);
;             PG8_WAIT_V(8); PG8_WAIT_L(0); PG8_BAR; PG8_MMA(0, 0, At, B0); PG8_MMA(0, 1, At, B1); PG8_BAR; PG8_SCHED;
;     ...
;             PG8_LDA(At, 1, 1); PG8_STAGE(PG8_SB(1, 0), b3, voffB); PG8_STAGE(PG8_SB(1, 1), b3 + hstep, voffB); PG8_STAGE(PG8_SA(1, 0), a3, voffA);
;             PG8_WAIT_V(8); PG8_WAIT_L(0); PG8_BAR; PG8_MMA(1, 0, At, B0); PG8_MMA(1, 1, At, B1); PG8_BAR; PG8_SCHED;
	s_add_i32 s62, s89, s70
	s_mov_b32 m0, s62
	ds_read_b128 v[198:201], v165 offset:49152
	ds_read_b128 v[202:205], v165 offset:50176
	ds_read_b128 v[206:209], v165 offset:51200
	ds_read_b128 v[210:213], v165 offset:52224
	ds_read_b128 v[214:217], v165 offset:53248
	ds_read_b128 v[218:221], v165 offset:54272
	ds_read_b128 v[222:225], v165 offset:55296
	ds_read_b128 v[226:229], v165 offset:56320
	global_load_lds_dwordx4 v146, s[98:99]
	s_add_i32 m0, s62, 0x2000
	s_add_u32 s34, s34, 0x40080
	s_addc_u32 s35, s35, 0
	s_add_i32 s62, s90, s70
	global_load_lds_dwordx4 v150, s[98:99]
	s_mov_b32 m0, s62
	s_nop 0
	global_load_lds_dwordx4 v146, s[34:35]
	s_add_i32 m0, s62, 0x2000
	s_nop 0
	global_load_lds_dwordx4 v150, s[34:35]
	s_mov_b32 m0, s75
	s_nop 0
	global_load_lds_dwordx4 v144, s[100:101]
	s_mov_b32 m0, s76
	s_nop 0
	global_load_lds_dwordx4 v148, s[100:101]
	s_waitcnt vmcnt(8)
	s_waitcnt lgkmcnt(0)
	s_barrier
	v_mfma_f32_16x16x32_bf16 v[60:63], v[140:143], v[198:201], v[60:63]
	v_mfma_f32_16x16x32_bf16 v[56:59], v[172:175], v[198:201], v[56:59]
	v_mfma_f32_16x16x32_bf16 v[48:51], v[140:143], v[206:209], v[48:51]
	v_mfma_f32_16x16x32_bf16 v[40:43], v[172:175], v[206:209], v[40:43]
	v_mfma_f32_16x16x32_bf16 v[32:35], v[140:143], v[214:217], v[32:35]
	v_mfma_f32_16x16x32_bf16 v[24:27], v[172:175], v[214:217], v[24:27]
	v_mfma_f32_16x16x32_bf16 v[16:19], v[140:143], v[222:225], v[16:19]
	v_mfma_f32_16x16x32_bf16 v[8:11], v[172:175], v[222:225], v[8:11]
	v_mfma_f32_16x16x32_bf16 v[60:63], v[168:171], v[202:205], v[60:63]
	v_mfma_f32_16x16x32_bf16 v[56:59], v[176:179], v[202:205], v[56:59]
	v_mfma_f32_16x16x32_bf16 v[48:51], v[168:171], v[210:213], v[48:51]
	v_mfma_f32_16x16x32_bf16 v[40:43], v[176:179], v[210:213], v[40:43]
	v_mfma_f32_16x16x32_bf16 v[32:35], v[168:171], v[218:221], v[32:35]
	v_mfma_f32_16x16x32_bf16 v[24:27], v[176:179], v[218:221], v[24:27]
	v_mfma_f32_16x16x32_bf16 v[16:19], v[168:171], v[226:229], v[16:19]
	v_mfma_f32_16x16x32_bf16 v[8:11], v[176:179], v[226:229], v[8:11]
	v_mfma_f32_16x16x32_bf16 v[52:55], v[180:183], v[198:201], v[52:55]
	v_mfma_f32_16x16x32_bf16 v[44:47], v[188:191], v[198:201], v[44:47]
	v_mfma_f32_16x16x32_bf16 v[36:39], v[180:183], v[206:209], v[36:39]
	v_mfma_f32_16x16x32_bf16 v[28:31], v[188:191], v[206:209], v[28:31]
	v_mfma_f32_16x16x32_bf16 v[20:23], v[180:183], v[214:217], v[20:23]
	v_mfma_f32_16x16x32_bf16 v[12:15], v[188:191], v[214:217], v[12:15]
	v_mfma_f32_16x16x32_bf16 v[4:7], v[180:183], v[222:225], v[4:7]
	v_mfma_f32_16x16x32_bf16 v[0:3], v[188:191], v[222:225], v[0:3]
	v_mfma_f32_16x16x32_bf16 v[52:55], v[184:187], v[202:205], v[52:55]
	v_mfma_f32_16x16x32_bf16 v[44:47], v[192:195], v[202:205], v[44:47]
	v_mfma_f32_16x16x32_bf16 v[36:39], v[184:187], v[210:213], v[36:39]
	v_mfma_f32_16x16x32_bf16 v[28:31], v[192:195], v[210:213], v[28:31]
	v_mfma_f32_16x16x32_bf16 v[20:23], v[184:187], v[218:221], v[20:23]
	v_mfma_f32_16x16x32_bf16 v[12:15], v[192:195], v[218:221], v[12:15]
	v_mfma_f32_16x16x32_bf16 v[4:7], v[184:187], v[226:229], v[4:7]
	v_mfma_f32_16x16x32_bf16 v[0:3], v[192:195], v[226:229], v[0:3]
	s_barrier
	s_add_i32 s88, s88, 2
	s_add_u32 s20, s20, 0x100
	s_addc_u32 s21, s21, 0
	s_add_u32 s86, s86, 0x100
	s_addc_u32 s87, s87, 0
	s_cmp_gt_u32 s88, 13
.LBB0_1200:
	ds_read_b128 v[140:143], v163
	ds_read_b128 v[168:171], v163 offset:1024
	ds_read_b128 v[172:175], v163 offset:2048
	ds_read_b128 v[176:179], v163 offset:3072
	ds_read_b128 v[180:183], v164
	ds_read_b128 v[184:187], v164 offset:1024
	ds_read_b128 v[188:191], v164 offset:2048
	ds_read_b128 v[192:195], v164 offset:3072
	s_add_u32 s34, s20, 0xfffc0080
	s_addc_u32 s35, s21, -1
	s_cmp_eq_u32 s88, 12
	s_cselect_b32 s63, s1, s35
	s_cselect_b32 s62, s57, s34
	s_cselect_b32 s35, s55, s87
	s_cselect_b32 s34, s85, s86
	s_add_i32 m0, s71, 0xc000
	ds_read_b128 v[198:201], v165
	ds_read_b128 v[202:205], v165 offset:1024
	ds_read_b128 v[206:209], v165 offset:2048
	ds_read_b128 v[210:213], v165 offset:3072
	ds_read_b128 v[214:217], v165 offset:4096
	ds_read_b128 v[218:221], v165 offset:5120
	ds_read_b128 v[222:225], v165 offset:6144
	ds_read_b128 v[226:229], v165 offset:7168
	global_load_lds_dwordx4 v132, s[20:21]
	s_add_i32 m0, s71, 0xe000
	s_nop 0
	global_load_lds_dwordx4 v134, s[20:21]
	s_waitcnt vmcnt(8)
	s_waitcnt lgkmcnt(0)
	s_barrier
	v_mfma_f32_16x16x32_bf16 v[124:127], v[140:143], v[198:201], v[124:127]
	v_mfma_f32_16x16x32_bf16 v[120:123], v[172:175], v[198:201], v[120:123]
	v_mfma_f32_16x16x32_bf16 v[108:111], v[140:143], v[206:209], v[108:111]
	v_mfma_f32_16x16x32_bf16 v[104:107], v[172:175], v[206:209], v[104:107]
	v_mfma_f32_16x16x32_bf16 v[92:95], v[140:143], v[214:217], v[92:95]
	v_mfma_f32_16x16x32_bf16 v[88:91], v[172:175], v[214:217], v[88:91]
	v_mfma_f32_16x16x32_bf16 v[76:79], v[140:143], v[222:225], v[76:79]
	v_mfma_f32_16x16x32_bf16 v[72:75], v[172:175], v[222:225], v[72:75]
	v_mfma_f32_16x16x32_bf16 v[124:127], v[168:171], v[202:205], v[124:127]
	v_mfma_f32_16x16x32_bf16 v[120:123], v[176:179], v[202:205], v[120:123]
	v_mfma_f32_16x16x32_bf16 v[108:111], v[168:171], v[210:213], v[108:111]
	v_mfma_f32_16x16x32_bf16 v[104:107], v[176:179], v[210:213], v[104:107]
	v_mfma_f32_16x16x32_bf16 v[92:95], v[168:171], v[218:221], v[92:95]
	v_mfma_f32_16x16x32_bf16 v[88:91], v[176:179], v[218:221], v[88:91]
	v_mfma_f32_16x16x32_bf16 v[76:79], v[168:171], v[226:229], v[76:79]
	v_mfma_f32_16x16x32_bf16 v[72:75], v[176:179], v[226:229], v[72:75]
	v_mfma_f32_16x16x32_bf16 v[116:119], v[180:183], v[198:201], v[116:119]
	v_mfma_f32_16x16x32_bf16 v[112:115], v[188:191], v[198:201], v[112:115]
	v_mfma_f32_16x16x32_bf16 v[100:103], v[180:183], v[206:209], v[100:103]
	v_mfma_f32_16x16x32_bf16 v[96:99], v[188:191], v[206:209], v[96:99]
	v_mfma_f32_16x16x32_bf16 v[84:87], v[180:183], v[214:217], v[84:87]
	v_mfma_f32_16x16x32_bf16 v[80:83], v[188:191], v[214:217], v[80:83]
	v_mfma_f32_16x16x32_bf16 v[68:71], v[180:183], v[222:225], v[68:71]
	v_mfma_f32_16x16x32_bf16 v[64:67], v[188:191], v[222:225], v[64:67]
	v_mfma_f32_16x16x32_bf16 v[116:119], v[184:187], v[202:205], v[116:119]
	v_mfma_f32_16x16x32_bf16 v[112:115], v[192:195], v[202:205], v[112:115]
	v_mfma_f32_16x16x32_bf16 v[100:103], v[184:187], v[210:213], v[100:103]
	v_mfma_f32_16x16x32_bf16 v[96:99], v[192:195], v[210:213], v[96:99]
	v_mfma_f32_16x16x32_bf16 v[84:87], v[184:187], v[218:221], v[84:87]
	v_mfma_f32_16x16x32_bf16 v[80:83], v[192:195], v[218:221], v[80:83]
	v_mfma_f32_16x16x32_bf16 v[68:71], v[184:187], v[226:229], v[68:71]
	v_mfma_f32_16x16x32_bf16 v[64:67], v[192:195], v[226:229], v[64:67]
	s_barrier
; #define PG8_STAGE(bufoff, gbase, voff) do { _Pragma("unroll") for (int _i = 0; _i < 2; ++_i) \
;         __builtin_amdgcn_global_load_lds((const unsigned*)((const char*)(gbase) + (voff)[_i]), (PG8_LAS unsigned*)(lds + (bufoff) + ldsw + _i * 8192), 16, 0, 0); } while (0)
; #define PG8_LDA(dst, b, h) do { _Pragma("unroll") for (int m = 0; m < 4; ++m) _Pragma("unroll") for (int k = 0; k < 2; ++k) dst[m][k] = *(const PG8_LAS bf16x8*)(lds + PG8_SA(b, h) + aoff + m * 2048 + k * 1024); } while (0)
; #define PG8_LDB(dst, b, h) do { _Pragma("unroll") for (int n = 0; n < 2; ++n) _Pragma("unroll") for (int k = 0; k < 2; ++k) dst[n][k] = *(const PG8_LAS bf16x8*)(lds + PG8_SB(b, h) + boff + n * 2048 + k * 1024); } while (0)
; #define PG8_MMA(ai, bj, At, Bt) do { __builtin_amdgcn_s_setprio(1); _Pragma("unroll") for (int m = 0; m < 4; ++m) _Pragma("unroll") for (int n = 0; n < 2; ++n) _Pragma("unroll") for (int k = 0; k < 2; ++k) \
;         acc[ai][bj][m][n] = __builtin_amdgcn_mfma_f32_16x16x32_bf16(Bt[n][k], At[m][k], acc[ai][bj][m][n], 0, 0, 0); __builtin_amdgcn_s_setprio(0); } while (0)
; #define PG8_WAIT_V(n) asm volatile("s_waitcnt vmcnt(" #n ")" ::: "memory")
; #define PG8_WAIT_L(n) asm volatile("s_waitcnt lgkmcnt(" #n ")" ::: "memory")
; #define PG8_BAR __builtin_amdgcn_s_barrier()
; #define PG8_SCHED __builtin_amdgcn_sched_barrier(0)
; template <class Epi, class Sched, bool ALIGN_EPI = false, bool SP2 = false>
; __device__ __forceinline__ void gemm_phase(PG8_LAS unsigned char* lds, const Gemm g, const Sched& S, const Epi& E) {
;     ...
;             PG8_LDA(At, 0, 1); PG8_STAGE(PG8_SB(0, 0), b2, voffB); PG8_STAGE(PG8_SB(0, 1), b2 + hstep, voffB); PG8_STAGE(PG8_SA(0, 0), a2, voffA);
;             PG8_WAIT_V(8); PG8_WAIT_L(0); PG8_BAR; PG8_MMA(1, 0, At, B0); PG8_MMA(1, 1, At, B1); PG8_BAR; PG8_SCHED;
;             PG8_LDB(B0, 1, 0); PG8_LDB(B1, 1, 1); PG8_SCHED; PG8_LDA(At, 1, 0); PG8_STAGE(PG8_SA(0, 1), a2 + hstep, voffA);
;             PG8_WAIT_V(8); PG8_WAIT_L(0); PG8_BAR; PG8_MMA(0, 0, At, B0); PG8_MMA(0, 1, At, B1); PG8_BAR; PG8_SCHED;
	s_add_i32 s89, s77, s70
	s_add_u32 s98, s34, s18
	s_addc_u32 s99, s35, s19
	s_add_u32 s100, s62, s18
	s_addc_u32 s101, s63, s19
	s_mov_b32 m0, s89
	ds_read_b128 v[198:201], v165 offset:16384
	ds_read_b128 v[202:205], v165 offset:17408
	ds_read_b128 v[206:209], v165 offset:18432
	ds_read_b128 v[210:213], v165 offset:19456
	ds_read_b128 v[214:217], v165 offset:20480
	ds_read_b128 v[218:221], v165 offset:21504
	ds_read_b128 v[222:225], v165 offset:22528
	ds_read_b128 v[226:229], v165 offset:23552
	global_load_lds_dwordx4 v146, s[34:35]
	s_add_i32 m0, s89, 0x2000
	s_add_u32 s90, s34, 0x40000
	s_addc_u32 s91, s35, 0
	s_add_i32 s89, s78, s70
	global_load_lds_dwordx4 v150, s[34:35]
	s_mov_b32 m0, s89
	s_nop 0
	global_load_lds_dwordx4 v146, s[90:91]
	s_add_i32 m0, s89, 0x2000
	s_nop 0
	global_load_lds_dwordx4 v150, s[90:91]
	s_mov_b32 m0, s71
	s_nop 0
	global_load_lds_dwordx4 v144, s[62:63]
	s_mov_b32 m0, s72
	s_nop 0
	global_load_lds_dwordx4 v148, s[62:63]
	s_waitcnt vmcnt(8)
	s_waitcnt lgkmcnt(0)
	s_barrier
	v_mfma_f32_16x16x32_bf16 v[60:63], v[140:143], v[198:201], v[60:63]
	v_mfma_f32_16x16x32_bf16 v[56:59], v[172:175], v[198:201], v[56:59]
	v_mfma_f32_16x16x32_bf16 v[48:51], v[140:143], v[206:209], v[48:51]
	v_mfma_f32_16x16x32_bf16 v[40:43], v[172:175], v[206:209], v[40:43]
	v_mfma_f32_16x16x32_bf16 v[32:35], v[140:143], v[214:217], v[32:35]
	v_mfma_f32_16x16x32_bf16 v[24:27], v[172:175], v[214:217], v[24:27]
	v_mfma_f32_16x16x32_bf16 v[16:19], v[140:143], v[222:225], v[16:19]
	v_mfma_f32_16x16x32_bf16 v[8:11], v[172:175], v[222:225], v[8:11]
	v_mfma_f32_16x16x32_bf16 v[60:63], v[168:171], v[202:205], v[60:63]
	v_mfma_f32_16x16x32_bf16 v[56:59], v[176:179], v[202:205], v[56:59]
	v_mfma_f32_16x16x32_bf16 v[48:51], v[168:171], v[210:213], v[48:51]
	v_mfma_f32_16x16x32_bf16 v[40:43], v[176:179], v[210:213], v[40:43]
	v_mfma_f32_16x16x32_bf16 v[32:35], v[168:171], v[218:221], v[32:35]
	v_mfma_f32_16x16x32_bf16 v[24:27], v[176:179], v[218:221], v[24:27]
	v_mfma_f32_16x16x32_bf16 v[16:19], v[168:171], v[226:229], v[16:19]
	v_mfma_f32_16x16x32_bf16 v[8:11], v[176:179], v[226:229], v[8:11]
	v_mfma_f32_16x16x32_bf16 v[52:55], v[180:183], v[198:201], v[52:55]
	v_mfma_f32_16x16x32_bf16 v[44:47], v[188:191], v[198:201], v[44:47]
	v_mfma_f32_16x16x32_bf16 v[36:39], v[180:183], v[206:209], v[36:39]
	v_mfma_f32_16x16x32_bf16 v[28:31], v[188:191], v[206:209], v[28:31]
	v_mfma_f32_16x16x32_bf16 v[20:23], v[180:183], v[214:217], v[20:23]
	v_mfma_f32_16x16x32_bf16 v[12:15], v[188:191], v[214:217], v[12:15]
	v_mfma_f32_16x16x32_bf16 v[4:7], v[180:183], v[222:225], v[4:7]
	v_mfma_f32_16x16x32_bf16 v[0:3], v[188:191], v[222:225], v[0:3]
	v_mfma_f32_16x16x32_bf16 v[52:55], v[184:187], v[202:205], v[52:55]
	v_mfma_f32_16x16x32_bf16 v[44:47], v[192:195], v[202:205], v[44:47]
	v_mfma_f32_16x16x32_bf16 v[36:39], v[184:187], v[210:213], v[36:39]
	v_mfma_f32_16x16x32_bf16 v[28:31], v[192:195], v[210:213], v[28:31]
	v_mfma_f32_16x16x32_bf16 v[20:23], v[184:187], v[218:221], v[20:23]
	v_mfma_f32_16x16x32_bf16 v[12:15], v[192:195], v[218:221], v[12:15]
	v_mfma_f32_16x16x32_bf16 v[4:7], v[184:187], v[226:229], v[4:7]
	v_mfma_f32_16x16x32_bf16 v[0:3], v[192:195], v[226:229], v[0:3]
	s_barrier
	s_add_i32 s89, 0, 0x18000
	v_add_u32_e32 v128, s89, v161
	s_add_i32 s90, 0, 0x1c000
	ds_read_b128 v[140:143], v128
	ds_read_b128 v[168:171], v128 offset:1024
	ds_read_b128 v[172:175], v128 offset:2048
	ds_read_b128 v[176:179], v128 offset:3072
	v_add_u32_e32 v128, s90, v161
	ds_read_b128 v[180:183], v128
	ds_read_b128 v[184:187], v128 offset:1024
	ds_read_b128 v[188:191], v128 offset:2048
	ds_read_b128 v[192:195], v128 offset:3072
	s_add_u32 s62, s62, 0x40000
	s_addc_u32 s63, s63, 0
	s_mov_b32 m0, s73
	ds_read_b128 v[198:201], v165 offset:32768
	ds_read_b128 v[202:205], v165 offset:33792
	ds_read_b128 v[206:209], v165 offset:34816
	ds_read_b128 v[210:213], v165 offset:35840
	ds_read_b128 v[214:217], v165 offset:36864
	ds_read_b128 v[218:221], v165 offset:37888
	ds_read_b128 v[222:225], v165 offset:38912
	ds_read_b128 v[226:229], v165 offset:39936
	global_load_lds_dwordx4 v144, s[62:63]
	s_mov_b32 m0, s74
	s_nop 0
	global_load_lds_dwordx4 v148, s[62:63]
	s_waitcnt vmcnt(8)
	s_waitcnt lgkmcnt(0)
	s_barrier
; #define PG8_STAGE(bufoff, gbase, voff) do { _Pragma("unroll") for (int _i = 0; _i < 2; ++_i) \
;         __builtin_amdgcn_global_load_lds((const unsigned*)((const char*)(gbase) + (voff)[_i]), (PG8_LAS unsigned*)(lds + (bufoff) + ldsw + _i * 8192), 16, 0, 0); } while (0)
; #define PG8_LDA(dst, b, h) do { _Pragma("unroll") for (int m = 0; m < 4; ++m) _Pragma("unroll") for (int k = 0; k < 2; ++k) dst[m][k] = *(const PG8_LAS bf16x8*)(lds + PG8_SA(b, h) + aoff + m * 2048 + k * 1024); } while (0)
; #define PG8_MMA(ai, bj, At, Bt) do { __builtin_amdgcn_s_setprio(1); _Pragma("unroll") for (int m = 0; m < 4; ++m) _Pragma("unroll") for (int n = 0; n < 2; ++n) _Pragma("unroll") for (int k = 0; k < 2; ++k) \
;         acc[ai][bj][m][n] = __builtin_amdgcn_mfma_f32_16x16x32_bf16(Bt[n][k], At[m][k], acc[ai][bj][m][n], 0, 0, 0); __builtin_amdgcn_s_setprio(0); } while (0)
; #define PG8_WAIT_V(n) asm volatile("s_waitcnt vmcnt(" #n ")" ::: "memory")
; #define PG8_WAIT_L(n) asm volatile("s_waitcnt lgkmcnt(" #n ")" ::: "memory")
; #define PG8_BAR __builtin_amdgcn_s_barrier()
; #define PG8_SCHED __builtin_amdgcn_sched_barrier(0)
; template <class Epi, class Sched, bool ALIGN_EPI = false, bool SP2 = false>
; __device__ __forceinline__ void gemm_phase(PG8_LAS unsigned char* lds, const Gemm g, const Sched& S, const Epi& E) {
;     ...
;             PG8_WAIT_V(8); PG8_WAIT_L(0); PG8_BAR; PG8_MMA(0, 0, At, B0); PG8_MMA(0, 1, At, B1); PG8_BAR; PG8_SCHED;
;             PG8_LDA(At, 1, 1); PG8_STAGE(PG8_SB(1, 0), b3, voffB); PG8_STAGE(PG8_SB(1, 1), b3 + hstep, voffB); PG8_STAGE(PG8_SA(1, 0), a3, voffA);
;             PG8_WAIT_V(8); PG8_WAIT_L(0); PG8_BAR; PG8_MMA(1, 0, At, B0); PG8_MMA(1, 1, At, B1); PG8_BAR; PG8_SCHED;
;     ...
;         if constexpr (ALIGN_EPI) { if (wr == 0) PG8_BAR; }
;         if constexpr (!Epi::AFTER_DRAIN) { E(acc, cur, wr, wc, fr, fq); S.done(cur); }
	v_mfma_f32_16x16x32_bf16 v[124:127], v[140:143], v[198:201], v[124:127]
	v_mfma_f32_16x16x32_bf16 v[120:123], v[172:175], v[198:201], v[120:123]
	v_mfma_f32_16x16x32_bf16 v[108:111], v[140:143], v[206:209], v[108:111]
	v_mfma_f32_16x16x32_bf16 v[104:107], v[172:175], v[206:209], v[104:107]
	v_mfma_f32_16x16x32_bf16 v[92:95], v[140:143], v[214:217], v[92:95]
	v_mfma_f32_16x16x32_bf16 v[88:91], v[172:175], v[214:217], v[88:91]
	v_mfma_f32_16x16x32_bf16 v[76:79], v[140:143], v[222:225], v[76:79]
	v_mfma_f32_16x16x32_bf16 v[72:75], v[172:175], v[222:225], v[72:75]
	v_mfma_f32_16x16x32_bf16 v[124:127], v[168:171], v[202:205], v[124:127]
	v_mfma_f32_16x16x32_bf16 v[120:123], v[176:179], v[202:205], v[120:123]
	v_mfma_f32_16x16x32_bf16 v[108:111], v[168:171], v[210:213], v[108:111]
	v_mfma_f32_16x16x32_bf16 v[104:107], v[176:179], v[210:213], v[104:107]
	v_mfma_f32_16x16x32_bf16 v[92:95], v[168:171], v[218:221], v[92:95]
	v_mfma_f32_16x16x32_bf16 v[88:91], v[176:179], v[218:221], v[88:91]
	v_mfma_f32_16x16x32_bf16 v[76:79], v[168:171], v[226:229], v[76:79]
	v_mfma_f32_16x16x32_bf16 v[72:75], v[176:179], v[226:229], v[72:75]
	v_mfma_f32_16x16x32_bf16 v[116:119], v[180:183], v[198:201], v[116:119]
	v_mfma_f32_16x16x32_bf16 v[112:115], v[188:191], v[198:201], v[112:115]
	v_mfma_f32_16x16x32_bf16 v[100:103], v[180:183], v[206:209], v[100:103]
	v_mfma_f32_16x16x32_bf16 v[96:99], v[188:191], v[206:209], v[96:99]
	v_mfma_f32_16x16x32_bf16 v[84:87], v[180:183], v[214:217], v[84:87]
	v_mfma_f32_16x16x32_bf16 v[80:83], v[188:191], v[214:217], v[80:83]
	v_mfma_f32_16x16x32_bf16 v[68:71], v[180:183], v[222:225], v[68:71]
	v_mfma_f32_16x16x32_bf16 v[64:67], v[188:191], v[222:225], v[64:67]
	v_mfma_f32_16x16x32_bf16 v[116:119], v[184:187], v[202:205], v[116:119]
	v_mfma_f32_16x16x32_bf16 v[112:115], v[192:195], v[202:205], v[112:115]
	v_mfma_f32_16x16x32_bf16 v[100:103], v[184:187], v[210:213], v[100:103]
	v_mfma_f32_16x16x32_bf16 v[96:99], v[192:195], v[210:213], v[96:99]
	v_mfma_f32_16x16x32_bf16 v[84:87], v[184:187], v[218:221], v[84:87]
	v_mfma_f32_16x16x32_bf16 v[80:83], v[192:195], v[218:221], v[80:83]
	v_mfma_f32_16x16x32_bf16 v[68:71], v[184:187], v[226:229], v[68:71]
	v_mfma_f32_16x16x32_bf16 v[64:67], v[192:195], v[226:229], v[64:67]
	s_barrier
	s_add_i32 s62, s89, s70
	s_mov_b32 m0, s62
	ds_read_b128 v[198:201], v165 offset:49152
	ds_read_b128 v[202:205], v165 offset:50176
	ds_read_b128 v[206:209], v165 offset:51200
	ds_read_b128 v[210:213], v165 offset:52224
	ds_read_b128 v[214:217], v165 offset:53248
	ds_read_b128 v[218:221], v165 offset:54272
	ds_read_b128 v[222:225], v165 offset:55296
	ds_read_b128 v[226:229], v165 offset:56320
	global_load_lds_dwordx4 v146, s[98:99]
	s_add_i32 m0, s62, 0x2000
	s_add_u32 s34, s34, 0x40080
	s_addc_u32 s35, s35, 0
	s_add_i32 s62, s90, s70
	global_load_lds_dwordx4 v150, s[98:99]
	s_mov_b32 m0, s62
	s_nop 0
	global_load_lds_dwordx4 v146, s[34:35]
	s_add_i32 m0, s62, 0x2000
	s_nop 0
	global_load_lds_dwordx4 v150, s[34:35]
	s_mov_b32 m0, s75
	s_nop 0
	global_load_lds_dwordx4 v144, s[100:101]
	s_mov_b32 m0, s76
	s_nop 0
	global_load_lds_dwordx4 v148, s[100:101]
	s_waitcnt vmcnt(8)
	s_waitcnt lgkmcnt(0)
	s_barrier
	v_mfma_f32_16x16x32_bf16 v[60:63], v[140:143], v[198:201], v[60:63]
	v_mfma_f32_16x16x32_bf16 v[56:59], v[172:175], v[198:201], v[56:59]
	v_mfma_f32_16x16x32_bf16 v[48:51], v[140:143], v[206:209], v[48:51]
	v_mfma_f32_16x16x32_bf16 v[40:43], v[172:175], v[206:209], v[40:43]
	v_mfma_f32_16x16x32_bf16 v[32:35], v[140:143], v[214:217], v[32:35]
	v_mfma_f32_16x16x32_bf16 v[24:27], v[172:175], v[214:217], v[24:27]
	v_mfma_f32_16x16x32_bf16 v[16:19], v[140:143], v[222:225], v[16:19]
	v_mfma_f32_16x16x32_bf16 v[8:11], v[172:175], v[222:225], v[8:11]
	v_mfma_f32_16x16x32_bf16 v[60:63], v[168:171], v[202:205], v[60:63]
	v_mfma_f32_16x16x32_bf16 v[56:59], v[176:179], v[202:205], v[56:59]
	v_mfma_f32_16x16x32_bf16 v[48:51], v[168:171], v[210:213], v[48:51]
	v_mfma_f32_16x16x32_bf16 v[40:43], v[176:179], v[210:213], v[40:43]
	v_mfma_f32_16x16x32_bf16 v[32:35], v[168:171], v[218:221], v[32:35]
	v_mfma_f32_16x16x32_bf16 v[24:27], v[176:179], v[218:221], v[24:27]
	v_mfma_f32_16x16x32_bf16 v[16:19], v[168:171], v[226:229], v[16:19]
	v_mfma_f32_16x16x32_bf16 v[8:11], v[176:179], v[226:229], v[8:11]
	v_mfma_f32_16x16x32_bf16 v[52:55], v[180:183], v[198:201], v[52:55]
	v_mfma_f32_16x16x32_bf16 v[44:47], v[188:191], v[198:201], v[44:47]
	v_mfma_f32_16x16x32_bf16 v[36:39], v[180:183], v[206:209], v[36:39]
	v_mfma_f32_16x16x32_bf16 v[28:31], v[188:191], v[206:209], v[28:31]
	v_mfma_f32_16x16x32_bf16 v[20:23], v[180:183], v[214:217], v[20:23]
	v_mfma_f32_16x16x32_bf16 v[12:15], v[188:191], v[214:217], v[12:15]
	v_mfma_f32_16x16x32_bf16 v[4:7], v[180:183], v[222:225], v[4:7]
	v_mfma_f32_16x16x32_bf16 v[0:3], v[188:191], v[222:225], v[0:3]
	v_mfma_f32_16x16x32_bf16 v[52:55], v[184:187], v[202:205], v[52:55]
	v_mfma_f32_16x16x32_bf16 v[44:47], v[192:195], v[202:205], v[44:47]
	v_mfma_f32_16x16x32_bf16 v[36:39], v[184:187], v[210:213], v[36:39]
	v_mfma_f32_16x16x32_bf16 v[28:31], v[192:195], v[210:213], v[28:31]
	v_mfma_f32_16x16x32_bf16 v[20:23], v[184:187], v[218:221], v[20:23]
	v_mfma_f32_16x16x32_bf16 v[12:15], v[192:195], v[218:221], v[12:15]
	v_mfma_f32_16x16x32_bf16 v[4:7], v[184:187], v[226:229], v[4:7]
	v_mfma_f32_16x16x32_bf16 v[0:3], v[192:195], v[226:229], v[0:3]
	s_barrier
	s_add_i32 s88, s88, 2
	s_add_u32 s20, s20, 0x100
	s_addc_u32 s21, s21, 0
	s_add_u32 s86, s86, 0x100
	s_addc_u32 s87, s87, 0
	s_cmp_gt_u32 s88, 13
	s_cbranch_scc0 .LBB0_1200
	v_readlane_b32 s101, v249, 49
	s_nop 3
	s_cmp_eq_u32 s101, 0
	s_cbranch_scc1 .Ldw_done_2
	v_cmp_le_u32_e32 vcc, s101, v250
	s_cbranch_vccnz .Ldw_ok_2
	s_add_u32 s98, s28, 0x183500
	s_addc_u32 s99, s29, 0
	v_mov_b32_e32 v251, 0
	s_mov_b32 s100, 0

; #define PG8_STAGE(bufoff, gbase, voff) do { _Pragma("unroll") for (int _i = 0; _i < 2; ++_i) \
;         __builtin_amdgcn_global_load_lds((const unsigned*)((const char*)(gbase) + (voff)[_i]), (PG8_LAS unsigned*)(lds + (bufoff) + ldsw + _i * 8192), 16, 0, 0); } while (0)
; #define PG8_LDA(dst, b, h) do { _Pragma("unroll") for (int m = 0; m < 4; ++m) _Pragma("unroll") for (int k = 0; k < 2; ++k) dst[m][k] = *(const PG8_LAS bf16x8*)(lds + PG8_SA(b, h) + aoff + m * 2048 + k * 1024); } while (0)
; #define PG8_LDB(dst, b, h) do { _Pragma("unroll") for (int n = 0; n < 2; ++n) _Pragma("unroll") for (int k = 0; k < 2; ++k) dst[n][k] = *(const PG8_LAS bf16x8*)(lds + PG8_SB(b, h) + boff + n * 2048 + k * 1024); } while (0)
; #define PG8_WAIT_V(n) asm volatile("s_waitcnt vmcnt(" #n ")" ::: "memory")
; #define PG8_WAIT_L(n) asm volatile("s_waitcnt lgkmcnt(" #n ")" ::: "memory")
; #define PG8_BAR __builtin_amdgcn_s_barrier()
; #define PG8_SCHED __builtin_amdgcn_sched_barrier(0)
; template <class Epi, class Sched, bool ALIGN_EPI = false, bool SP2 = false>
; __device__ __forceinline__ void gemm_phase(PG8_LAS unsigned char* lds, const Gemm g, const Sched& S, const Epi& E) {
;     ...
;         const bool has_next = S.next(ui + 1, nxt);
;         const char* nA = has_next ? (const char*)g.A + (size_t)nxt.pm * tstep : cA; const char* nB = has_next ? (const char*)g.Bt + (size_t)nxt.pn * tstep : cB;
;         for (int t = 0; t < nt; t += 2) {
;             const bool last = (t == nt - 2);
;             const char* a1 = cA + (size_t)(t + 1) * kstep;
;             const char* a2 = last ? nA : cA + (size_t)(t + 2) * kstep; const char* b2 = last ? nB : cB + (size_t)(t + 2) * kstep;
;             const char* a3 = a2 + kstep; const char* b3 = b2 + kstep;
;             if (last && has_next) S.a_ready(nxt);
;             if constexpr (SP2) {
;             PG8_LDB(B0, 0, 0); PG8_LDB(B1, 0, 1); PG8_SCHED; PG8_LDA(At, 0, 0); PG8_STAGE(PG8_SA(1, 1), a1 + hstep, voffA);
;             PG8_WAIT_V(8); PG8_WAIT_L(0); PG8_BAR; PG8_MMA(0, 0, At, B0); PG8_MMA(0, 1, At, B1); PG8_BAR; PG8_SCHED;
;             PG8_LDA(At, 0, 1); PG8_STAGE(PG8_SB(0, 0), b2, voffB); PG8_STAGE(PG8_SB(0, 1), b2 + hstep, voffB); PG8_STAGE(PG8_SA(0, 0), a2, voffA);
;             PG8_WAIT_V(8); PG8_WAIT_L(0); PG8_BAR; PG8_MMA(1, 0, At, B0); PG8_MMA(1, 1, At, B1); PG8_BAR; PG8_SCHED;
.LBB0_1739:
	s_ashr_i32 s15, s14, 31
	s_lshl_b64 s[16:17], s[14:15], 19
	s_add_u32 s16, s36, s16
	s_addc_u32 s17, s37, s17
	s_and_b64 s[18:19], s[4:5], exec
	s_cselect_b32 s15, s17, s21
	s_cselect_b32 s63, s16, s20
	s_ashr_i32 s13, s12, 31
	s_lshl_b64 s[18:19], s[12:13], 19
	s_add_u32 s18, s48, s18
	s_addc_u32 s19, s49, s19
	s_and_b64 s[42:43], s[4:5], exec
	s_cselect_b32 s13, s19, s39
	s_cselect_b32 s64, s18, s38
	s_add_u32 s20, s20, 0x40080
	s_addc_u32 s21, s21, 0
	s_add_u32 s65, s38, 0x100
	s_addc_u32 s66, s39, 0
	s_mov_b32 s67, -2
	s_add_u32 s98, s28, 0x183500
	s_addc_u32 s99, s29, 0
	v_mov_b32_e32 v251, 0
	global_load_dword v250, v251, s[98:99] sc1
	ds_read_b128 v[154:157], v150
	ds_read_b128 v[158:161], v150 offset:1024
	ds_read_b128 v[162:165], v150 offset:2048
	ds_read_b128 v[166:169], v150 offset:3072
	ds_read_b128 v[170:173], v151
	ds_read_b128 v[174:177], v151 offset:1024
	ds_read_b128 v[178:181], v151 offset:2048
	ds_read_b128 v[182:185], v151 offset:3072
	s_add_u32 s38, s20, 0xfffc0080
	s_addc_u32 s39, s21, -1
	s_cmp_eq_u32 s67, 12
	s_cselect_b32 s43, s15, s39
	s_cselect_b32 s42, s63, s38
	s_cselect_b32 s39, s13, s66
	s_cselect_b32 s38, s64, s65
	s_add_i32 m0, s35, 0xc000
	ds_read_b128 v[186:189], v152
	ds_read_b128 v[190:193], v152 offset:1024
	ds_read_b128 v[198:201], v152 offset:2048
	ds_read_b128 v[202:205], v152 offset:3072
	ds_read_b128 v[206:209], v152 offset:4096
	ds_read_b128 v[210:213], v152 offset:5120
	ds_read_b128 v[214:217], v152 offset:6144
	ds_read_b128 v[218:221], v152 offset:7168
	global_load_lds_dwordx4 v136, s[20:21]
	s_add_i32 m0, s35, 0xe000
	s_nop 0
	global_load_lds_dwordx4 v138, s[20:21]
	s_waitcnt vmcnt(8)
	s_waitcnt lgkmcnt(0)
	s_barrier
	v_mfma_f32_16x16x32_bf16 v[124:127], v[154:157], v[186:189], 0
	v_mfma_f32_16x16x32_bf16 v[116:119], v[162:165], v[186:189], 0
	v_mfma_f32_16x16x32_bf16 v[108:111], v[154:157], v[198:201], 0
	v_mfma_f32_16x16x32_bf16 v[100:103], v[162:165], v[198:201], 0
	v_mfma_f32_16x16x32_bf16 v[92:95], v[154:157], v[206:209], 0
	v_mfma_f32_16x16x32_bf16 v[84:87], v[162:165], v[206:209], 0
	v_mfma_f32_16x16x32_bf16 v[76:79], v[154:157], v[214:217], 0
	v_mfma_f32_16x16x32_bf16 v[68:71], v[162:165], v[214:217], 0
	v_mfma_f32_16x16x32_bf16 v[124:127], v[158:161], v[190:193], v[124:127]
	v_mfma_f32_16x16x32_bf16 v[116:119], v[166:169], v[190:193], v[116:119]
	v_mfma_f32_16x16x32_bf16 v[108:111], v[158:161], v[202:205], v[108:111]
	v_mfma_f32_16x16x32_bf16 v[100:103], v[166:169], v[202:205], v[100:103]
	v_mfma_f32_16x16x32_bf16 v[92:95], v[158:161], v[210:213], v[92:95]
	v_mfma_f32_16x16x32_bf16 v[84:87], v[166:169], v[210:213], v[84:87]
	v_mfma_f32_16x16x32_bf16 v[76:79], v[158:161], v[218:221], v[76:79]
	v_mfma_f32_16x16x32_bf16 v[68:71], v[166:169], v[218:221], v[68:71]
	v_mfma_f32_16x16x32_bf16 v[120:123], v[170:173], v[186:189], 0
	v_mfma_f32_16x16x32_bf16 v[112:115], v[178:181], v[186:189], 0
	v_mfma_f32_16x16x32_bf16 v[104:107], v[170:173], v[198:201], 0
	v_mfma_f32_16x16x32_bf16 v[96:99], v[178:181], v[198:201], 0
	v_mfma_f32_16x16x32_bf16 v[88:91], v[170:173], v[206:209], 0
	v_mfma_f32_16x16x32_bf16 v[80:83], v[178:181], v[206:209], 0
	v_mfma_f32_16x16x32_bf16 v[72:75], v[170:173], v[214:217], 0
	v_mfma_f32_16x16x32_bf16 v[64:67], v[178:181], v[214:217], 0
	v_mfma_f32_16x16x32_bf16 v[120:123], v[174:177], v[190:193], v[120:123]
	v_mfma_f32_16x16x32_bf16 v[112:115], v[182:185], v[190:193], v[112:115]
	v_mfma_f32_16x16x32_bf16 v[104:107], v[174:177], v[202:205], v[104:107]
	v_mfma_f32_16x16x32_bf16 v[96:99], v[182:185], v[202:205], v[96:99]
	v_mfma_f32_16x16x32_bf16 v[88:91], v[174:177], v[210:213], v[88:91]
	v_mfma_f32_16x16x32_bf16 v[80:83], v[182:185], v[210:213], v[80:83]
	v_mfma_f32_16x16x32_bf16 v[72:75], v[174:177], v[218:221], v[72:75]
	v_mfma_f32_16x16x32_bf16 v[64:67], v[182:185], v[218:221], v[64:67]
	s_barrier
	s_add_i32 s68, s58, s50
	s_add_u32 s98, s38, s8
	s_addc_u32 s99, s39, s9
	s_add_u32 s100, s42, s8
	s_addc_u32 s101, s43, s9
	s_mov_b32 m0, s68
	ds_read_b128 v[186:189], v152 offset:16384
	ds_read_b128 v[190:193], v152 offset:17408
	ds_read_b128 v[198:201], v152 offset:18432
	ds_read_b128 v[202:205], v152 offset:19456
	ds_read_b128 v[206:209], v152 offset:20480
	ds_read_b128 v[210:213], v152 offset:21504
	ds_read_b128 v[214:217], v152 offset:22528
	ds_read_b128 v[218:221], v152 offset:23552
	global_load_lds_dwordx4 v132, s[38:39]
	s_add_i32 m0, s68, 0x2000
	s_add_u32 s68, s38, 0x40000
	s_addc_u32 s69, s39, 0
	s_add_i32 s70, s59, s50
	global_load_lds_dwordx4 v128, s[38:39]
	s_mov_b32 m0, s70
	s_nop 0
	global_load_lds_dwordx4 v132, s[68:69]
	s_add_i32 m0, s70, 0x2000
	s_nop 0
	global_load_lds_dwordx4 v128, s[68:69]
	s_mov_b32 m0, s35
	s_nop 0
	global_load_lds_dwordx4 v134, s[42:43]
	s_mov_b32 m0, s52
	s_nop 0
	global_load_lds_dwordx4 v130, s[42:43]
	s_waitcnt vmcnt(8)
	s_waitcnt lgkmcnt(0)
	s_barrier
; #define PG8_STAGE(bufoff, gbase, voff) do { _Pragma("unroll") for (int _i = 0; _i < 2; ++_i) \
;         __builtin_amdgcn_global_load_lds((const unsigned*)((const char*)(gbase) + (voff)[_i]), (PG8_LAS unsigned*)(lds + (bufoff) + ldsw + _i * 8192), 16, 0, 0); } while (0)
; #define PG8_LDA(dst, b, h) do { _Pragma("unroll") for (int m = 0; m < 4; ++m) _Pragma("unroll") for (int k = 0; k < 2; ++k) dst[m][k] = *(const PG8_LAS bf16x8*)(lds + PG8_SA(b, h) + aoff + m * 2048 + k * 1024); } while (0)
; #define PG8_LDB(dst, b, h) do { _Pragma("unroll") for (int n = 0; n < 2; ++n) _Pragma("unroll") for (int k = 0; k < 2; ++k) dst[n][k] = *(const PG8_LAS bf16x8*)(lds + PG8_SB(b, h) + boff + n * 2048 + k * 1024); } while (0)
; #define PG8_MMA(ai, bj, At, Bt) do { __builtin_amdgcn_s_setprio(1); _Pragma("unroll") for (int m = 0; m < 4; ++m) _Pragma("unroll") for (int n = 0; n < 2; ++n) _Pragma("unroll") for (int k = 0; k < 2; ++k) \
;         acc[ai][bj][m][n] = __builtin_amdgcn_mfma_f32_16x16x32_bf16(Bt[n][k], At[m][k], acc[ai][bj][m][n], 0, 0, 0); __builtin_amdgcn_s_setprio(0); } while (0)
; #define PG8_WAIT_V(n) asm volatile("s_waitcnt vmcnt(" #n ")" ::: "memory")
; #define PG8_WAIT_L(n) asm volatile("s_waitcnt lgkmcnt(" #n ")" ::: "memory")
; #define PG8_BAR __builtin_amdgcn_s_barrier()
; #define PG8_SCHED __builtin_amdgcn_sched_barrier(0)
; template <class Epi, class Sched, bool ALIGN_EPI = false, bool SP2 = false>
; __device__ __forceinline__ void gemm_phase(PG8_LAS unsigned char* lds, const Gemm g, const Sched& S, const Epi& E) {
;     ...
;             PG8_WAIT_V(8); PG8_WAIT_L(0); PG8_BAR; PG8_MMA(1, 0, At, B0); PG8_MMA(1, 1, At, B1); PG8_BAR; PG8_SCHED;
;             PG8_LDB(B0, 1, 0); PG8_LDB(B1, 1, 1); PG8_SCHED; PG8_LDA(At, 1, 0); PG8_STAGE(PG8_SA(0, 1), a2 + hstep, voffA);
;             PG8_WAIT_V(8); PG8_WAIT_L(0); PG8_BAR; PG8_MMA(0, 0, At, B0); PG8_MMA(0, 1, At, B1); PG8_BAR; PG8_SCHED;
	v_mfma_f32_16x16x32_bf16 v[60:63], v[154:157], v[186:189], 0
	v_mfma_f32_16x16x32_bf16 v[52:55], v[162:165], v[186:189], 0
	v_mfma_f32_16x16x32_bf16 v[44:47], v[154:157], v[198:201], 0
	v_mfma_f32_16x16x32_bf16 v[36:39], v[162:165], v[198:201], 0
	v_mfma_f32_16x16x32_bf16 v[28:31], v[154:157], v[206:209], 0
	v_mfma_f32_16x16x32_bf16 v[20:23], v[162:165], v[206:209], 0
	v_mfma_f32_16x16x32_bf16 v[12:15], v[154:157], v[214:217], 0
	v_mfma_f32_16x16x32_bf16 v[4:7], v[162:165], v[214:217], 0
	v_mfma_f32_16x16x32_bf16 v[60:63], v[158:161], v[190:193], v[60:63]
	v_mfma_f32_16x16x32_bf16 v[52:55], v[166:169], v[190:193], v[52:55]
	v_mfma_f32_16x16x32_bf16 v[44:47], v[158:161], v[202:205], v[44:47]
	v_mfma_f32_16x16x32_bf16 v[36:39], v[166:169], v[202:205], v[36:39]
	v_mfma_f32_16x16x32_bf16 v[28:31], v[158:161], v[210:213], v[28:31]
	v_mfma_f32_16x16x32_bf16 v[20:23], v[166:169], v[210:213], v[20:23]
	v_mfma_f32_16x16x32_bf16 v[12:15], v[158:161], v[218:221], v[12:15]
	v_mfma_f32_16x16x32_bf16 v[4:7], v[166:169], v[218:221], v[4:7]
	v_mfma_f32_16x16x32_bf16 v[56:59], v[170:173], v[186:189], 0
	v_mfma_f32_16x16x32_bf16 v[48:51], v[178:181], v[186:189], 0
	v_mfma_f32_16x16x32_bf16 v[40:43], v[170:173], v[198:201], 0
	v_mfma_f32_16x16x32_bf16 v[32:35], v[178:181], v[198:201], 0
	v_mfma_f32_16x16x32_bf16 v[24:27], v[170:173], v[206:209], 0
	v_mfma_f32_16x16x32_bf16 v[16:19], v[178:181], v[206:209], 0
	v_mfma_f32_16x16x32_bf16 v[8:11], v[170:173], v[214:217], 0
	v_mfma_f32_16x16x32_bf16 v[0:3], v[178:181], v[214:217], 0
	v_mfma_f32_16x16x32_bf16 v[56:59], v[174:177], v[190:193], v[56:59]
	v_mfma_f32_16x16x32_bf16 v[48:51], v[182:185], v[190:193], v[48:51]
	v_mfma_f32_16x16x32_bf16 v[40:43], v[174:177], v[202:205], v[40:43]
	v_mfma_f32_16x16x32_bf16 v[32:35], v[182:185], v[202:205], v[32:35]
	v_mfma_f32_16x16x32_bf16 v[24:27], v[174:177], v[210:213], v[24:27]
	v_mfma_f32_16x16x32_bf16 v[16:19], v[182:185], v[210:213], v[16:19]
	v_mfma_f32_16x16x32_bf16 v[8:11], v[174:177], v[218:221], v[8:11]
	v_mfma_f32_16x16x32_bf16 v[0:3], v[182:185], v[218:221], v[0:3]
	s_barrier
	s_add_i32 s68, 0, 0x18000
	v_add_u32_e32 v153, s68, v147
	s_add_i32 s69, 0, 0x1c000
	ds_read_b128 v[154:157], v153
	ds_read_b128 v[158:161], v153 offset:1024
	ds_read_b128 v[162:165], v153 offset:2048
	ds_read_b128 v[166:169], v153 offset:3072
	v_add_u32_e32 v153, s69, v147
	ds_read_b128 v[170:173], v153
	ds_read_b128 v[174:177], v153 offset:1024
	ds_read_b128 v[178:181], v153 offset:2048
	ds_read_b128 v[182:185], v153 offset:3072
	s_add_u32 s42, s42, 0x40000
	s_addc_u32 s43, s43, 0
	s_mov_b32 m0, s53
	ds_read_b128 v[186:189], v152 offset:32768
	ds_read_b128 v[190:193], v152 offset:33792
	ds_read_b128 v[198:201], v152 offset:34816
	ds_read_b128 v[202:205], v152 offset:35840
	ds_read_b128 v[206:209], v152 offset:36864
	ds_read_b128 v[210:213], v152 offset:37888
	ds_read_b128 v[214:217], v152 offset:38912
	ds_read_b128 v[218:221], v152 offset:39936
	global_load_lds_dwordx4 v134, s[42:43]
	s_mov_b32 m0, s54
	s_nop 0
	global_load_lds_dwordx4 v130, s[42:43]
	s_waitcnt vmcnt(8)
	s_waitcnt lgkmcnt(0)
	s_barrier
	v_mfma_f32_16x16x32_bf16 v[124:127], v[154:157], v[186:189], v[124:127]
	v_mfma_f32_16x16x32_bf16 v[116:119], v[162:165], v[186:189], v[116:119]
	v_mfma_f32_16x16x32_bf16 v[108:111], v[154:157], v[198:201], v[108:111]
	v_mfma_f32_16x16x32_bf16 v[100:103], v[162:165], v[198:201], v[100:103]
	v_mfma_f32_16x16x32_bf16 v[92:95], v[154:157], v[206:209], v[92:95]
	v_mfma_f32_16x16x32_bf16 v[84:87], v[162:165], v[206:209], v[84:87]
	v_mfma_f32_16x16x32_bf16 v[76:79], v[154:157], v[214:217], v[76:79]
	v_mfma_f32_16x16x32_bf16 v[68:71], v[162:165], v[214:217], v[68:71]
	v_mfma_f32_16x16x32_bf16 v[124:127], v[158:161], v[190:193], v[124:127]
	v_mfma_f32_16x16x32_bf16 v[116:119], v[166:169], v[190:193], v[116:119]
	v_mfma_f32_16x16x32_bf16 v[108:111], v[158:161], v[202:205], v[108:111]
	v_mfma_f32_16x16x32_bf16 v[100:103], v[166:169], v[202:205], v[100:103]
	v_mfma_f32_16x16x32_bf16 v[92:95], v[158:161], v[210:213], v[92:95]
	v_mfma_f32_16x16x32_bf16 v[84:87], v[166:169], v[210:213], v[84:87]
	v_mfma_f32_16x16x32_bf16 v[76:79], v[158:161], v[218:221], v[76:79]
	v_mfma_f32_16x16x32_bf16 v[68:71], v[166:169], v[218:221], v[68:71]
	v_mfma_f32_16x16x32_bf16 v[120:123], v[170:173], v[186:189], v[120:123]
	v_mfma_f32_16x16x32_bf16 v[112:115], v[178:181], v[186:189], v[112:115]
	v_mfma_f32_16x16x32_bf16 v[104:107], v[170:173], v[198:201], v[104:107]
	v_mfma_f32_16x16x32_bf16 v[96:99], v[178:181], v[198:201], v[96:99]
	v_mfma_f32_16x16x32_bf16 v[88:91], v[170:173], v[206:209], v[88:91]
	v_mfma_f32_16x16x32_bf16 v[80:83], v[178:181], v[206:209], v[80:83]
	v_mfma_f32_16x16x32_bf16 v[72:75], v[170:173], v[214:217], v[72:75]
	v_mfma_f32_16x16x32_bf16 v[64:67], v[178:181], v[214:217], v[64:67]
	v_mfma_f32_16x16x32_bf16 v[120:123], v[174:177], v[190:193], v[120:123]
	v_mfma_f32_16x16x32_bf16 v[112:115], v[182:185], v[190:193], v[112:115]
	v_mfma_f32_16x16x32_bf16 v[104:107], v[174:177], v[202:205], v[104:107]
	v_mfma_f32_16x16x32_bf16 v[96:99], v[182:185], v[202:205], v[96:99]
	v_mfma_f32_16x16x32_bf16 v[88:91], v[174:177], v[210:213], v[88:91]
	v_mfma_f32_16x16x32_bf16 v[80:83], v[182:185], v[210:213], v[80:83]
	v_mfma_f32_16x16x32_bf16 v[72:75], v[174:177], v[218:221], v[72:75]
	v_mfma_f32_16x16x32_bf16 v[64:67], v[182:185], v[218:221], v[64:67]
	s_barrier
; #define PG8_STAGE(bufoff, gbase, voff) do { _Pragma("unroll") for (int _i = 0; _i < 2; ++_i) \
;         __builtin_amdgcn_global_load_lds((const unsigned*)((const char*)(gbase) + (voff)[_i]), (PG8_LAS unsigned*)(lds + (bufoff) + ldsw + _i * 8192), 16, 0, 0); } while (0)
; #define PG8_LDA(dst, b, h) do { _Pragma("unroll") for (int m = 0; m < 4; ++m) _Pragma("unroll") for (int k = 0; k < 2; ++k) dst[m][k] = *(const PG8_LAS bf16x8*)(lds + PG8_SA(b, h) + aoff + m * 2048 + k * 1024); } while (0)
; #define PG8_LDB(dst, b, h) do { _Pragma("unroll") for (int n = 0; n < 2; ++n) _Pragma("unroll") for (int k = 0; k < 2; ++k) dst[n][k] = *(const PG8_LAS bf16x8*)(lds + PG8_SB(b, h) + boff + n * 2048 + k * 1024); } while (0)
; #define PG8_MMA(ai, bj, At, Bt) do { __builtin_amdgcn_s_setprio(1); _Pragma("unroll") for (int m = 0; m < 4; ++m) _Pragma("unroll") for (int n = 0; n < 2; ++n) _Pragma("unroll") for (int k = 0; k < 2; ++k) \
;         acc[ai][bj][m][n] = __builtin_amdgcn_mfma_f32_16x16x32_bf16(Bt[n][k], At[m][k], acc[ai][bj][m][n], 0, 0, 0); __builtin_amdgcn_s_setprio(0); } while (0)
; #define PG8_WAIT_V(n) asm volatile("s_waitcnt vmcnt(" #n ")" ::: "memory")
; #define PG8_WAIT_L(n) asm volatile("s_waitcnt lgkmcnt(" #n ")" ::: "memory")
; #define PG8_BAR __builtin_amdgcn_s_barrier()
; #define PG8_SCHED __builtin_amdgcn_sched_barrier(0)
; template <class Epi, class Sched, bool ALIGN_EPI = false, bool SP2 = false>
; __device__ __forceinline__ void gemm_phase(PG8_LAS unsigned char* lds, const Gemm g, const Sched& S, const Epi& E) {
;     ...
;             PG8_LDB(B0, 0, 0); PG8_LDB(B1, 0, 1); PG8_SCHED; PG8_LDA(At, 0, 0); PG8_STAGE(PG8_SA(1, 1), a1 + hstep, voffA);
;             PG8_WAIT_V(8); PG8_WAIT_L(0); PG8_BAR; PG8_MMA(0, 0, At, B0); PG8_MMA(0, 1, At, B1); PG8_BAR; PG8_SCHED;
;     ...
;             PG8_LDA(At, 1, 1); PG8_STAGE(PG8_SB(1, 0), b3, voffB); PG8_STAGE(PG8_SB(1, 1), b3 + hstep, voffB); PG8_STAGE(PG8_SA(1, 0), a3, voffA);
;             PG8_WAIT_V(8); PG8_WAIT_L(0); PG8_BAR; PG8_MMA(1, 0, At, B0); PG8_MMA(1, 1, At, B1); PG8_BAR; PG8_SCHED;
	s_add_i32 s42, s68, s50
	s_mov_b32 m0, s42
	ds_read_b128 v[186:189], v152 offset:49152
	ds_read_b128 v[190:193], v152 offset:50176
	ds_read_b128 v[198:201], v152 offset:51200
	ds_read_b128 v[202:205], v152 offset:52224
	ds_read_b128 v[206:209], v152 offset:53248
	ds_read_b128 v[210:213], v152 offset:54272
	ds_read_b128 v[214:217], v152 offset:55296
	ds_read_b128 v[218:221], v152 offset:56320
	global_load_lds_dwordx4 v132, s[98:99]
	s_add_i32 m0, s42, 0x2000
	s_add_u32 s38, s38, 0x40080
	s_addc_u32 s39, s39, 0
	s_add_i32 s42, s69, s50
	global_load_lds_dwordx4 v128, s[98:99]
	s_mov_b32 m0, s42
	s_nop 0
	global_load_lds_dwordx4 v132, s[38:39]
	s_add_i32 m0, s42, 0x2000
	s_nop 0
	global_load_lds_dwordx4 v128, s[38:39]
	s_mov_b32 m0, s56
	s_nop 0
	global_load_lds_dwordx4 v134, s[100:101]
	s_mov_b32 m0, s57
	s_nop 0
	global_load_lds_dwordx4 v130, s[100:101]
	s_waitcnt vmcnt(8)
	s_waitcnt lgkmcnt(0)
	s_barrier
	v_mfma_f32_16x16x32_bf16 v[60:63], v[154:157], v[186:189], v[60:63]
	v_mfma_f32_16x16x32_bf16 v[52:55], v[162:165], v[186:189], v[52:55]
	v_mfma_f32_16x16x32_bf16 v[44:47], v[154:157], v[198:201], v[44:47]
	v_mfma_f32_16x16x32_bf16 v[36:39], v[162:165], v[198:201], v[36:39]
	v_mfma_f32_16x16x32_bf16 v[28:31], v[154:157], v[206:209], v[28:31]
	v_mfma_f32_16x16x32_bf16 v[20:23], v[162:165], v[206:209], v[20:23]
	v_mfma_f32_16x16x32_bf16 v[12:15], v[154:157], v[214:217], v[12:15]
	v_mfma_f32_16x16x32_bf16 v[4:7], v[162:165], v[214:217], v[4:7]
	v_mfma_f32_16x16x32_bf16 v[60:63], v[158:161], v[190:193], v[60:63]
	v_mfma_f32_16x16x32_bf16 v[52:55], v[166:169], v[190:193], v[52:55]
	v_mfma_f32_16x16x32_bf16 v[44:47], v[158:161], v[202:205], v[44:47]
	v_mfma_f32_16x16x32_bf16 v[36:39], v[166:169], v[202:205], v[36:39]
	v_mfma_f32_16x16x32_bf16 v[28:31], v[158:161], v[210:213], v[28:31]
	v_mfma_f32_16x16x32_bf16 v[20:23], v[166:169], v[210:213], v[20:23]
	v_mfma_f32_16x16x32_bf16 v[12:15], v[158:161], v[218:221], v[12:15]
	v_mfma_f32_16x16x32_bf16 v[4:7], v[166:169], v[218:221], v[4:7]
	v_mfma_f32_16x16x32_bf16 v[56:59], v[170:173], v[186:189], v[56:59]
	v_mfma_f32_16x16x32_bf16 v[48:51], v[178:181], v[186:189], v[48:51]
	v_mfma_f32_16x16x32_bf16 v[40:43], v[170:173], v[198:201], v[40:43]
	v_mfma_f32_16x16x32_bf16 v[32:35], v[178:181], v[198:201], v[32:35]
	v_mfma_f32_16x16x32_bf16 v[24:27], v[170:173], v[206:209], v[24:27]
	v_mfma_f32_16x16x32_bf16 v[16:19], v[178:181], v[206:209], v[16:19]
	v_mfma_f32_16x16x32_bf16 v[8:11], v[170:173], v[214:217], v[8:11]
	v_mfma_f32_16x16x32_bf16 v[0:3], v[178:181], v[214:217], v[0:3]
	v_mfma_f32_16x16x32_bf16 v[56:59], v[174:177], v[190:193], v[56:59]
	v_mfma_f32_16x16x32_bf16 v[48:51], v[182:185], v[190:193], v[48:51]
	v_mfma_f32_16x16x32_bf16 v[40:43], v[174:177], v[202:205], v[40:43]
	v_mfma_f32_16x16x32_bf16 v[32:35], v[182:185], v[202:205], v[32:35]
	v_mfma_f32_16x16x32_bf16 v[24:27], v[174:177], v[210:213], v[24:27]
	v_mfma_f32_16x16x32_bf16 v[16:19], v[182:185], v[210:213], v[16:19]
	v_mfma_f32_16x16x32_bf16 v[8:11], v[174:177], v[218:221], v[8:11]
	v_mfma_f32_16x16x32_bf16 v[0:3], v[182:185], v[218:221], v[0:3]
	s_barrier
	s_add_i32 s67, s67, 2
	s_add_u32 s20, s20, 0x100
	s_addc_u32 s21, s21, 0
	s_add_u32 s65, s65, 0x100
	s_addc_u32 s66, s66, 0
	s_cmp_gt_u32 s67, 13
.LBB0_1740:
	ds_read_b128 v[154:157], v150
	ds_read_b128 v[158:161], v150 offset:1024
	ds_read_b128 v[162:165], v150 offset:2048
	ds_read_b128 v[166:169], v150 offset:3072
	ds_read_b128 v[170:173], v151
	ds_read_b128 v[174:177], v151 offset:1024
	ds_read_b128 v[178:181], v151 offset:2048
	ds_read_b128 v[182:185], v151 offset:3072
	s_add_u32 s38, s20, 0xfffc0080
	s_addc_u32 s39, s21, -1
	s_cmp_eq_u32 s67, 12
	s_cselect_b32 s43, s15, s39
	s_cselect_b32 s42, s63, s38
	s_cselect_b32 s39, s13, s66
	s_cselect_b32 s38, s64, s65
	s_add_i32 m0, s35, 0xc000
	ds_read_b128 v[186:189], v152
	ds_read_b128 v[190:193], v152 offset:1024
	ds_read_b128 v[198:201], v152 offset:2048
	ds_read_b128 v[202:205], v152 offset:3072
	ds_read_b128 v[206:209], v152 offset:4096
	ds_read_b128 v[210:213], v152 offset:5120
	ds_read_b128 v[214:217], v152 offset:6144
	ds_read_b128 v[218:221], v152 offset:7168
	global_load_lds_dwordx4 v136, s[20:21]
	s_add_i32 m0, s35, 0xe000
	s_nop 0
	global_load_lds_dwordx4 v138, s[20:21]
	s_waitcnt vmcnt(8)
	s_waitcnt lgkmcnt(0)
	s_barrier
	v_mfma_f32_16x16x32_bf16 v[124:127], v[154:157], v[186:189], v[124:127]
	v_mfma_f32_16x16x32_bf16 v[116:119], v[162:165], v[186:189], v[116:119]
	v_mfma_f32_16x16x32_bf16 v[108:111], v[154:157], v[198:201], v[108:111]
	v_mfma_f32_16x16x32_bf16 v[100:103], v[162:165], v[198:201], v[100:103]
	v_mfma_f32_16x16x32_bf16 v[92:95], v[154:157], v[206:209], v[92:95]
	v_mfma_f32_16x16x32_bf16 v[84:87], v[162:165], v[206:209], v[84:87]
	v_mfma_f32_16x16x32_bf16 v[76:79], v[154:157], v[214:217], v[76:79]
	v_mfma_f32_16x16x32_bf16 v[68:71], v[162:165], v[214:217], v[68:71]
	v_mfma_f32_16x16x32_bf16 v[124:127], v[158:161], v[190:193], v[124:127]
	v_mfma_f32_16x16x32_bf16 v[116:119], v[166:169], v[190:193], v[116:119]
	v_mfma_f32_16x16x32_bf16 v[108:111], v[158:161], v[202:205], v[108:111]
	v_mfma_f32_16x16x32_bf16 v[100:103], v[166:169], v[202:205], v[100:103]
	v_mfma_f32_16x16x32_bf16 v[92:95], v[158:161], v[210:213], v[92:95]
	v_mfma_f32_16x16x32_bf16 v[84:87], v[166:169], v[210:213], v[84:87]
	v_mfma_f32_16x16x32_bf16 v[76:79], v[158:161], v[218:221], v[76:79]
	v_mfma_f32_16x16x32_bf16 v[68:71], v[166:169], v[218:221], v[68:71]
	v_mfma_f32_16x16x32_bf16 v[120:123], v[170:173], v[186:189], v[120:123]
	v_mfma_f32_16x16x32_bf16 v[112:115], v[178:181], v[186:189], v[112:115]
	v_mfma_f32_16x16x32_bf16 v[104:107], v[170:173], v[198:201], v[104:107]
	v_mfma_f32_16x16x32_bf16 v[96:99], v[178:181], v[198:201], v[96:99]
	v_mfma_f32_16x16x32_bf16 v[88:91], v[170:173], v[206:209], v[88:91]
	v_mfma_f32_16x16x32_bf16 v[80:83], v[178:181], v[206:209], v[80:83]
	v_mfma_f32_16x16x32_bf16 v[72:75], v[170:173], v[214:217], v[72:75]
	v_mfma_f32_16x16x32_bf16 v[64:67], v[178:181], v[214:217], v[64:67]
	v_mfma_f32_16x16x32_bf16 v[120:123], v[174:177], v[190:193], v[120:123]
	v_mfma_f32_16x16x32_bf16 v[112:115], v[182:185], v[190:193], v[112:115]
	v_mfma_f32_16x16x32_bf16 v[104:107], v[174:177], v[202:205], v[104:107]
	v_mfma_f32_16x16x32_bf16 v[96:99], v[182:185], v[202:205], v[96:99]
	v_mfma_f32_16x16x32_bf16 v[88:91], v[174:177], v[210:213], v[88:91]
	v_mfma_f32_16x16x32_bf16 v[80:83], v[182:185], v[210:213], v[80:83]
	v_mfma_f32_16x16x32_bf16 v[72:75], v[174:177], v[218:221], v[72:75]
	v_mfma_f32_16x16x32_bf16 v[64:67], v[182:185], v[218:221], v[64:67]
	s_barrier
; #define PG8_STAGE(bufoff, gbase, voff) do { _Pragma("unroll") for (int _i = 0; _i < 2; ++_i) \
;         __builtin_amdgcn_global_load_lds((const unsigned*)((const char*)(gbase) + (voff)[_i]), (PG8_LAS unsigned*)(lds + (bufoff) + ldsw + _i * 8192), 16, 0, 0); } while (0)
; #define PG8_LDA(dst, b, h) do { _Pragma("unroll") for (int m = 0; m < 4; ++m) _Pragma("unroll") for (int k = 0; k < 2; ++k) dst[m][k] = *(const PG8_LAS bf16x8*)(lds + PG8_SA(b, h) + aoff + m * 2048 + k * 1024); } while (0)
; #define PG8_LDB(dst, b, h) do { _Pragma("unroll") for (int n = 0; n < 2; ++n) _Pragma("unroll") for (int k = 0; k < 2; ++k) dst[n][k] = *(const PG8_LAS bf16x8*)(lds + PG8_SB(b, h) + boff + n * 2048 + k * 1024); } while (0)
; #define PG8_MMA(ai, bj, At, Bt) do { __builtin_amdgcn_s_setprio(1); _Pragma("unroll") for (int m = 0; m < 4; ++m) _Pragma("unroll") for (int n = 0; n < 2; ++n) _Pragma("unroll") for (int k = 0; k < 2; ++k) \
;         acc[ai][bj][m][n] = __builtin_amdgcn_mfma_f32_16x16x32_bf16(Bt[n][k], At[m][k], acc[ai][bj][m][n], 0, 0, 0); __builtin_amdgcn_s_setprio(0); } while (0)
; #define PG8_WAIT_V(n) asm volatile("s_waitcnt vmcnt(" #n ")" ::: "memory")
; #define PG8_WAIT_L(n) asm volatile("s_waitcnt lgkmcnt(" #n ")" ::: "memory")
; #define PG8_BAR __builtin_amdgcn_s_barrier()
; #define PG8_SCHED __builtin_amdgcn_sched_barrier(0)
; template <class Epi, class Sched, bool ALIGN_EPI = false, bool SP2 = false>
; __device__ __forceinline__ void gemm_phase(PG8_LAS unsigned char* lds, const Gemm g, const Sched& S, const Epi& E) {
;     ...
;             PG8_LDA(At, 0, 1); PG8_STAGE(PG8_SB(0, 0), b2, voffB); PG8_STAGE(PG8_SB(0, 1), b2 + hstep, voffB); PG8_STAGE(PG8_SA(0, 0), a2, voffA);
;             PG8_WAIT_V(8); PG8_WAIT_L(0); PG8_BAR; PG8_MMA(1, 0, At, B0); PG8_MMA(1, 1, At, B1); PG8_BAR; PG8_SCHED;
;             PG8_LDB(B0, 1, 0); PG8_LDB(B1, 1, 1); PG8_SCHED; PG8_LDA(At, 1, 0); PG8_STAGE(PG8_SA(0, 1), a2 + hstep, voffA);
;             PG8_WAIT_V(8); PG8_WAIT_L(0); PG8_BAR; PG8_MMA(0, 0, At, B0); PG8_MMA(0, 1, At, B1); PG8_BAR; PG8_SCHED;
	s_add_i32 s68, s58, s50
	s_add_u32 s98, s38, s8
	s_addc_u32 s99, s39, s9
	s_add_u32 s100, s42, s8
	s_addc_u32 s101, s43, s9
	s_mov_b32 m0, s68
	ds_read_b128 v[186:189], v152 offset:16384
	ds_read_b128 v[190:193], v152 offset:17408
	ds_read_b128 v[198:201], v152 offset:18432
	ds_read_b128 v[202:205], v152 offset:19456
	ds_read_b128 v[206:209], v152 offset:20480
	ds_read_b128 v[210:213], v152 offset:21504
	ds_read_b128 v[214:217], v152 offset:22528
	ds_read_b128 v[218:221], v152 offset:23552
	global_load_lds_dwordx4 v132, s[38:39]
	s_add_i32 m0, s68, 0x2000
	s_add_u32 s68, s38, 0x40000
	s_addc_u32 s69, s39, 0
	s_add_i32 s70, s59, s50
	global_load_lds_dwordx4 v128, s[38:39]
	s_mov_b32 m0, s70
	s_nop 0
	global_load_lds_dwordx4 v132, s[68:69]
	s_add_i32 m0, s70, 0x2000
	s_nop 0
	global_load_lds_dwordx4 v128, s[68:69]
	s_mov_b32 m0, s35
	s_nop 0
	global_load_lds_dwordx4 v134, s[42:43]
	s_mov_b32 m0, s52
	s_nop 0
	global_load_lds_dwordx4 v130, s[42:43]
	s_waitcnt vmcnt(8)
	s_waitcnt lgkmcnt(0)
	s_barrier
	v_mfma_f32_16x16x32_bf16 v[60:63], v[154:157], v[186:189], v[60:63]
	v_mfma_f32_16x16x32_bf16 v[52:55], v[162:165], v[186:189], v[52:55]
	v_mfma_f32_16x16x32_bf16 v[44:47], v[154:157], v[198:201], v[44:47]
	v_mfma_f32_16x16x32_bf16 v[36:39], v[162:165], v[198:201], v[36:39]
	v_mfma_f32_16x16x32_bf16 v[28:31], v[154:157], v[206:209], v[28:31]
	v_mfma_f32_16x16x32_bf16 v[20:23], v[162:165], v[206:209], v[20:23]
	v_mfma_f32_16x16x32_bf16 v[12:15], v[154:157], v[214:217], v[12:15]
	v_mfma_f32_16x16x32_bf16 v[4:7], v[162:165], v[214:217], v[4:7]
	v_mfma_f32_16x16x32_bf16 v[60:63], v[158:161], v[190:193], v[60:63]
	v_mfma_f32_16x16x32_bf16 v[52:55], v[166:169], v[190:193], v[52:55]
	v_mfma_f32_16x16x32_bf16 v[44:47], v[158:161], v[202:205], v[44:47]
	v_mfma_f32_16x16x32_bf16 v[36:39], v[166:169], v[202:205], v[36:39]
	v_mfma_f32_16x16x32_bf16 v[28:31], v[158:161], v[210:213], v[28:31]
	v_mfma_f32_16x16x32_bf16 v[20:23], v[166:169], v[210:213], v[20:23]
	v_mfma_f32_16x16x32_bf16 v[12:15], v[158:161], v[218:221], v[12:15]
	v_mfma_f32_16x16x32_bf16 v[4:7], v[166:169], v[218:221], v[4:7]
	v_mfma_f32_16x16x32_bf16 v[56:59], v[170:173], v[186:189], v[56:59]
	v_mfma_f32_16x16x32_bf16 v[48:51], v[178:181], v[186:189], v[48:51]
	v_mfma_f32_16x16x32_bf16 v[40:43], v[170:173], v[198:201], v[40:43]
	v_mfma_f32_16x16x32_bf16 v[32:35], v[178:181], v[198:201], v[32:35]
	v_mfma_f32_16x16x32_bf16 v[24:27], v[170:173], v[206:209], v[24:27]
	v_mfma_f32_16x16x32_bf16 v[16:19], v[178:181], v[206:209], v[16:19]
	v_mfma_f32_16x16x32_bf16 v[8:11], v[170:173], v[214:217], v[8:11]
	v_mfma_f32_16x16x32_bf16 v[0:3], v[178:181], v[214:217], v[0:3]
	v_mfma_f32_16x16x32_bf16 v[56:59], v[174:177], v[190:193], v[56:59]
	v_mfma_f32_16x16x32_bf16 v[48:51], v[182:185], v[190:193], v[48:51]
	v_mfma_f32_16x16x32_bf16 v[40:43], v[174:177], v[202:205], v[40:43]
	v_mfma_f32_16x16x32_bf16 v[32:35], v[182:185], v[202:205], v[32:35]
	v_mfma_f32_16x16x32_bf16 v[24:27], v[174:177], v[210:213], v[24:27]
	v_mfma_f32_16x16x32_bf16 v[16:19], v[182:185], v[210:213], v[16:19]
	v_mfma_f32_16x16x32_bf16 v[8:11], v[174:177], v[218:221], v[8:11]
	v_mfma_f32_16x16x32_bf16 v[0:3], v[182:185], v[218:221], v[0:3]
	s_barrier
	s_add_i32 s68, 0, 0x18000
	v_add_u32_e32 v153, s68, v147
	s_add_i32 s69, 0, 0x1c000
	ds_read_b128 v[154:157], v153
	ds_read_b128 v[158:161], v153 offset:1024
	ds_read_b128 v[162:165], v153 offset:2048
	ds_read_b128 v[166:169], v153 offset:3072
	v_add_u32_e32 v153, s69, v147
	ds_read_b128 v[170:173], v153
	ds_read_b128 v[174:177], v153 offset:1024
	ds_read_b128 v[178:181], v153 offset:2048
	ds_read_b128 v[182:185], v153 offset:3072
	s_add_u32 s42, s42, 0x40000
	s_addc_u32 s43, s43, 0
	s_mov_b32 m0, s53
	ds_read_b128 v[186:189], v152 offset:32768
	ds_read_b128 v[190:193], v152 offset:33792
	ds_read_b128 v[198:201], v152 offset:34816
	ds_read_b128 v[202:205], v152 offset:35840
	ds_read_b128 v[206:209], v152 offset:36864
	ds_read_b128 v[210:213], v152 offset:37888
	ds_read_b128 v[214:217], v152 offset:38912
	ds_read_b128 v[218:221], v152 offset:39936
	global_load_lds_dwordx4 v134, s[42:43]
	s_mov_b32 m0, s54
	s_nop 0
	global_load_lds_dwordx4 v130, s[42:43]
	s_waitcnt vmcnt(8)
	s_waitcnt lgkmcnt(0)
	s_barrier
; #define PG8_STAGE(bufoff, gbase, voff) do { _Pragma("unroll") for (int _i = 0; _i < 2; ++_i) \
;         __builtin_amdgcn_global_load_lds((const unsigned*)((const char*)(gbase) + (voff)[_i]), (PG8_LAS unsigned*)(lds + (bufoff) + ldsw + _i * 8192), 16, 0, 0); } while (0)
; #define PG8_LDA(dst, b, h) do { _Pragma("unroll") for (int m = 0; m < 4; ++m) _Pragma("unroll") for (int k = 0; k < 2; ++k) dst[m][k] = *(const PG8_LAS bf16x8*)(lds + PG8_SA(b, h) + aoff + m * 2048 + k * 1024); } while (0)
; #define PG8_MMA(ai, bj, At, Bt) do { __builtin_amdgcn_s_setprio(1); _Pragma("unroll") for (int m = 0; m < 4; ++m) _Pragma("unroll") for (int n = 0; n < 2; ++n) _Pragma("unroll") for (int k = 0; k < 2; ++k) \
;         acc[ai][bj][m][n] = __builtin_amdgcn_mfma_f32_16x16x32_bf16(Bt[n][k], At[m][k], acc[ai][bj][m][n], 0, 0, 0); __builtin_amdgcn_s_setprio(0); } while (0)
; #define PG8_WAIT_V(n) asm volatile("s_waitcnt vmcnt(" #n ")" ::: "memory")
; #define PG8_WAIT_L(n) asm volatile("s_waitcnt lgkmcnt(" #n ")" ::: "memory")
; #define PG8_BAR __builtin_amdgcn_s_barrier()
; #define PG8_SCHED __builtin_amdgcn_sched_barrier(0)
; template <class Epi, class Sched, bool ALIGN_EPI = false, bool SP2 = false>
; __device__ __forceinline__ void gemm_phase(PG8_LAS unsigned char* lds, const Gemm g, const Sched& S, const Epi& E) {
;     ...
;             PG8_WAIT_V(8); PG8_WAIT_L(0); PG8_BAR; PG8_MMA(0, 0, At, B0); PG8_MMA(0, 1, At, B1); PG8_BAR; PG8_SCHED;
;             PG8_LDA(At, 1, 1); PG8_STAGE(PG8_SB(1, 0), b3, voffB); PG8_STAGE(PG8_SB(1, 1), b3 + hstep, voffB); PG8_STAGE(PG8_SA(1, 0), a3, voffA);
;             PG8_WAIT_V(8); PG8_WAIT_L(0); PG8_BAR; PG8_MMA(1, 0, At, B0); PG8_MMA(1, 1, At, B1); PG8_BAR; PG8_SCHED;
;     ...
;         if constexpr (ALIGN_EPI) { if (wr == 0) PG8_BAR; }
;         if constexpr (!Epi::AFTER_DRAIN) { E(acc, cur, wr, wc, fr, fq); S.done(cur); }
	v_mfma_f32_16x16x32_bf16 v[124:127], v[154:157], v[186:189], v[124:127]
	v_mfma_f32_16x16x32_bf16 v[116:119], v[162:165], v[186:189], v[116:119]
	v_mfma_f32_16x16x32_bf16 v[108:111], v[154:157], v[198:201], v[108:111]
	v_mfma_f32_16x16x32_bf16 v[100:103], v[162:165], v[198:201], v[100:103]
	v_mfma_f32_16x16x32_bf16 v[92:95], v[154:157], v[206:209], v[92:95]
	v_mfma_f32_16x16x32_bf16 v[84:87], v[162:165], v[206:209], v[84:87]
	v_mfma_f32_16x16x32_bf16 v[76:79], v[154:157], v[214:217], v[76:79]
	v_mfma_f32_16x16x32_bf16 v[68:71], v[162:165], v[214:217], v[68:71]
	v_mfma_f32_16x16x32_bf16 v[124:127], v[158:161], v[190:193], v[124:127]
	v_mfma_f32_16x16x32_bf16 v[116:119], v[166:169], v[190:193], v[116:119]
	v_mfma_f32_16x16x32_bf16 v[108:111], v[158:161], v[202:205], v[108:111]
	v_mfma_f32_16x16x32_bf16 v[100:103], v[166:169], v[202:205], v[100:103]
	v_mfma_f32_16x16x32_bf16 v[92:95], v[158:161], v[210:213], v[92:95]
	v_mfma_f32_16x16x32_bf16 v[84:87], v[166:169], v[210:213], v[84:87]
	v_mfma_f32_16x16x32_bf16 v[76:79], v[158:161], v[218:221], v[76:79]
	v_mfma_f32_16x16x32_bf16 v[68:71], v[166:169], v[218:221], v[68:71]
	v_mfma_f32_16x16x32_bf16 v[120:123], v[170:173], v[186:189], v[120:123]
	v_mfma_f32_16x16x32_bf16 v[112:115], v[178:181], v[186:189], v[112:115]
	v_mfma_f32_16x16x32_bf16 v[104:107], v[170:173], v[198:201], v[104:107]
	v_mfma_f32_16x16x32_bf16 v[96:99], v[178:181], v[198:201], v[96:99]
	v_mfma_f32_16x16x32_bf16 v[88:91], v[170:173], v[206:209], v[88:91]
	v_mfma_f32_16x16x32_bf16 v[80:83], v[178:181], v[206:209], v[80:83]
	v_mfma_f32_16x16x32_bf16 v[72:75], v[170:173], v[214:217], v[72:75]
	v_mfma_f32_16x16x32_bf16 v[64:67], v[178:181], v[214:217], v[64:67]
	v_mfma_f32_16x16x32_bf16 v[120:123], v[174:177], v[190:193], v[120:123]
	v_mfma_f32_16x16x32_bf16 v[112:115], v[182:185], v[190:193], v[112:115]
	v_mfma_f32_16x16x32_bf16 v[104:107], v[174:177], v[202:205], v[104:107]
	v_mfma_f32_16x16x32_bf16 v[96:99], v[182:185], v[202:205], v[96:99]
	v_mfma_f32_16x16x32_bf16 v[88:91], v[174:177], v[210:213], v[88:91]
	v_mfma_f32_16x16x32_bf16 v[80:83], v[182:185], v[210:213], v[80:83]
	v_mfma_f32_16x16x32_bf16 v[72:75], v[174:177], v[218:221], v[72:75]
	v_mfma_f32_16x16x32_bf16 v[64:67], v[182:185], v[218:221], v[64:67]
	s_barrier
	s_add_i32 s42, s68, s50
	s_mov_b32 m0, s42
	ds_read_b128 v[186:189], v152 offset:49152
	ds_read_b128 v[190:193], v152 offset:50176
	ds_read_b128 v[198:201], v152 offset:51200
	ds_read_b128 v[202:205], v152 offset:52224
	ds_read_b128 v[206:209], v152 offset:53248
	ds_read_b128 v[210:213], v152 offset:54272
	ds_read_b128 v[214:217], v152 offset:55296
	ds_read_b128 v[218:221], v152 offset:56320
	global_load_lds_dwordx4 v132, s[98:99]
	s_add_i32 m0, s42, 0x2000
	s_add_u32 s38, s38, 0x40080
	s_addc_u32 s39, s39, 0
	s_add_i32 s42, s69, s50
	global_load_lds_dwordx4 v128, s[98:99]
	s_mov_b32 m0, s42
	s_nop 0
	global_load_lds_dwordx4 v132, s[38:39]
	s_add_i32 m0, s42, 0x2000
	s_nop 0
	global_load_lds_dwordx4 v128, s[38:39]
	s_mov_b32 m0, s56
	s_nop 0
	global_load_lds_dwordx4 v134, s[100:101]
	s_mov_b32 m0, s57
	s_nop 0
	global_load_lds_dwordx4 v130, s[100:101]
	s_waitcnt vmcnt(8)
	s_waitcnt lgkmcnt(0)
	s_barrier
	v_mfma_f32_16x16x32_bf16 v[60:63], v[154:157], v[186:189], v[60:63]
	v_mfma_f32_16x16x32_bf16 v[52:55], v[162:165], v[186:189], v[52:55]
	v_mfma_f32_16x16x32_bf16 v[44:47], v[154:157], v[198:201], v[44:47]
	v_mfma_f32_16x16x32_bf16 v[36:39], v[162:165], v[198:201], v[36:39]
	v_mfma_f32_16x16x32_bf16 v[28:31], v[154:157], v[206:209], v[28:31]
	v_mfma_f32_16x16x32_bf16 v[20:23], v[162:165], v[206:209], v[20:23]
	v_mfma_f32_16x16x32_bf16 v[12:15], v[154:157], v[214:217], v[12:15]
	v_mfma_f32_16x16x32_bf16 v[4:7], v[162:165], v[214:217], v[4:7]
	v_mfma_f32_16x16x32_bf16 v[60:63], v[158:161], v[190:193], v[60:63]
	v_mfma_f32_16x16x32_bf16 v[52:55], v[166:169], v[190:193], v[52:55]
	v_mfma_f32_16x16x32_bf16 v[44:47], v[158:161], v[202:205], v[44:47]
	v_mfma_f32_16x16x32_bf16 v[36:39], v[166:169], v[202:205], v[36:39]
	v_mfma_f32_16x16x32_bf16 v[28:31], v[158:161], v[210:213], v[28:31]
	v_mfma_f32_16x16x32_bf16 v[20:23], v[166:169], v[210:213], v[20:23]
	v_mfma_f32_16x16x32_bf16 v[12:15], v[158:161], v[218:221], v[12:15]
	v_mfma_f32_16x16x32_bf16 v[4:7], v[166:169], v[218:221], v[4:7]
	v_mfma_f32_16x16x32_bf16 v[56:59], v[170:173], v[186:189], v[56:59]
	v_mfma_f32_16x16x32_bf16 v[48:51], v[178:181], v[186:189], v[48:51]
	v_mfma_f32_16x16x32_bf16 v[40:43], v[170:173], v[198:201], v[40:43]
	v_mfma_f32_16x16x32_bf16 v[32:35], v[178:181], v[198:201], v[32:35]
	v_mfma_f32_16x16x32_bf16 v[24:27], v[170:173], v[206:209], v[24:27]
	v_mfma_f32_16x16x32_bf16 v[16:19], v[178:181], v[206:209], v[16:19]
	v_mfma_f32_16x16x32_bf16 v[8:11], v[170:173], v[214:217], v[8:11]
	v_mfma_f32_16x16x32_bf16 v[0:3], v[178:181], v[214:217], v[0:3]
	v_mfma_f32_16x16x32_bf16 v[56:59], v[174:177], v[190:193], v[56:59]
	v_mfma_f32_16x16x32_bf16 v[48:51], v[182:185], v[190:193], v[48:51]
	v_mfma_f32_16x16x32_bf16 v[40:43], v[174:177], v[202:205], v[40:43]
	v_mfma_f32_16x16x32_bf16 v[32:35], v[182:185], v[202:205], v[32:35]
	v_mfma_f32_16x16x32_bf16 v[24:27], v[174:177], v[210:213], v[24:27]
	v_mfma_f32_16x16x32_bf16 v[16:19], v[182:185], v[210:213], v[16:19]
	v_mfma_f32_16x16x32_bf16 v[8:11], v[174:177], v[218:221], v[8:11]
	v_mfma_f32_16x16x32_bf16 v[0:3], v[182:185], v[218:221], v[0:3]
	s_barrier
	s_add_i32 s67, s67, 2
	s_add_u32 s20, s20, 0x100
	s_addc_u32 s21, s21, 0
	s_add_u32 s65, s65, 0x100
	s_addc_u32 s66, s66, 0
	s_cmp_gt_u32 s67, 13
	s_cbranch_scc0 .LBB0_1740
	v_readlane_b32 s101, v249, 49
	s_nop 3
	s_cmp_eq_u32 s101, 0
	s_cbranch_scc1 .Ldw_done_3
	v_cmp_le_u32_e32 vcc, s101, v250
	s_cbranch_vccnz .Ldw_ok_3
	s_add_u32 s98, s28, 0x183500
	s_addc_u32 s99, s29, 0
	v_mov_b32_e32 v251, 0
	s_mov_b32 s100, 0
